# phase 6: thread-private stash re-laid out so 8 lanes share a 128-B line (coalesced); plus earlier dual-tile P1/P9 work
# speedup vs baseline: 1.0846x; 1.0307x over previous
.LBB0_453:
	s_load_dwordx2 s[22:23], s[0:1], 0x60
	s_load_dwordx8 s[8:15], s[0:1], 0xa0
	s_load_dwordx4 s[16:19], s[0:1], 0xd8
	s_load_dwordx2 s[6:7], s[0:1], 0x100
	s_mov_b32 s3, 0
	s_lshl_b64 s[24:25], s[2:3], 16
	v_and_b32_e32 v0, 64, v168
	s_waitcnt lgkmcnt(0)
	s_add_u32 s18, s18, s24
	v_lshrrev_b32_e32 v1, 2, v168
	v_lshrrev_b32_e32 v3, 4, v168
	s_addc_u32 s19, s19, s25
	v_lshlrev_b32_e32 v96, 8, v168
	v_mov_b32_e32 v97, 0
	v_and_or_b32 v128, v1, 12, v0
	v_xor_b32_e32 v0, v3, v168
	v_lshrrev_b32_e32 v98, 3, v168
	v_and_b32_e32 v99, 7, v168
	v_lshlrev_b32_e32 v98, 11, v98
	v_lshl_or_b32 v98, v99, 4, v98
	v_mov_b32_e32 v99, 0
	v_lshl_add_u64 v[98:99], s[18:19], 0, v[98:99]
	v_and_b32_e32 v96, 0x3f800, v96
	v_lshlrev_b32_e32 v0, 4, v0
	s_lshr_b32 s3, s52, 1
	v_lshlrev_b32_e32 v4, 6, v168
	v_lshlrev_b32_e32 v5, 7, v168
	v_bfe_u32 v7, v168, 4, 2
	v_lshrrev_b32_e32 v8, 1, v168
	v_lshl_add_u64 v[100:101], s[8:9], 0, v[96:97]
	v_and_b32_e32 v0, 0x70, v0
	v_mov_b32_e32 v1, v97
	s_cmp_ge_u32 s2, s3
	v_and_b32_e32 v4, 0xe000, v4
	v_and_b32_e32 v6, 0x2000, v5
	v_bitop3_b32 v7, v8, v7, 7 bitop3:0x6c
	v_and_b32_e32 v5, 0x780, v5
	v_lshl_add_u64 v[106:107], s[10:11], 0, v[96:97]
	v_lshl_add_u64 v[110:111], s[12:13], 0, v[96:97]
	v_lshl_add_u64 v[114:115], s[6:7], 0, v[96:97]
	v_lshl_add_u64 v[118:119], s[14:15], 0, v[96:97]
	v_lshl_add_u64 v[102:103], v[100:101], 0, v[0:1]
	s_cselect_b64 s[18:19], -1, 0
	v_add3_u32 v4, 16, v4, v5
	v_add3_u32 v5, 16, v6, v5
	v_lshlrev_b32_e32 v6, 4, v7
	s_mov_b64 s[8:9], 0x2000000
	v_lshl_add_u64 v[108:109], v[106:107], 0, v[0:1]
	v_lshl_add_u64 v[112:113], v[110:111], 0, v[0:1]
	v_lshl_add_u64 v[116:117], v[114:115], 0, v[0:1]
	v_lshl_add_u64 v[120:121], v[118:119], 0, v[0:1]
	v_bitop3_b32 v0, v3, 7, v168 bitop3:0x48
	v_and_b32_e32 v2, 15, v168
	v_lshl_add_u32 v129, v168, 4, 16
	v_add_u32_e32 v130, v4, v6
	v_add_u32_e32 v131, v5, v6
	v_xor_b32_e32 v6, 64, v6
	v_lshl_add_u64 v[104:105], v[102:103], 0, s[8:9]
	s_movk_i32 s3, 0x1c0
	s_add_u32 s8, s22, 0x1000
	v_lshlrev_b32_e32 v96, 4, v0
	v_cndmask_b32_e64 v0, 0, 1, s[18:19]
	v_add_u32_e32 v132, v4, v6
	v_add_u32_e32 v133, v5, v6
	v_and_or_b32 v134, v8, s3, v2
	s_addc_u32 s9, s23, 0
	s_mov_b64 s[10:11], 0x10000
	v_add_u32_e32 v135, 0x1000, v129
	s_mov_b64 s[12:13], 0x20000
	v_add_u32_e32 v136, 0x2000, v129
	s_mov_b64 s[14:15], 0x30000
	v_add_u32_e32 v137, 0x3000, v129
	v_add_u32_e32 v138, 0x4000, v129
	v_add_u32_e32 v139, 0x5000, v129
	v_add_u32_e32 v140, 0x6000, v129
	v_add_u32_e32 v141, 0x7000, v129
	v_cmp_ne_u32_e64 s[6:7], 1, v0
	s_mov_b64 s[18:19], 0x80
	s_mov_b64 s[24:25], 0x10080
	s_mov_b64 s[26:27], 0x20080
	s_mov_b64 s[28:29], 0x30080
	s_mov_b64 s[30:31], 0x100
	s_mov_b64 s[34:35], 0x10100
	s_mov_b64 s[36:37], 0x20100
	s_mov_b64 s[38:39], 0x30100
	s_mov_b64 s[40:41], 0x780
	s_mov_b64 s[42:43], 0x10780
	s_mov_b64 s[44:45], 0x20780
	s_mov_b64 s[48:49], 0x30780
	s_movk_i32 s3, 0x7fff
	s_mov_b64 s[50:51], 0x2000080
	s_mov_b64 s[56:57], 0x2010080
	s_mov_b64 s[58:59], 0x2020080
	s_mov_b64 s[60:61], 0x2030080
	s_mov_b64 s[62:63], 0x2000100
	s_mov_b64 s[64:65], 0x2010100
	s_mov_b64 s[66:67], 0x2020100
	s_mov_b64 s[68:69], 0x2030100
	v_mov_b32_e32 v142, 1

.LBB0_461:
	v_add_u32_e32 v92, 0x8000, v129
	v_lshl_add_u64 v[126:127], v[78:79], 0, v[96:97]
	v_add_u32_e32 v93, 0x9000, v129
	v_readfirstlane_b32 s75, v92
	s_waitcnt vmcnt(0) lgkmcnt(0)
	s_barrier
	v_add_u32_e32 v94, 0xa000, v129
	v_lshl_add_u64 v[88:89], v[126:127], 0, s[18:19]
	v_readfirstlane_b32 s76, v93
	s_mov_b32 m0, s75
	v_add_u32_e32 v95, 0xb000, v129
	v_lshl_add_u64 v[146:147], v[126:127], 0, s[24:25]
	v_readfirstlane_b32 s77, v94
	ds_read_b128 v[80:83], v131 offset:16384
	ds_read_b128 v[84:87], v131 offset:18432
	global_load_lds_dwordx4 v[88:89], off
	s_mov_b32 m0, s76
	v_add_u32_e32 v122, 0xc000, v129
	v_lshl_add_u64 v[148:149], v[126:127], 0, s[26:27]
	v_readfirstlane_b32 s84, v95
	global_load_lds_dwordx4 v[146:147], off
	s_mov_b32 m0, s77
	v_lshl_add_u64 v[158:159], v[76:77], 0, v[96:97]
	v_add_u32_e32 v123, 0xd000, v129
	v_lshl_add_u64 v[150:151], v[126:127], 0, s[28:29]
	v_readfirstlane_b32 s85, v122
	global_load_lds_dwordx4 v[148:149], off
	s_mov_b32 m0, s84
	v_add_u32_e32 v124, 0xe000, v129
	v_lshl_add_u64 v[90:91], v[158:159], 0, s[18:19]
	v_readfirstlane_b32 s86, v123
	global_load_lds_dwordx4 v[150:151], off
	s_mov_b32 m0, s85
	v_lshl_add_u64 v[152:153], v[158:159], 0, s[24:25]
	v_readfirstlane_b32 s87, v124
	global_load_lds_dwordx4 v[90:91], off
	s_mov_b32 m0, s86
	v_lshl_add_u64 v[154:155], v[158:159], 0, s[26:27]
	global_load_lds_dwordx4 v[152:153], off
	s_mov_b32 m0, s87
	v_add_u32_e32 v125, 0xf000, v129
	global_load_lds_dwordx4 v[154:155], off
	ds_read_b128 v[88:91], v130
	ds_read_b128 v[146:149], v130 offset:2048
	ds_read_b128 v[150:153], v131 offset:20480
	ds_read_b128 v[154:157], v131 offset:22528
	v_readfirstlane_b32 s75, v125
	s_waitcnt lgkmcnt(0)
	v_mfma_f32_16x16x32_bf16 v[60:63], v[80:83], v[88:91], v[60:63]
	s_mov_b32 m0, s75
	v_readfirstlane_b32 s75, v129
	v_readfirstlane_b32 s76, v135
	v_mfma_f32_16x16x32_bf16 v[56:59], v[84:87], v[88:91], v[56:59]
	v_lshl_add_u64 v[162:163], v[126:127], 0, s[30:31]
	v_lshl_add_u64 v[166:167], v[158:159], 0, s[30:31]
	v_lshl_add_u64 v[174:175], v[158:159], 0, s[34:35]
	v_mfma_f32_16x16x32_bf16 v[52:55], v[150:153], v[88:91], v[52:55]
	v_lshl_add_u64 v[176:177], v[158:159], 0, s[36:37]
	v_lshl_add_u64 v[178:179], v[158:159], 0, s[38:39]
	v_readfirstlane_b32 s77, v136
	v_mfma_f32_16x16x32_bf16 v[48:51], v[154:157], v[88:91], v[48:51]
	v_lshl_add_u64 v[88:89], v[158:159], 0, s[28:29]
	global_load_lds_dwordx4 v[88:89], off
	v_mfma_f32_16x16x32_bf16 v[44:47], v[80:83], v[146:149], v[44:47]
	s_mov_b32 m0, s75
	v_lshl_add_u64 v[170:171], v[126:127], 0, s[34:35]
	v_readfirstlane_b32 s84, v137
	v_mfma_f32_16x16x32_bf16 v[40:43], v[84:87], v[146:149], v[40:43]
	v_lshl_add_u64 v[172:173], v[126:127], 0, s[36:37]
	v_readfirstlane_b32 s85, v138
	v_lshl_add_u64 v[126:127], v[126:127], 0, s[38:39]
	v_mfma_f32_16x16x32_bf16 v[36:39], v[150:153], v[146:149], v[36:39]
	v_readfirstlane_b32 s86, v139
	v_readfirstlane_b32 s87, v140
	v_readfirstlane_b32 s88, v141
	v_mfma_f32_16x16x32_bf16 v[32:35], v[154:157], v[146:149], v[32:35]
	ds_read_b128 v[88:91], v130 offset:4096
	ds_read_b128 v[146:149], v130 offset:6144
	s_add_i32 s71, s71, 2
	v_lshl_add_u64 v[76:77], v[76:77], 0, s[30:31]
	s_waitcnt lgkmcnt(0)
	v_mfma_f32_16x16x32_bf16 v[28:31], v[80:83], v[88:91], v[28:31]
	s_cmp_lt_u32 s71, 12
	v_lshl_add_u64 v[78:79], v[78:79], 0, s[30:31]
	v_mfma_f32_16x16x32_bf16 v[24:27], v[84:87], v[88:91], v[24:27]
	v_mfma_f32_16x16x32_bf16 v[20:23], v[150:153], v[88:91], v[20:23]
	v_mfma_f32_16x16x32_bf16 v[16:19], v[154:157], v[88:91], v[16:19]
	v_mfma_f32_16x16x32_bf16 v[12:15], v[80:83], v[146:149], v[12:15]
	v_mfma_f32_16x16x32_bf16 v[4:7], v[84:87], v[146:149], v[4:7]
	ds_read_b128 v[80:83], v133 offset:16384
	ds_read_b128 v[84:87], v133 offset:18432
	v_mfma_f32_16x16x32_bf16 v[0:3], v[150:153], v[146:149], v[0:3]
	v_mfma_f32_16x16x32_bf16 v[8:11], v[154:157], v[146:149], v[8:11]
	ds_read_b128 v[88:91], v132
	ds_read_b128 v[146:149], v132 offset:2048
	ds_read_b128 v[150:153], v133 offset:20480
	ds_read_b128 v[154:157], v133 offset:22528
	s_waitcnt lgkmcnt(0)
	v_mfma_f32_16x16x32_bf16 v[60:63], v[80:83], v[88:91], v[60:63]
	v_mfma_f32_16x16x32_bf16 v[56:59], v[84:87], v[88:91], v[56:59]
	v_mfma_f32_16x16x32_bf16 v[52:55], v[150:153], v[88:91], v[52:55]
	v_mfma_f32_16x16x32_bf16 v[48:51], v[154:157], v[88:91], v[48:51]
	ds_read_b128 v[88:91], v132 offset:4096
	ds_read_b128 v[158:161], v132 offset:6144
	s_waitcnt vmcnt(0) lgkmcnt(0)
	s_barrier
	global_load_lds_dwordx4 v[162:163], off
	s_mov_b32 m0, s76
	v_mfma_f32_16x16x32_bf16 v[44:47], v[80:83], v[146:149], v[44:47]
	v_mfma_f32_16x16x32_bf16 v[40:43], v[84:87], v[146:149], v[40:43]
	v_mfma_f32_16x16x32_bf16 v[36:39], v[150:153], v[146:149], v[36:39]
	v_mfma_f32_16x16x32_bf16 v[32:35], v[154:157], v[146:149], v[32:35]
	ds_read_b128 v[146:149], v131 offset:49152
	ds_read_b128 v[162:165], v131 offset:51200
	global_load_lds_dwordx4 v[170:171], off
	s_mov_b32 m0, s77
	s_waitcnt lgkmcnt(0)
	v_mfma_f32_16x16x32_bf16 v[28:31], v[80:83], v[88:91], v[28:31]
	global_load_lds_dwordx4 v[172:173], off
	s_mov_b32 m0, s84
	v_mfma_f32_16x16x32_bf16 v[24:27], v[84:87], v[88:91], v[24:27]
	global_load_lds_dwordx4 v[126:127], off
	s_mov_b32 m0, s85
	v_mfma_f32_16x16x32_bf16 v[20:23], v[150:153], v[88:91], v[20:23]
	global_load_lds_dwordx4 v[166:167], off
	s_mov_b32 m0, s86
	v_mfma_f32_16x16x32_bf16 v[16:19], v[154:157], v[88:91], v[16:19]
	global_load_lds_dwordx4 v[174:175], off
	s_mov_b32 m0, s87
	v_mfma_f32_16x16x32_bf16 v[12:15], v[80:83], v[158:161], v[12:15]
	global_load_lds_dwordx4 v[176:177], off
	s_mov_b32 m0, s88
	v_mfma_f32_16x16x32_bf16 v[4:7], v[84:87], v[158:161], v[4:7]
	global_load_lds_dwordx4 v[178:179], off
	ds_read_b128 v[80:83], v130 offset:32768
	ds_read_b128 v[84:87], v130 offset:34816
	v_mfma_f32_16x16x32_bf16 v[0:3], v[150:153], v[158:161], v[0:3]
	ds_read_b128 v[88:91], v131 offset:53248
	ds_read_b128 v[150:153], v131 offset:55296
	s_waitcnt lgkmcnt(0)
	v_mfma_f32_16x16x32_bf16 v[60:63], v[146:149], v[80:83], v[60:63]
	v_mfma_f32_16x16x32_bf16 v[56:59], v[162:165], v[80:83], v[56:59]
	v_mfma_f32_16x16x32_bf16 v[52:55], v[88:91], v[80:83], v[52:55]
	v_mfma_f32_16x16x32_bf16 v[48:51], v[150:153], v[80:83], v[48:51]
	v_mfma_f32_16x16x32_bf16 v[44:47], v[146:149], v[84:87], v[44:47]
	v_mfma_f32_16x16x32_bf16 v[40:43], v[162:165], v[84:87], v[40:43]
	v_mfma_f32_16x16x32_bf16 v[36:39], v[88:91], v[84:87], v[36:39]
	v_mfma_f32_16x16x32_bf16 v[32:35], v[150:153], v[84:87], v[32:35]
	ds_read_b128 v[80:83], v130 offset:36864
	ds_read_b128 v[84:87], v130 offset:38912
	v_mfma_f32_16x16x32_bf16 v[8:11], v[154:157], v[158:161], v[8:11]
	s_waitcnt lgkmcnt(0)
	v_mfma_f32_16x16x32_bf16 v[28:31], v[146:149], v[80:83], v[28:31]
	v_mfma_f32_16x16x32_bf16 v[24:27], v[162:165], v[80:83], v[24:27]
	v_mfma_f32_16x16x32_bf16 v[20:23], v[88:91], v[80:83], v[20:23]
	v_mfma_f32_16x16x32_bf16 v[16:19], v[150:153], v[80:83], v[16:19]
	v_mfma_f32_16x16x32_bf16 v[12:15], v[146:149], v[84:87], v[12:15]
	v_mfma_f32_16x16x32_bf16 v[4:7], v[162:165], v[84:87], v[4:7]
	v_mfma_f32_16x16x32_bf16 v[0:3], v[88:91], v[84:87], v[0:3]
	ds_read_b128 v[80:83], v133 offset:49152
	ds_read_b128 v[88:91], v133 offset:51200
	v_mfma_f32_16x16x32_bf16 v[8:11], v[150:153], v[84:87], v[8:11]
	ds_read_b128 v[84:87], v132 offset:32768
	ds_read_b128 v[146:149], v132 offset:34816
	ds_read_b128 v[150:153], v133 offset:53248
	ds_read_b128 v[154:157], v133 offset:55296
	s_waitcnt lgkmcnt(0)
	v_mfma_f32_16x16x32_bf16 v[60:63], v[80:83], v[84:87], v[60:63]
	v_mfma_f32_16x16x32_bf16 v[56:59], v[88:91], v[84:87], v[56:59]
	v_mfma_f32_16x16x32_bf16 v[52:55], v[150:153], v[84:87], v[52:55]
	v_mfma_f32_16x16x32_bf16 v[48:51], v[154:157], v[84:87], v[48:51]
	v_mfma_f32_16x16x32_bf16 v[44:47], v[80:83], v[146:149], v[44:47]
	v_mfma_f32_16x16x32_bf16 v[40:43], v[88:91], v[146:149], v[40:43]
	v_mfma_f32_16x16x32_bf16 v[36:39], v[150:153], v[146:149], v[36:39]
	v_mfma_f32_16x16x32_bf16 v[32:35], v[154:157], v[146:149], v[32:35]
	ds_read_b128 v[84:87], v132 offset:36864
	ds_read_b128 v[146:149], v132 offset:38912
	s_waitcnt lgkmcnt(0)
	v_mfma_f32_16x16x32_bf16 v[28:31], v[80:83], v[84:87], v[28:31]
	v_mfma_f32_16x16x32_bf16 v[24:27], v[88:91], v[84:87], v[24:27]
	v_mfma_f32_16x16x32_bf16 v[20:23], v[150:153], v[84:87], v[20:23]
	v_mfma_f32_16x16x32_bf16 v[16:19], v[154:157], v[84:87], v[16:19]
	v_mfma_f32_16x16x32_bf16 v[12:15], v[80:83], v[146:149], v[12:15]
	v_mfma_f32_16x16x32_bf16 v[4:7], v[88:91], v[146:149], v[4:7]
	v_mfma_f32_16x16x32_bf16 v[0:3], v[150:153], v[146:149], v[0:3]
	v_mfma_f32_16x16x32_bf16 v[8:11], v[154:157], v[146:149], v[8:11]
	s_cbranch_scc1 .LBB0_461
	v_readfirstlane_b32 s71, v92
	s_waitcnt vmcnt(0) lgkmcnt(0)
	s_barrier
	v_lshl_add_u64 v[76:77], v[68:69], 0, s[40:41]
	s_mov_b32 m0, s71
	v_readfirstlane_b32 s71, v93
	global_load_lds_dwordx4 v[76:77], off
	v_lshl_add_u64 v[78:79], v[68:69], 0, s[42:43]
	s_mov_b32 m0, s71
	v_readfirstlane_b32 s71, v94
	global_load_lds_dwordx4 v[78:79], off
	v_lshl_add_u64 v[80:81], v[68:69], 0, s[44:45]
	s_mov_b32 m0, s71
	v_readfirstlane_b32 s71, v95
	global_load_lds_dwordx4 v[80:81], off
	v_lshl_add_u64 v[82:83], v[68:69], 0, s[48:49]
	s_mov_b32 m0, s71
	v_readfirstlane_b32 s71, v122
	v_lshl_add_u64 v[84:85], v[66:67], 0, s[40:41]
	global_load_lds_dwordx4 v[82:83], off
	s_mov_b32 m0, s71
	v_readfirstlane_b32 s71, v123
	global_load_lds_dwordx4 v[84:85], off
	v_lshl_add_u64 v[84:85], v[66:67], 0, s[42:43]
	s_mov_b32 m0, s71
	v_readfirstlane_b32 s71, v124
	global_load_lds_dwordx4 v[84:85], off
	v_lshl_add_u64 v[88:89], v[66:67], 0, s[44:45]
	s_mov_b32 m0, s71
	ds_read_b128 v[84:87], v131 offset:16384
	global_load_lds_dwordx4 v[88:89], off
	ds_read_b128 v[88:91], v131 offset:18432
	ds_read_b128 v[146:149], v130
	ds_read_b128 v[150:153], v130 offset:2048
	ds_read_b128 v[154:157], v131 offset:20480
	ds_read_b128 v[158:161], v131 offset:22528
	v_readfirstlane_b32 s71, v125
	v_lshl_add_u64 v[66:67], v[66:67], 0, s[48:49]
	s_mov_b32 m0, s71
	s_waitcnt lgkmcnt(0)
	v_mfma_f32_16x16x32_bf16 v[60:63], v[84:87], v[146:149], v[60:63]
	global_load_lds_dwordx4 v[66:67], off
	v_or_b32_e32 v66, s83, v128
	v_mfma_f32_16x16x32_bf16 v[56:59], v[88:91], v[146:149], v[56:59]
	v_ashrrev_i32_e32 v67, 31, v66
	v_lshl_add_u64 v[126:127], v[66:67], 2, s[22:23]
	v_readfirstlane_b32 s71, v129
	v_mfma_f32_16x16x32_bf16 v[52:55], v[154:157], v[146:149], v[52:55]
	s_mov_b32 m0, s71
	v_readfirstlane_b32 s71, v135
	s_ashr_i32 s75, s74, 31
	v_mfma_f32_16x16x32_bf16 v[48:51], v[158:161], v[146:149], v[48:51]
	s_lshl_b64 s[74:75], s[74:75], 18
	v_mfma_f32_16x16x32_bf16 v[44:47], v[84:87], v[150:153], v[44:47]
	v_mfma_f32_16x16x32_bf16 v[40:43], v[88:91], v[150:153], v[40:43]
	v_mfma_f32_16x16x32_bf16 v[36:39], v[154:157], v[150:153], v[36:39]
	v_mfma_f32_16x16x32_bf16 v[32:35], v[158:161], v[150:153], v[32:35]
	ds_read_b128 v[146:149], v130 offset:4096
	ds_read_b128 v[150:153], v130 offset:6144
	s_waitcnt lgkmcnt(0)
	v_mfma_f32_16x16x32_bf16 v[28:31], v[84:87], v[146:149], v[28:31]
	v_mfma_f32_16x16x32_bf16 v[24:27], v[88:91], v[146:149], v[24:27]
	v_mfma_f32_16x16x32_bf16 v[20:23], v[154:157], v[146:149], v[20:23]
	v_mfma_f32_16x16x32_bf16 v[12:15], v[84:87], v[150:153], v[12:15]
	v_mfma_f32_16x16x32_bf16 v[84:87], v[88:91], v[150:153], v[4:7]
	v_mfma_f32_16x16x32_bf16 v[88:91], v[154:157], v[150:153], v[0:3]
	ds_read_b128 v[154:157], v133 offset:16384
	v_mfma_f32_16x16x32_bf16 v[8:11], v[158:161], v[150:153], v[8:11]
	ds_read_b128 v[150:153], v133 offset:18432
	ds_read_b128 v[0:3], v132
	ds_read_b128 v[4:7], v132 offset:2048
	v_mfma_f32_16x16x32_bf16 v[146:149], v[158:161], v[146:149], v[16:19]
	ds_read_b128 v[158:161], v133 offset:22528
	s_waitcnt lgkmcnt(0)
	v_mfma_f32_16x16x32_bf16 v[16:19], v[154:157], v[0:3], v[60:63]
	s_nop 2
	ds_read_b128 v[60:63], v133 offset:20480
	ds_read_b128 v[162:165], v132 offset:4096
	ds_read_b128 v[170:173], v132 offset:6144
	s_waitcnt vmcnt(0) lgkmcnt(0)
	s_barrier
	ds_read_b128 v[174:177], v130 offset:32768
	ds_read_b128 v[178:181], v130 offset:34816
	ds_read_b128 v[182:185], v130 offset:36864
	ds_read_b128 v[186:189], v130 offset:38912
	ds_read_b128 v[190:193], v131 offset:49152
	ds_read_b128 v[194:197], v131 offset:51200
	ds_read_b128 v[198:201], v131 offset:53248
	ds_read_b128 v[202:205], v131 offset:55296
	ds_read_b128 v[206:209], v132 offset:32768
	ds_read_b128 v[210:213], v132 offset:34816
	ds_read_b128 v[214:217], v132 offset:36864
	ds_read_b128 v[218:221], v132 offset:38912
	ds_read_b128 v[222:225], v133 offset:49152
	ds_read_b128 v[226:229], v133 offset:51200
	ds_read_b128 v[230:233], v133 offset:53248
	ds_read_b128 v[234:237], v133 offset:55296
	s_waitcnt lgkmcnt(0)
	s_waitcnt lgkmcnt(0)
	v_mfma_f32_16x16x32_bf16 v[238:241], v[60:63], v[162:165], v[20:23]
	s_nop 2
	global_load_dwordx4 v[20:23], v[126:127], off
	v_mfma_f32_16x16x32_bf16 v[56:59], v[150:153], v[0:3], v[56:59]
	v_mfma_f32_16x16x32_bf16 v[52:55], v[60:63], v[0:3], v[52:55]
	v_mfma_f32_16x16x32_bf16 v[48:51], v[158:161], v[0:3], v[48:51]
	v_mfma_f32_16x16x32_bf16 v[0:3], v[190:193], v[174:177], v[16:19]
	s_nop 2
	global_load_dwordx4 v[16:19], v[126:127], off offset:64
	v_mfma_f32_16x16x32_bf16 v[56:59], v[194:197], v[174:177], v[56:59]
	v_mfma_f32_16x16x32_bf16 v[242:245], v[222:225], v[206:209], v[0:3]
	v_mfma_f32_16x16x32_bf16 v[56:59], v[226:229], v[206:209], v[56:59]
	v_mfma_f32_16x16x32_bf16 v[44:47], v[154:157], v[4:7], v[44:47]
	s_waitcnt vmcnt(0)
	s_nop 4
	v_add_f32_e32 v143, v245, v23
	v_mfma_f32_16x16x32_bf16 v[40:43], v[150:153], v[4:7], v[40:43]
	v_mul_f32_e32 v143, 0xbfb8aa3b, v143
	v_add_f32_e32 v56, v56, v16
	v_mfma_f32_16x16x32_bf16 v[36:39], v[60:63], v[4:7], v[36:39]
	v_mul_f32_e32 v56, 0xbfb8aa3b, v56
	v_mfma_f32_16x16x32_bf16 v[32:35], v[158:161], v[4:7], v[32:35]
	global_load_dwordx4 v[4:7], v[126:127], off offset:128
	global_load_dwordx4 v[0:3], v[126:127], off offset:192
	v_add_f32_e32 v127, v243, v21
	v_mul_f32_e32 v127, 0xbfb8aa3b, v127
	v_mfma_f32_16x16x32_bf16 v[28:31], v[154:157], v[162:165], v[28:31]
	v_add_f32_e32 v126, v242, v20
	v_mul_f32_e32 v126, 0xbfb8aa3b, v126
	v_exp_f32_e32 v126, v126
	v_mfma_f32_16x16x32_bf16 v[12:15], v[154:157], v[170:173], v[12:15]
	v_exp_f32_e32 v154, v127
	v_add_f32_e32 v127, v244, v22
	v_mul_f32_e32 v127, 0xbfb8aa3b, v127
	v_mfma_f32_16x16x32_bf16 v[24:27], v[150:153], v[162:165], v[24:27]
	v_exp_f32_e32 v127, v127
	v_exp_f32_e32 v155, v143
	v_mfma_f32_16x16x32_bf16 v[146:149], v[158:161], v[162:165], v[146:149]
	v_exp_f32_e32 v162, v56
	v_add_f32_e32 v56, v57, v17
	v_mul_f32_e32 v56, 0xbfb8aa3b, v56
	v_exp_f32_e32 v164, v56
	v_add_f32_e32 v56, v58, v18
	v_mul_f32_e32 v56, 0xbfb8aa3b, v56
	v_exp_f32_e32 v163, v56
	v_pk_add_f32 v[56:57], v[126:127], 1.0 op_sel_hi:[1,0]
	v_add_f32_e32 v58, v59, v19
	v_div_scale_f32 v59, s[76:77], v56, v56, 1.0
	v_mfma_f32_16x16x32_bf16 v[60:63], v[60:63], v[170:173], v[88:91]
	v_mul_f32_e32 v58, 0xbfb8aa3b, v58
	v_exp_f32_e32 v165, v58
	s_nop 0
	v_rcp_f32_e32 v88, v59
	v_mfma_f32_16x16x32_bf16 v[48:51], v[202:205], v[174:177], v[48:51]
	v_fma_f32 v58, -v59, v88, 1.0
	v_fmac_f32_e32 v88, v58, v88
	v_div_scale_f32 v58, vcc, 1.0, v56, 1.0
	v_mul_f32_e32 v89, v58, v88
	v_fma_f32 v90, -v59, v89, v58
	v_fmac_f32_e32 v89, v90, v88
	v_fma_f32 v58, -v59, v89, v58
	v_div_scale_f32 v59, s[76:77], v57, v57, 1.0
	v_rcp_f32_e32 v143, v59
	v_div_fmas_f32 v58, v58, v88, v89
	v_div_fixup_f32 v145, v58, v56, 1.0
	v_mfma_f32_16x16x32_bf16 v[84:87], v[150:153], v[170:173], v[84:87]
	v_fma_f32 v56, -v59, v143, 1.0
	v_fmac_f32_e32 v143, v56, v143
	v_div_scale_f32 v56, vcc, 1.0, v57, 1.0
	v_mul_f32_e32 v58, v56, v143
	v_fma_f32 v126, -v59, v58, v56
	v_fmac_f32_e32 v58, v126, v143
	v_pk_add_f32 v[126:127], v[154:155], 1.0 op_sel_hi:[1,0]
	v_fma_f32 v56, -v59, v58, v56
	v_div_scale_f32 v59, s[76:77], v126, v126, 1.0
	v_rcp_f32_e32 v166, v59
	v_div_fmas_f32 v56, v56, v143, v58
	v_div_fixup_f32 v143, v56, v57, 1.0
	v_div_scale_f32 v167, s[76:77], v127, v127, 1.0
	v_fma_f32 v56, -v59, v166, 1.0
	v_fmac_f32_e32 v166, v56, v166
	v_div_scale_f32 v56, vcc, 1.0, v126, 1.0
	v_mul_f32_e32 v57, v56, v166
	v_mfma_f32_16x16x32_bf16 v[8:11], v[158:161], v[170:173], v[8:11]
	v_fma_f32 v58, -v59, v57, v56
	v_rcp_f32_e32 v170, v167
	v_fmac_f32_e32 v57, v58, v166
	v_mfma_f32_16x16x32_bf16 v[44:47], v[190:193], v[178:181], v[44:47]
	v_fma_f32 v56, -v59, v57, v56
	v_mfma_f32_16x16x32_bf16 v[40:43], v[194:197], v[178:181], v[40:43]
	v_mfma_f32_16x16x32_bf16 v[158:161], v[234:237], v[206:209], v[48:51]
	s_nop 2
	v_div_fmas_f32 v48, v56, v166, v57
	v_div_fixup_f32 v126, v48, v126, 1.0
	v_fma_f32 v48, -v167, v170, 1.0
	v_mfma_f32_16x16x32_bf16 v[52:55], v[198:201], v[174:177], v[52:55]
	v_fmac_f32_e32 v170, v48, v170
	v_mfma_f32_16x16x32_bf16 v[36:39], v[198:201], v[178:181], v[36:39]
	v_mfma_f32_16x16x32_bf16 v[150:153], v[198:201], v[186:189], v[60:63]
	v_mfma_f32_16x16x32_bf16 v[60:63], v[222:225], v[210:213], v[44:47]
	s_nop 2
	v_div_scale_f32 v44, vcc, 1.0, v127, 1.0
	v_mfma_f32_16x16x32_bf16 v[56:59], v[226:229], v[210:213], v[40:43]
	s_nop 2
	v_add_f32_e32 v61, v61, v21
	v_mul_f32_e32 v61, 0xbfb8aa3b, v61
	v_add_f32_e32 v60, v60, v20
	v_mul_f32_e32 v40, v44, v170
	v_mfma_f32_16x16x32_bf16 v[32:35], v[202:205], v[178:181], v[32:35]
	v_fma_f32 v41, -v167, v40, v44
	v_fmac_f32_e32 v40, v41, v170
	v_mul_f32_e32 v60, 0xbfb8aa3b, v60
	v_mfma_f32_16x16x32_bf16 v[24:27], v[194:197], v[182:185], v[24:27]
	v_exp_f32_e32 v60, v60
	v_add_f32_e32 v57, v57, v17
	v_mul_f32_e32 v57, 0xbfb8aa3b, v57
	v_mfma_f32_16x16x32_bf16 v[88:91], v[198:201], v[182:185], v[238:241]
	v_add_f32_e32 v59, v59, v19
	v_mul_f32_e32 v59, 0xbfb8aa3b, v59
	v_add_f32_e32 v56, v56, v16
	v_mfma_f32_16x16x32_bf16 v[154:157], v[230:233], v[206:209], v[52:55]
	v_mul_f32_e32 v56, 0xbfb8aa3b, v56
	v_exp_f32_e32 v56, v56
	v_mfma_f32_16x16x32_bf16 v[52:55], v[230:233], v[210:213], v[36:39]
	s_nop 2
	v_fma_f32 v36, -v167, v40, v44
	v_div_fmas_f32 v36, v36, v170, v40
	v_mfma_f32_16x16x32_bf16 v[28:31], v[190:193], v[182:185], v[28:31]
	s_waitcnt vmcnt(1)
	s_nop 0
	v_add_f32_e32 v53, v53, v5
	v_mul_f32_e32 v53, 0xbfb8aa3b, v53
	v_add_f32_e32 v52, v52, v4
	v_mfma_f32_16x16x32_bf16 v[48:51], v[234:237], v[210:213], v[32:35]
	v_mul_f32_e32 v52, 0xbfb8aa3b, v52
	v_exp_f32_e32 v52, v52
	s_nop 0
	v_div_fixup_f32 v32, v36, v127, 1.0
	v_mfma_f32_16x16x32_bf16 v[40:43], v[226:229], v[214:217], v[24:27]
	v_and_b32_sdwa v34, v145, v142 dst_sel:DWORD dst_unused:UNUSED_PAD src0_sel:WORD_1 src1_sel:DWORD
	v_add3_u32 v127, v145, v34, s3
	v_and_b32_sdwa v33, v143, v142 dst_sel:DWORD dst_unused:UNUSED_PAD src0_sel:WORD_1 src1_sel:DWORD
	v_and_b32_sdwa v24, v126, v142 dst_sel:DWORD dst_unused:UNUSED_PAD src0_sel:WORD_1 src1_sel:DWORD
	v_mfma_f32_16x16x32_bf16 v[36:39], v[230:233], v[214:217], v[88:91]
	v_add3_u32 v24, v126, v24, s3
	v_add3_u32 v143, v143, v33, s3
	v_and_b32_e32 v24, 0xffff0000, v24
	v_pk_add_f32 v[90:91], v[162:163], 1.0 op_sel_hi:[1,0]
	v_mfma_f32_16x16x32_bf16 v[12:15], v[190:193], v[186:189], v[12:15]
	v_div_scale_f32 v126, s[76:77], v90, v90, 1.0
	v_rcp_f32_e32 v145, v126
	v_mfma_f32_16x16x32_bf16 v[84:87], v[194:197], v[186:189], v[84:87]
	v_or_b32_sdwa v88, v24, v127 dst_sel:DWORD dst_unused:UNUSED_PAD src0_sel:DWORD src1_sel:WORD_1
	s_waitcnt vmcnt(0)
	v_add_f32_e32 v49, v49, v1
	v_mul_f32_e32 v49, 0xbfb8aa3b, v49
	v_mfma_f32_16x16x32_bf16 v[44:47], v[222:225], v[214:217], v[28:31]
	v_add_f32_e32 v51, v51, v3
	v_mul_f32_e32 v51, 0xbfb8aa3b, v51
	v_add_f32_e32 v48, v48, v0
	v_and_b32_sdwa v28, v32, v142 dst_sel:DWORD dst_unused:UNUSED_PAD src0_sel:WORD_1 src1_sel:DWORD
	v_add3_u32 v25, v32, v28, s3
	v_and_b32_e32 v25, 0xffff0000, v25
	v_mfma_f32_16x16x32_bf16 v[28:31], v[222:225], v[218:221], v[12:15]
	v_or_b32_sdwa v89, v25, v143 dst_sel:DWORD dst_unused:UNUSED_PAD src0_sel:DWORD src1_sel:WORD_1
	v_mul_f32_e32 v48, 0xbfb8aa3b, v48
	v_exp_f32_e32 v48, v48
	v_fma_f32 v12, -v126, v145, 1.0
	v_mfma_f32_16x16x32_bf16 v[24:27], v[226:229], v[218:221], v[84:87]
	v_fmac_f32_e32 v145, v12, v145
	v_add_f32_e32 v45, v45, v21
	v_mul_f32_e32 v45, 0xbfb8aa3b, v45
	v_div_scale_f32 v84, vcc, 1.0, v90, 1.0
	v_mul_f32_e32 v85, v84, v145
	v_fma_f32 v86, -v126, v85, v84
	v_fmac_f32_e32 v85, v86, v145
	v_div_scale_f32 v86, s[76:77], v91, v91, 1.0
	v_rcp_f32_e32 v87, v86
	v_fma_f32 v84, -v126, v85, v84
	v_div_fmas_f32 v84, v84, v145, v85
	v_div_fixup_f32 v90, v84, v90, 1.0
	v_fma_f32 v84, -v86, v87, 1.0
	v_fmac_f32_e32 v87, v84, v87
	v_div_scale_f32 v84, vcc, 1.0, v91, 1.0
	v_mul_f32_e32 v126, v84, v87
	v_fma_f32 v85, -v86, v126, v84
	v_fmac_f32_e32 v126, v85, v87
	v_fma_f32 v86, -v86, v126, v84
	v_pk_add_f32 v[84:85], v[164:165], 1.0 op_sel_hi:[1,0]
	v_div_fmas_f32 v86, v86, v87, v126
	v_div_scale_f32 v127, s[76:77], v84, v84, 1.0
	v_rcp_f32_e32 v143, v127
	v_div_fixup_f32 v86, v86, v91, 1.0
	v_mfma_f32_16x16x32_bf16 v[146:149], v[202:205], v[182:185], v[146:149]
	v_add_f32_e32 v44, v44, v20
	v_fma_f32 v87, -v127, v143, 1.0
	v_fmac_f32_e32 v143, v87, v143
	v_div_scale_f32 v87, vcc, 1.0, v84, 1.0
	v_mul_f32_e32 v91, v87, v143
	v_fma_f32 v126, -v127, v91, v87
	v_fmac_f32_e32 v91, v126, v143
	v_div_scale_f32 v126, s[76:77], v85, v85, 1.0
	v_fma_f32 v87, -v127, v91, v87
	v_rcp_f32_e32 v127, v126
	v_div_fmas_f32 v87, v87, v143, v91
	v_div_fixup_f32 v84, v87, v84, 1.0
	v_mfma_f32_16x16x32_bf16 v[32:35], v[234:237], v[214:217], v[146:149]
	v_fma_f32 v87, -v126, v127, 1.0
	v_fmac_f32_e32 v127, v87, v127
	v_div_scale_f32 v87, vcc, 1.0, v85, 1.0
	v_mul_f32_e32 v91, v87, v127
	v_fma_f32 v143, -v126, v91, v87
	v_fmac_f32_e32 v91, v143, v127
	v_fma_f32 v87, -v126, v91, v87
	v_div_fmas_f32 v87, v87, v127, v91
	v_div_fixup_f32 v85, v87, v85, 1.0
	v_and_b32_sdwa v87, v86, v142 dst_sel:DWORD dst_unused:UNUSED_PAD src0_sel:WORD_1 src1_sel:DWORD
	v_add3_u32 v86, v86, v87, s3
	v_and_b32_sdwa v87, v85, v142 dst_sel:DWORD dst_unused:UNUSED_PAD src0_sel:WORD_1 src1_sel:DWORD
	v_and_b32_sdwa v91, v90, v142 dst_sel:DWORD dst_unused:UNUSED_PAD src0_sel:WORD_1 src1_sel:DWORD
	v_add3_u32 v85, v85, v87, s3
	v_add3_u32 v90, v90, v91, s3
	v_and_b32_sdwa v91, v84, v142 dst_sel:DWORD dst_unused:UNUSED_PAD src0_sel:WORD_1 src1_sel:DWORD
	v_and_b32_e32 v85, 0xffff0000, v85
	v_add3_u32 v84, v84, v91, s3
	v_or_b32_sdwa v91, v85, v86 dst_sel:DWORD dst_unused:UNUSED_PAD src0_sel:DWORD src1_sel:WORD_1
	v_add_f32_e32 v85, v155, v5
	v_and_b32_e32 v84, 0xffff0000, v84
	v_mul_f32_e32 v85, 0xbfb8aa3b, v85
	v_or_b32_sdwa v90, v84, v90 dst_sel:DWORD dst_unused:UNUSED_PAD src0_sel:DWORD src1_sel:WORD_1
	v_add_f32_e32 v84, v154, v4
	v_exp_f32_e32 v86, v85
	v_add_f32_e32 v85, v156, v6
	v_mul_f32_e32 v84, 0xbfb8aa3b, v84
	v_mul_f32_e32 v85, 0xbfb8aa3b, v85
	v_exp_f32_e32 v84, v84
	v_exp_f32_e32 v85, v85
	v_add_f32_e32 v87, v157, v7
	v_mul_f32_e32 v87, 0xbfb8aa3b, v87
	v_exp_f32_e32 v87, v87
	v_pk_add_f32 v[84:85], v[84:85], 1.0 op_sel_hi:[1,0]
	global_store_dwordx4 v[98:99], v[88:91], off
	v_div_scale_f32 v126, s[76:77], v84, v84, 1.0
	v_rcp_f32_e32 v127, v126
	v_pk_add_f32 v[86:87], v[86:87], 1.0 op_sel_hi:[1,0]
	v_add_f32_e32 v89, v159, v1
	v_mul_f32_e32 v89, 0xbfb8aa3b, v89
	v_fma_f32 v143, -v126, v127, 1.0
	v_fmac_f32_e32 v127, v143, v127
	v_div_scale_f32 v143, vcc, 1.0, v84, 1.0
	v_mul_f32_e32 v145, v143, v127
	v_fma_f32 v146, -v126, v145, v143
	v_fmac_f32_e32 v145, v146, v127
	v_fma_f32 v126, -v126, v145, v143
	v_div_scale_f32 v143, s[76:77], v85, v85, 1.0
	v_rcp_f32_e32 v146, v143
	v_div_fmas_f32 v126, v126, v127, v145
	v_div_fixup_f32 v84, v126, v84, 1.0
	v_add_f32_e32 v88, v158, v0
	v_fma_f32 v126, -v143, v146, 1.0
	v_fmac_f32_e32 v146, v126, v146
	v_div_scale_f32 v126, vcc, 1.0, v85, 1.0
	v_mul_f32_e32 v127, v126, v146
	v_fma_f32 v145, -v143, v127, v126
	v_fmac_f32_e32 v127, v145, v146
	v_fma_f32 v126, -v143, v127, v126
	v_div_scale_f32 v143, s[76:77], v86, v86, 1.0
	v_rcp_f32_e32 v145, v143
	v_div_fmas_f32 v126, v126, v146, v127
	v_div_fixup_f32 v85, v126, v85, 1.0
	v_exp_f32_e32 v90, v89
	v_fma_f32 v126, -v143, v145, 1.0
	v_fmac_f32_e32 v145, v126, v145
	v_div_scale_f32 v126, vcc, 1.0, v86, 1.0
	v_mul_f32_e32 v127, v126, v145
	v_fma_f32 v146, -v143, v127, v126
	v_fmac_f32_e32 v127, v146, v145
	v_fma_f32 v126, -v143, v127, v126
	v_div_scale_f32 v143, s[76:77], v87, v87, 1.0
	v_rcp_f32_e32 v146, v143
	v_div_fmas_f32 v126, v126, v145, v127
	v_div_fixup_f32 v86, v126, v86, 1.0
	v_add_f32_e32 v89, v160, v2
	v_fma_f32 v126, -v143, v146, 1.0
	v_fmac_f32_e32 v146, v126, v146
	v_div_scale_f32 v126, vcc, 1.0, v87, 1.0
	v_mul_f32_e32 v127, v126, v146
	v_fma_f32 v145, -v143, v127, v126
	v_fmac_f32_e32 v127, v145, v146
	v_mul_f32_e32 v88, 0xbfb8aa3b, v88
	v_mul_f32_e32 v89, 0xbfb8aa3b, v89
	v_fma_f32 v126, -v143, v127, v126
	v_exp_f32_e32 v88, v88
	v_exp_f32_e32 v89, v89
	v_div_fmas_f32 v126, v126, v146, v127
	v_div_fixup_f32 v87, v126, v87, 1.0
	v_and_b32_sdwa v126, v85, v142 dst_sel:DWORD dst_unused:UNUSED_PAD src0_sel:WORD_1 src1_sel:DWORD
	v_and_b32_sdwa v127, v84, v142 dst_sel:DWORD dst_unused:UNUSED_PAD src0_sel:WORD_1 src1_sel:DWORD
	v_add3_u32 v85, v85, v126, s3
	v_and_b32_sdwa v126, v87, v142 dst_sel:DWORD dst_unused:UNUSED_PAD src0_sel:WORD_1 src1_sel:DWORD
	v_add3_u32 v84, v84, v127, s3
	v_and_b32_sdwa v127, v86, v142 dst_sel:DWORD dst_unused:UNUSED_PAD src0_sel:WORD_1 src1_sel:DWORD
	v_add3_u32 v87, v87, v126, s3
	v_add3_u32 v126, v86, v127, s3
	v_and_b32_e32 v127, 0xffff0000, v87
	v_pk_add_f32 v[86:87], v[88:89], 1.0 op_sel_hi:[1,0]
	v_and_b32_e32 v126, 0xffff0000, v126
	v_div_scale_f32 v88, s[76:77], v86, v86, 1.0
	v_rcp_f32_e32 v89, v88
	v_or_b32_sdwa v84, v126, v84 dst_sel:DWORD dst_unused:UNUSED_PAD src0_sel:DWORD src1_sel:WORD_1
	v_or_b32_sdwa v85, v127, v85 dst_sel:DWORD dst_unused:UNUSED_PAD src0_sel:DWORD src1_sel:WORD_1
	v_add_f32_e32 v91, v161, v3
	v_fma_f32 v126, -v88, v89, 1.0
	v_fmac_f32_e32 v89, v126, v89
	v_div_scale_f32 v126, vcc, 1.0, v86, 1.0
	v_mul_f32_e32 v127, v126, v89
	v_fma_f32 v143, -v88, v127, v126
	v_fmac_f32_e32 v127, v143, v89
	v_fma_f32 v88, -v88, v127, v126
	v_div_scale_f32 v126, s[76:77], v87, v87, 1.0
	v_rcp_f32_e32 v143, v126
	v_div_fmas_f32 v88, v88, v89, v127
	v_mul_f32_e32 v91, 0xbfb8aa3b, v91
	v_div_fixup_f32 v86, v88, v86, 1.0
	v_fma_f32 v88, -v126, v143, 1.0
	v_exp_f32_e32 v91, v91
	v_fmac_f32_e32 v143, v88, v143
	v_div_scale_f32 v88, vcc, 1.0, v87, 1.0
	v_mul_f32_e32 v127, v88, v143
	v_fma_f32 v89, -v126, v127, v88
	v_fmac_f32_e32 v127, v89, v143
	v_fma_f32 v126, -v126, v127, v88
	v_pk_add_f32 v[88:89], v[90:91], 1.0 op_sel_hi:[1,0]
	v_div_fmas_f32 v126, v126, v143, v127
	v_div_scale_f32 v90, s[76:77], v88, v88, 1.0
	v_rcp_f32_e32 v91, v90
	v_div_fixup_f32 v87, v126, v87, 1.0
	v_mul_f32_e32 v44, 0xbfb8aa3b, v44
	v_exp_f32_e32 v44, v44
	v_fma_f32 v126, -v90, v91, 1.0
	v_fmac_f32_e32 v91, v126, v91
	v_div_scale_f32 v126, vcc, 1.0, v88, 1.0
	v_mul_f32_e32 v127, v126, v91
	v_fma_f32 v143, -v90, v127, v126
	v_fmac_f32_e32 v127, v143, v91
	v_fma_f32 v90, -v90, v127, v126
	v_div_scale_f32 v126, s[76:77], v89, v89, 1.0
	v_rcp_f32_e32 v143, v126
	v_div_fmas_f32 v90, v90, v91, v127
	v_div_fixup_f32 v88, v90, v88, 1.0
	v_add_f32_e32 v41, v41, v17
	v_fma_f32 v90, -v126, v143, 1.0
	v_fmac_f32_e32 v143, v90, v143
	v_div_scale_f32 v90, vcc, 1.0, v89, 1.0
	v_mul_f32_e32 v91, v90, v143
	v_fma_f32 v127, -v126, v91, v90
	v_fmac_f32_e32 v91, v127, v143
	v_fma_f32 v90, -v126, v91, v90
	v_div_fmas_f32 v90, v90, v143, v91
	v_div_fixup_f32 v89, v90, v89, 1.0
	v_and_b32_sdwa v90, v87, v142 dst_sel:DWORD dst_unused:UNUSED_PAD src0_sel:WORD_1 src1_sel:DWORD
	v_and_b32_sdwa v91, v86, v142 dst_sel:DWORD dst_unused:UNUSED_PAD src0_sel:WORD_1 src1_sel:DWORD
	v_add3_u32 v86, v86, v91, s3
	v_add3_u32 v87, v87, v90, s3
	v_and_b32_sdwa v90, v89, v142 dst_sel:DWORD dst_unused:UNUSED_PAD src0_sel:WORD_1 src1_sel:DWORD
	v_and_b32_sdwa v91, v88, v142 dst_sel:DWORD dst_unused:UNUSED_PAD src0_sel:WORD_1 src1_sel:DWORD
	v_add3_u32 v89, v89, v90, s3
	v_add3_u32 v88, v88, v91, s3
	v_and_b32_e32 v89, 0xffff0000, v89
	v_and_b32_e32 v88, 0xffff0000, v88
	v_or_b32_sdwa v87, v89, v87 dst_sel:DWORD dst_unused:UNUSED_PAD src0_sel:DWORD src1_sel:WORD_1
	v_or_b32_sdwa v86, v88, v86 dst_sel:DWORD dst_unused:UNUSED_PAD src0_sel:DWORD src1_sel:WORD_1
	global_store_dwordx4 v[98:99], v[84:87], off offset:128
	v_mul_f32_e32 v41, 0xbfb8aa3b, v41
	v_add_f32_e32 v43, v43, v19
	v_exp_f32_e32 v84, v61
	v_add_f32_e32 v61, v62, v22
	v_mul_f32_e32 v61, 0xbfb8aa3b, v61
	v_exp_f32_e32 v61, v61
	v_add_f32_e32 v62, v63, v23
	v_mul_f32_e32 v62, 0xbfb8aa3b, v62
	v_exp_f32_e32 v85, v62
	v_pk_add_f32 v[60:61], v[60:61], 1.0 op_sel_hi:[1,0]
	v_exp_f32_e32 v62, v57
	v_add_f32_e32 v57, v58, v18
	v_div_scale_f32 v58, s[76:77], v60, v60, 1.0
	v_rcp_f32_e32 v86, v58
	v_exp_f32_e32 v63, v59
	v_mul_f32_e32 v57, 0xbfb8aa3b, v57
	v_exp_f32_e32 v57, v57
	v_fma_f32 v59, -v58, v86, 1.0
	v_fmac_f32_e32 v86, v59, v86
	v_div_scale_f32 v59, vcc, 1.0, v60, 1.0
	v_mul_f32_e32 v87, v59, v86
	v_fma_f32 v88, -v58, v87, v59
	v_fmac_f32_e32 v87, v88, v86
	v_fma_f32 v58, -v58, v87, v59
	v_div_scale_f32 v59, s[76:77], v61, v61, 1.0
	v_rcp_f32_e32 v88, v59
	v_div_fmas_f32 v58, v58, v86, v87
	v_div_fixup_f32 v60, v58, v60, 1.0
	v_mul_f32_e32 v43, 0xbfb8aa3b, v43
	v_fma_f32 v58, -v59, v88, 1.0
	v_fmac_f32_e32 v88, v58, v88
	v_div_scale_f32 v58, vcc, 1.0, v61, 1.0
	v_mul_f32_e32 v86, v58, v88
	v_fma_f32 v87, -v59, v86, v58
	v_fmac_f32_e32 v86, v87, v88
	v_fma_f32 v87, -v59, v86, v58
	v_pk_add_f32 v[58:59], v[84:85], 1.0 op_sel_hi:[1,0]
	v_div_fmas_f32 v86, v87, v88, v86
	v_div_scale_f32 v84, s[76:77], v58, v58, 1.0
	v_rcp_f32_e32 v85, v84
	v_div_fixup_f32 v61, v86, v61, 1.0
	v_add_f32_e32 v40, v40, v16
	v_mul_f32_e32 v40, 0xbfb8aa3b, v40
	v_fma_f32 v86, -v84, v85, 1.0
	v_fmac_f32_e32 v85, v86, v85
	v_div_scale_f32 v86, vcc, 1.0, v58, 1.0
	v_mul_f32_e32 v87, v86, v85
	v_fma_f32 v88, -v84, v87, v86
	v_fmac_f32_e32 v87, v88, v85
	v_fma_f32 v84, -v84, v87, v86
	v_div_scale_f32 v86, s[76:77], v59, v59, 1.0
	v_rcp_f32_e32 v88, v86
	v_div_fmas_f32 v84, v84, v85, v87
	v_div_fixup_f32 v58, v84, v58, 1.0
	v_exp_f32_e32 v40, v40
	v_fma_f32 v84, -v86, v88, 1.0
	v_fmac_f32_e32 v88, v84, v88
	v_div_scale_f32 v84, vcc, 1.0, v59, 1.0
	v_mul_f32_e32 v85, v84, v88
	v_fma_f32 v87, -v86, v85, v84
	v_fmac_f32_e32 v85, v87, v88
	v_fma_f32 v84, -v86, v85, v84
	v_div_fmas_f32 v84, v84, v88, v85
	v_div_fixup_f32 v59, v84, v59, 1.0
	v_and_b32_sdwa v84, v61, v142 dst_sel:DWORD dst_unused:UNUSED_PAD src0_sel:WORD_1 src1_sel:DWORD
	v_and_b32_sdwa v85, v60, v142 dst_sel:DWORD dst_unused:UNUSED_PAD src0_sel:WORD_1 src1_sel:DWORD
	v_add3_u32 v61, v61, v84, s3
	v_and_b32_sdwa v84, v59, v142 dst_sel:DWORD dst_unused:UNUSED_PAD src0_sel:WORD_1 src1_sel:DWORD
	v_add3_u32 v60, v60, v85, s3
	v_and_b32_sdwa v85, v58, v142 dst_sel:DWORD dst_unused:UNUSED_PAD src0_sel:WORD_1 src1_sel:DWORD
	v_add3_u32 v59, v59, v84, s3
	v_add3_u32 v84, v58, v85, s3
	v_and_b32_e32 v85, 0xffff0000, v59
	v_pk_add_f32 v[58:59], v[56:57], 1.0 op_sel_hi:[1,0]
	v_and_b32_e32 v56, 0xffff0000, v84
	v_div_scale_f32 v86, s[76:77], v58, v58, 1.0
	v_rcp_f32_e32 v87, v86
	v_or_b32_sdwa v56, v56, v60 dst_sel:DWORD dst_unused:UNUSED_PAD src0_sel:DWORD src1_sel:WORD_1
	v_or_b32_sdwa v57, v85, v61 dst_sel:DWORD dst_unused:UNUSED_PAD src0_sel:DWORD src1_sel:WORD_1
	v_add_f32_e32 v37, v37, v5
	v_fma_f32 v60, -v86, v87, 1.0
	v_fmac_f32_e32 v87, v60, v87
	v_div_scale_f32 v60, vcc, 1.0, v58, 1.0
	v_mul_f32_e32 v61, v60, v87
	v_fma_f32 v84, -v86, v61, v60
	v_fmac_f32_e32 v61, v84, v87
	v_div_scale_f32 v84, s[76:77], v59, v59, 1.0
	v_rcp_f32_e32 v85, v84
	v_fma_f32 v60, -v86, v61, v60
	v_div_fmas_f32 v60, v60, v87, v61
	v_div_fixup_f32 v58, v60, v58, 1.0
	v_fma_f32 v60, -v84, v85, 1.0
	v_fmac_f32_e32 v85, v60, v85
	v_div_scale_f32 v60, vcc, 1.0, v59, 1.0
	v_mul_f32_e32 v86, v60, v85
	v_fma_f32 v61, -v84, v86, v60
	v_fmac_f32_e32 v86, v61, v85
	v_fma_f32 v84, -v84, v86, v60
	v_pk_add_f32 v[60:61], v[62:63], 1.0 op_sel_hi:[1,0]
	v_div_fmas_f32 v84, v84, v85, v86
	v_div_scale_f32 v62, s[76:77], v60, v60, 1.0
	v_rcp_f32_e32 v63, v62
	v_div_fixup_f32 v59, v84, v59, 1.0
	v_mul_f32_e32 v37, 0xbfb8aa3b, v37
	v_add_f32_e32 v36, v36, v4
	v_fma_f32 v84, -v62, v63, 1.0
	v_fmac_f32_e32 v63, v84, v63
	v_div_scale_f32 v84, vcc, 1.0, v60, 1.0
	v_mul_f32_e32 v85, v84, v63
	v_fma_f32 v86, -v62, v85, v84
	v_fmac_f32_e32 v85, v86, v63
	v_fma_f32 v62, -v62, v85, v84
	v_div_scale_f32 v84, s[76:77], v61, v61, 1.0
	v_rcp_f32_e32 v86, v84
	v_div_fmas_f32 v62, v62, v63, v85
	v_div_fixup_f32 v60, v62, v60, 1.0
	v_mul_f32_e32 v36, 0xbfb8aa3b, v36
	v_fma_f32 v62, -v84, v86, 1.0
	v_fmac_f32_e32 v86, v62, v86
	v_div_scale_f32 v62, vcc, 1.0, v61, 1.0
	v_mul_f32_e32 v63, v62, v86
	v_fma_f32 v85, -v84, v63, v62
	v_fmac_f32_e32 v63, v85, v86
	v_fma_f32 v62, -v84, v63, v62
	v_div_fmas_f32 v62, v62, v86, v63
	v_div_fixup_f32 v61, v62, v61, 1.0
	v_and_b32_sdwa v62, v59, v142 dst_sel:DWORD dst_unused:UNUSED_PAD src0_sel:WORD_1 src1_sel:DWORD
	v_and_b32_sdwa v63, v58, v142 dst_sel:DWORD dst_unused:UNUSED_PAD src0_sel:WORD_1 src1_sel:DWORD
	v_add3_u32 v58, v58, v63, s3
	v_add3_u32 v59, v59, v62, s3
	v_and_b32_sdwa v62, v61, v142 dst_sel:DWORD dst_unused:UNUSED_PAD src0_sel:WORD_1 src1_sel:DWORD
	v_and_b32_sdwa v63, v60, v142 dst_sel:DWORD dst_unused:UNUSED_PAD src0_sel:WORD_1 src1_sel:DWORD
	v_add3_u32 v61, v61, v62, s3
	v_add3_u32 v60, v60, v63, s3
	v_and_b32_e32 v61, 0xffff0000, v61
	v_and_b32_e32 v60, 0xffff0000, v60
	v_or_b32_sdwa v59, v61, v59 dst_sel:DWORD dst_unused:UNUSED_PAD src0_sel:DWORD src1_sel:WORD_1
	v_or_b32_sdwa v58, v60, v58 dst_sel:DWORD dst_unused:UNUSED_PAD src0_sel:DWORD src1_sel:WORD_1
	global_store_dwordx4 v[98:99], v[56:59], off offset:256
	v_exp_f32_e32 v36, v36
	v_add_f32_e32 v33, v33, v1
	v_exp_f32_e32 v56, v53
	v_add_f32_e32 v53, v54, v6
	v_mul_f32_e32 v53, 0xbfb8aa3b, v53
	v_exp_f32_e32 v53, v53
	v_add_f32_e32 v54, v55, v7
	v_mul_f32_e32 v54, 0xbfb8aa3b, v54
	v_exp_f32_e32 v57, v54
	v_pk_add_f32 v[52:53], v[52:53], 1.0 op_sel_hi:[1,0]
	v_exp_f32_e32 v54, v49
	v_add_f32_e32 v49, v50, v2
	v_div_scale_f32 v50, s[76:77], v52, v52, 1.0
	v_rcp_f32_e32 v58, v50
	v_exp_f32_e32 v55, v51
	v_mul_f32_e32 v49, 0xbfb8aa3b, v49
	v_exp_f32_e32 v49, v49
	v_fma_f32 v51, -v50, v58, 1.0
	v_fmac_f32_e32 v58, v51, v58
	v_div_scale_f32 v51, vcc, 1.0, v52, 1.0
	v_mul_f32_e32 v59, v51, v58
	v_fma_f32 v60, -v50, v59, v51
	v_fmac_f32_e32 v59, v60, v58
	v_fma_f32 v50, -v50, v59, v51
	v_div_scale_f32 v51, s[76:77], v53, v53, 1.0
	v_rcp_f32_e32 v60, v51
	v_div_fmas_f32 v50, v50, v58, v59
	v_div_fixup_f32 v52, v50, v52, 1.0
	v_mul_f32_e32 v33, 0xbfb8aa3b, v33
	v_fma_f32 v50, -v51, v60, 1.0
	v_fmac_f32_e32 v60, v50, v60
	v_div_scale_f32 v50, vcc, 1.0, v53, 1.0
	v_mul_f32_e32 v58, v50, v60
	v_fma_f32 v59, -v51, v58, v50
	v_fmac_f32_e32 v58, v59, v60
	v_fma_f32 v59, -v51, v58, v50
	v_pk_add_f32 v[50:51], v[56:57], 1.0 op_sel_hi:[1,0]
	v_div_fmas_f32 v58, v59, v60, v58
	v_div_scale_f32 v56, s[76:77], v50, v50, 1.0
	v_rcp_f32_e32 v57, v56
	v_div_fixup_f32 v53, v58, v53, 1.0
	v_add_f32_e32 v35, v35, v3
	v_mul_f32_e32 v35, 0xbfb8aa3b, v35
	v_fma_f32 v58, -v56, v57, 1.0
	v_fmac_f32_e32 v57, v58, v57
	v_div_scale_f32 v58, vcc, 1.0, v50, 1.0
	v_mul_f32_e32 v59, v58, v57
	v_fma_f32 v60, -v56, v59, v58
	v_fmac_f32_e32 v59, v60, v57
	v_fma_f32 v56, -v56, v59, v58
	v_div_scale_f32 v58, s[76:77], v51, v51, 1.0
	v_rcp_f32_e32 v60, v58
	v_div_fmas_f32 v56, v56, v57, v59
	v_div_fixup_f32 v50, v56, v50, 1.0
	v_add_f32_e32 v32, v32, v0
	v_fma_f32 v56, -v58, v60, 1.0
	v_fmac_f32_e32 v60, v56, v60
	v_div_scale_f32 v56, vcc, 1.0, v51, 1.0
	v_mul_f32_e32 v57, v56, v60
	v_fma_f32 v59, -v58, v57, v56
	v_fmac_f32_e32 v57, v59, v60
	v_fma_f32 v56, -v58, v57, v56
	v_div_fmas_f32 v56, v56, v60, v57
	v_div_fixup_f32 v51, v56, v51, 1.0
	v_and_b32_sdwa v56, v53, v142 dst_sel:DWORD dst_unused:UNUSED_PAD src0_sel:WORD_1 src1_sel:DWORD
	v_and_b32_sdwa v57, v52, v142 dst_sel:DWORD dst_unused:UNUSED_PAD src0_sel:WORD_1 src1_sel:DWORD
	v_add3_u32 v53, v53, v56, s3
	v_and_b32_sdwa v56, v51, v142 dst_sel:DWORD dst_unused:UNUSED_PAD src0_sel:WORD_1 src1_sel:DWORD
	v_add3_u32 v52, v52, v57, s3
	v_and_b32_sdwa v57, v50, v142 dst_sel:DWORD dst_unused:UNUSED_PAD src0_sel:WORD_1 src1_sel:DWORD
	v_add3_u32 v51, v51, v56, s3
	v_add3_u32 v56, v50, v57, s3
	v_and_b32_e32 v57, 0xffff0000, v51
	v_pk_add_f32 v[50:51], v[48:49], 1.0 op_sel_hi:[1,0]
	v_and_b32_e32 v48, 0xffff0000, v56
	v_div_scale_f32 v58, s[76:77], v50, v50, 1.0
	v_rcp_f32_e32 v59, v58
	v_or_b32_sdwa v48, v48, v52 dst_sel:DWORD dst_unused:UNUSED_PAD src0_sel:DWORD src1_sel:WORD_1
	v_or_b32_sdwa v49, v57, v53 dst_sel:DWORD dst_unused:UNUSED_PAD src0_sel:DWORD src1_sel:WORD_1
	v_mul_f32_e32 v32, 0xbfb8aa3b, v32
	v_fma_f32 v52, -v58, v59, 1.0
	v_fmac_f32_e32 v59, v52, v59
	v_div_scale_f32 v52, vcc, 1.0, v50, 1.0
	v_mul_f32_e32 v53, v52, v59
	v_fma_f32 v56, -v58, v53, v52
	v_fmac_f32_e32 v53, v56, v59
	v_div_scale_f32 v56, s[76:77], v51, v51, 1.0
	v_rcp_f32_e32 v57, v56
	v_fma_f32 v52, -v58, v53, v52
	v_div_fmas_f32 v52, v52, v59, v53
	v_div_fixup_f32 v50, v52, v50, 1.0
	v_fma_f32 v52, -v56, v57, 1.0
	v_fmac_f32_e32 v57, v52, v57
	v_div_scale_f32 v52, vcc, 1.0, v51, 1.0
	v_mul_f32_e32 v58, v52, v57
	v_fma_f32 v53, -v56, v58, v52
	v_fmac_f32_e32 v58, v53, v57
	v_fma_f32 v56, -v56, v58, v52
	v_pk_add_f32 v[52:53], v[54:55], 1.0 op_sel_hi:[1,0]
	v_div_fmas_f32 v56, v56, v57, v58
	v_div_scale_f32 v54, s[76:77], v52, v52, 1.0
	v_rcp_f32_e32 v55, v54
	v_div_fixup_f32 v51, v56, v51, 1.0
	v_exp_f32_e32 v32, v32
	v_add_f32_e32 v21, v29, v21
	v_fma_f32 v56, -v54, v55, 1.0
	v_fmac_f32_e32 v55, v56, v55
	v_div_scale_f32 v56, vcc, 1.0, v52, 1.0
	v_mul_f32_e32 v57, v56, v55
	v_fma_f32 v58, -v54, v57, v56
	v_fmac_f32_e32 v57, v58, v55
	v_fma_f32 v54, -v54, v57, v56
	v_div_scale_f32 v56, s[76:77], v53, v53, 1.0
	v_rcp_f32_e32 v58, v56
	v_div_fmas_f32 v54, v54, v55, v57
	v_div_fixup_f32 v52, v54, v52, 1.0
	v_mul_f32_e32 v21, 0xbfb8aa3b, v21
	v_fma_f32 v54, -v56, v58, 1.0
	v_fmac_f32_e32 v58, v54, v58
	v_div_scale_f32 v54, vcc, 1.0, v53, 1.0
	v_mul_f32_e32 v55, v54, v58
	v_fma_f32 v57, -v56, v55, v54
	v_fmac_f32_e32 v55, v57, v58
	v_fma_f32 v54, -v56, v55, v54
	v_div_fmas_f32 v54, v54, v58, v55
	v_div_fixup_f32 v53, v54, v53, 1.0
	v_and_b32_sdwa v54, v51, v142 dst_sel:DWORD dst_unused:UNUSED_PAD src0_sel:WORD_1 src1_sel:DWORD
	v_and_b32_sdwa v55, v50, v142 dst_sel:DWORD dst_unused:UNUSED_PAD src0_sel:WORD_1 src1_sel:DWORD
	v_add3_u32 v50, v50, v55, s3
	v_add3_u32 v51, v51, v54, s3
	v_and_b32_sdwa v54, v53, v142 dst_sel:DWORD dst_unused:UNUSED_PAD src0_sel:WORD_1 src1_sel:DWORD
	v_and_b32_sdwa v55, v52, v142 dst_sel:DWORD dst_unused:UNUSED_PAD src0_sel:WORD_1 src1_sel:DWORD
	v_add3_u32 v53, v53, v54, s3
	v_add3_u32 v52, v52, v55, s3
	v_and_b32_e32 v53, 0xffff0000, v53
	v_and_b32_e32 v52, 0xffff0000, v52
	v_or_b32_sdwa v51, v53, v51 dst_sel:DWORD dst_unused:UNUSED_PAD src0_sel:DWORD src1_sel:WORD_1
	v_or_b32_sdwa v50, v52, v50 dst_sel:DWORD dst_unused:UNUSED_PAD src0_sel:DWORD src1_sel:WORD_1
	global_store_dwordx4 v[98:99], v[48:51], off offset:384
	v_add_f32_e32 v20, v28, v20
	v_exp_f32_e32 v28, v21
	v_exp_f32_e32 v48, v45
	v_add_f32_e32 v45, v46, v22
	v_mul_f32_e32 v45, 0xbfb8aa3b, v45
	v_exp_f32_e32 v45, v45
	v_add_f32_e32 v46, v47, v23
	v_mul_f32_e32 v46, 0xbfb8aa3b, v46
	v_exp_f32_e32 v49, v46
	v_pk_add_f32 v[44:45], v[44:45], 1.0 op_sel_hi:[1,0]
	v_exp_f32_e32 v46, v41
	v_add_f32_e32 v41, v42, v18
	v_div_scale_f32 v42, s[76:77], v44, v44, 1.0
	v_rcp_f32_e32 v50, v42
	v_exp_f32_e32 v47, v43
	v_mul_f32_e32 v41, 0xbfb8aa3b, v41
	v_exp_f32_e32 v41, v41
	v_fma_f32 v43, -v42, v50, 1.0
	v_fmac_f32_e32 v50, v43, v50
	v_div_scale_f32 v43, vcc, 1.0, v44, 1.0
	v_mul_f32_e32 v51, v43, v50
	v_fma_f32 v52, -v42, v51, v43
	v_fmac_f32_e32 v51, v52, v50
	v_fma_f32 v42, -v42, v51, v43
	v_div_scale_f32 v43, s[76:77], v45, v45, 1.0
	v_rcp_f32_e32 v52, v43
	v_div_fmas_f32 v42, v42, v50, v51
	v_div_fixup_f32 v44, v42, v44, 1.0
	v_add_f32_e32 v21, v30, v22
	v_fma_f32 v42, -v43, v52, 1.0
	v_fmac_f32_e32 v52, v42, v52
	v_div_scale_f32 v42, vcc, 1.0, v45, 1.0
	v_mul_f32_e32 v50, v42, v52
	v_fma_f32 v51, -v43, v50, v42
	v_fmac_f32_e32 v50, v51, v52
	v_fma_f32 v51, -v43, v50, v42
	v_pk_add_f32 v[42:43], v[48:49], 1.0 op_sel_hi:[1,0]
	v_div_fmas_f32 v50, v51, v52, v50
	v_div_scale_f32 v48, s[76:77], v42, v42, 1.0
	v_rcp_f32_e32 v49, v48
	v_div_fixup_f32 v45, v50, v45, 1.0
	v_mul_f32_e32 v20, 0xbfb8aa3b, v20
	v_mul_f32_e32 v21, 0xbfb8aa3b, v21
	v_fma_f32 v50, -v48, v49, 1.0
	v_fmac_f32_e32 v49, v50, v49
	v_div_scale_f32 v50, vcc, 1.0, v42, 1.0
	v_mul_f32_e32 v51, v50, v49
	v_fma_f32 v52, -v48, v51, v50
	v_fmac_f32_e32 v51, v52, v49
	v_fma_f32 v48, -v48, v51, v50
	v_div_scale_f32 v50, s[76:77], v43, v43, 1.0
	v_rcp_f32_e32 v52, v50
	v_div_fmas_f32 v48, v48, v49, v51
	v_div_fixup_f32 v42, v48, v42, 1.0
	v_exp_f32_e32 v20, v20
	v_fma_f32 v48, -v50, v52, 1.0
	v_fmac_f32_e32 v52, v48, v52
	v_div_scale_f32 v48, vcc, 1.0, v43, 1.0
	v_mul_f32_e32 v49, v48, v52
	v_fma_f32 v51, -v50, v49, v48
	v_fmac_f32_e32 v49, v51, v52
	v_fma_f32 v48, -v50, v49, v48
	v_div_fmas_f32 v48, v48, v52, v49
	v_div_fixup_f32 v43, v48, v43, 1.0
	v_and_b32_sdwa v48, v45, v142 dst_sel:DWORD dst_unused:UNUSED_PAD src0_sel:WORD_1 src1_sel:DWORD
	v_and_b32_sdwa v49, v44, v142 dst_sel:DWORD dst_unused:UNUSED_PAD src0_sel:WORD_1 src1_sel:DWORD
	v_add3_u32 v45, v45, v48, s3
	v_and_b32_sdwa v48, v43, v142 dst_sel:DWORD dst_unused:UNUSED_PAD src0_sel:WORD_1 src1_sel:DWORD
	v_add3_u32 v44, v44, v49, s3
	v_and_b32_sdwa v49, v42, v142 dst_sel:DWORD dst_unused:UNUSED_PAD src0_sel:WORD_1 src1_sel:DWORD
	v_add3_u32 v43, v43, v48, s3
	v_add3_u32 v48, v42, v49, s3
	v_and_b32_e32 v49, 0xffff0000, v43
	v_pk_add_f32 v[42:43], v[40:41], 1.0 op_sel_hi:[1,0]
	v_and_b32_e32 v40, 0xffff0000, v48
	v_div_scale_f32 v50, s[76:77], v42, v42, 1.0
	v_rcp_f32_e32 v51, v50
	v_or_b32_sdwa v40, v40, v44 dst_sel:DWORD dst_unused:UNUSED_PAD src0_sel:DWORD src1_sel:WORD_1
	v_or_b32_sdwa v41, v49, v45 dst_sel:DWORD dst_unused:UNUSED_PAD src0_sel:DWORD src1_sel:WORD_1
	v_exp_f32_e32 v21, v21
	v_fma_f32 v44, -v50, v51, 1.0
	v_fmac_f32_e32 v51, v44, v51
	v_div_scale_f32 v44, vcc, 1.0, v42, 1.0
	v_mul_f32_e32 v45, v44, v51
	v_fma_f32 v48, -v50, v45, v44
	v_fmac_f32_e32 v45, v48, v51
	v_div_scale_f32 v48, s[76:77], v43, v43, 1.0
	v_rcp_f32_e32 v49, v48
	v_fma_f32 v44, -v50, v45, v44
	v_div_fmas_f32 v44, v44, v51, v45
	v_div_fixup_f32 v42, v44, v42, 1.0
	v_fma_f32 v44, -v48, v49, 1.0
	v_fmac_f32_e32 v49, v44, v49
	v_div_scale_f32 v44, vcc, 1.0, v43, 1.0
	v_mul_f32_e32 v50, v44, v49
	v_fma_f32 v45, -v48, v50, v44
	v_fmac_f32_e32 v50, v45, v49
	v_fma_f32 v48, -v48, v50, v44
	v_pk_add_f32 v[44:45], v[46:47], 1.0 op_sel_hi:[1,0]
	v_div_fmas_f32 v48, v48, v49, v50
	v_div_scale_f32 v46, s[76:77], v44, v44, 1.0
	v_rcp_f32_e32 v47, v46
	v_div_fixup_f32 v43, v48, v43, 1.0
	v_add_f32_e32 v22, v31, v23
	v_add_f32_e32 v17, v25, v17
	v_fma_f32 v48, -v46, v47, 1.0
	v_fmac_f32_e32 v47, v48, v47
	v_div_scale_f32 v48, vcc, 1.0, v44, 1.0
	v_mul_f32_e32 v49, v48, v47
	v_fma_f32 v50, -v46, v49, v48
	v_fmac_f32_e32 v49, v50, v47
	v_fma_f32 v46, -v46, v49, v48
	v_div_scale_f32 v48, s[76:77], v45, v45, 1.0
	v_rcp_f32_e32 v50, v48
	v_div_fmas_f32 v46, v46, v47, v49
	v_div_fixup_f32 v44, v46, v44, 1.0
	v_mul_f32_e32 v22, 0xbfb8aa3b, v22
	v_fma_f32 v46, -v48, v50, 1.0
	v_fmac_f32_e32 v50, v46, v50
	v_div_scale_f32 v46, vcc, 1.0, v45, 1.0
	v_mul_f32_e32 v47, v46, v50
	v_fma_f32 v49, -v48, v47, v46
	v_fmac_f32_e32 v47, v49, v50
	v_fma_f32 v46, -v48, v47, v46
	v_div_fmas_f32 v46, v46, v50, v47
	v_div_fixup_f32 v45, v46, v45, 1.0
	v_and_b32_sdwa v46, v43, v142 dst_sel:DWORD dst_unused:UNUSED_PAD src0_sel:WORD_1 src1_sel:DWORD
	v_and_b32_sdwa v47, v42, v142 dst_sel:DWORD dst_unused:UNUSED_PAD src0_sel:WORD_1 src1_sel:DWORD
	v_add3_u32 v42, v42, v47, s3
	v_add3_u32 v43, v43, v46, s3
	v_and_b32_sdwa v46, v45, v142 dst_sel:DWORD dst_unused:UNUSED_PAD src0_sel:WORD_1 src1_sel:DWORD
	v_and_b32_sdwa v47, v44, v142 dst_sel:DWORD dst_unused:UNUSED_PAD src0_sel:WORD_1 src1_sel:DWORD
	v_add3_u32 v45, v45, v46, s3
	v_add3_u32 v44, v44, v47, s3
	v_and_b32_e32 v45, 0xffff0000, v45
	v_and_b32_e32 v44, 0xffff0000, v44
	v_or_b32_sdwa v43, v45, v43 dst_sel:DWORD dst_unused:UNUSED_PAD src0_sel:DWORD src1_sel:WORD_1
	v_or_b32_sdwa v42, v44, v42 dst_sel:DWORD dst_unused:UNUSED_PAD src0_sel:DWORD src1_sel:WORD_1
	global_store_dwordx4 v[98:99], v[40:43], off offset:512
	v_mul_f32_e32 v17, 0xbfb8aa3b, v17
	v_pk_add_f32 v[20:21], v[20:21], 1.0 op_sel_hi:[1,0]
	v_exp_f32_e32 v40, v37
	v_add_f32_e32 v37, v38, v6
	v_mul_f32_e32 v37, 0xbfb8aa3b, v37
	v_exp_f32_e32 v37, v37
	v_add_f32_e32 v38, v39, v7
	v_mul_f32_e32 v38, 0xbfb8aa3b, v38
	v_exp_f32_e32 v41, v38
	v_pk_add_f32 v[36:37], v[36:37], 1.0 op_sel_hi:[1,0]
	v_exp_f32_e32 v38, v33
	v_add_f32_e32 v33, v34, v2
	v_div_scale_f32 v34, s[76:77], v36, v36, 1.0
	v_rcp_f32_e32 v42, v34
	v_exp_f32_e32 v39, v35
	v_mul_f32_e32 v33, 0xbfb8aa3b, v33
	v_exp_f32_e32 v33, v33
	v_fma_f32 v35, -v34, v42, 1.0
	v_fmac_f32_e32 v42, v35, v42
	v_div_scale_f32 v35, vcc, 1.0, v36, 1.0
	v_mul_f32_e32 v43, v35, v42
	v_fma_f32 v44, -v34, v43, v35
	v_fmac_f32_e32 v43, v44, v42
	v_fma_f32 v34, -v34, v43, v35
	v_div_scale_f32 v35, s[76:77], v37, v37, 1.0
	v_rcp_f32_e32 v44, v35
	v_div_fmas_f32 v34, v34, v42, v43
	v_div_fixup_f32 v36, v34, v36, 1.0
	v_exp_f32_e32 v29, v22
	v_fma_f32 v34, -v35, v44, 1.0
	v_fmac_f32_e32 v44, v34, v44
	v_div_scale_f32 v34, vcc, 1.0, v37, 1.0
	v_mul_f32_e32 v42, v34, v44
	v_fma_f32 v43, -v35, v42, v34
	v_fmac_f32_e32 v42, v43, v44
	v_fma_f32 v43, -v35, v42, v34
	v_pk_add_f32 v[34:35], v[40:41], 1.0 op_sel_hi:[1,0]
	v_div_fmas_f32 v42, v43, v44, v42
	v_div_scale_f32 v40, s[76:77], v34, v34, 1.0
	v_rcp_f32_e32 v41, v40
	v_div_fixup_f32 v37, v42, v37, 1.0
	v_exp_f32_e32 v22, v17
	v_add_f32_e32 v17, v26, v18
	v_fma_f32 v42, -v40, v41, 1.0
	v_fmac_f32_e32 v41, v42, v41
	v_div_scale_f32 v42, vcc, 1.0, v34, 1.0
	v_mul_f32_e32 v43, v42, v41
	v_fma_f32 v44, -v40, v43, v42
	v_fmac_f32_e32 v43, v44, v41
	v_fma_f32 v40, -v40, v43, v42
	v_div_scale_f32 v42, s[76:77], v35, v35, 1.0
	v_rcp_f32_e32 v44, v42
	v_div_fmas_f32 v40, v40, v41, v43
	v_div_fixup_f32 v34, v40, v34, 1.0
	v_div_scale_f32 v18, s[76:77], v20, v20, 1.0
	v_fma_f32 v40, -v42, v44, 1.0
	v_fmac_f32_e32 v44, v40, v44
	v_div_scale_f32 v40, vcc, 1.0, v35, 1.0
	v_mul_f32_e32 v41, v40, v44
	v_fma_f32 v43, -v42, v41, v40
	v_fmac_f32_e32 v41, v43, v44
	v_fma_f32 v40, -v42, v41, v40
	v_div_fmas_f32 v40, v40, v44, v41
	v_div_fixup_f32 v35, v40, v35, 1.0
	v_and_b32_sdwa v40, v37, v142 dst_sel:DWORD dst_unused:UNUSED_PAD src0_sel:WORD_1 src1_sel:DWORD
	v_and_b32_sdwa v41, v36, v142 dst_sel:DWORD dst_unused:UNUSED_PAD src0_sel:WORD_1 src1_sel:DWORD
	v_add3_u32 v37, v37, v40, s3
	v_and_b32_sdwa v40, v35, v142 dst_sel:DWORD dst_unused:UNUSED_PAD src0_sel:WORD_1 src1_sel:DWORD
	v_add3_u32 v36, v36, v41, s3
	v_and_b32_sdwa v41, v34, v142 dst_sel:DWORD dst_unused:UNUSED_PAD src0_sel:WORD_1 src1_sel:DWORD
	v_add3_u32 v35, v35, v40, s3
	v_add3_u32 v40, v34, v41, s3
	v_and_b32_e32 v41, 0xffff0000, v35
	v_pk_add_f32 v[34:35], v[32:33], 1.0 op_sel_hi:[1,0]
	v_and_b32_e32 v32, 0xffff0000, v40
	v_div_scale_f32 v42, s[76:77], v34, v34, 1.0
	v_rcp_f32_e32 v43, v42
	v_or_b32_sdwa v32, v32, v36 dst_sel:DWORD dst_unused:UNUSED_PAD src0_sel:DWORD src1_sel:WORD_1
	v_or_b32_sdwa v33, v41, v37 dst_sel:DWORD dst_unused:UNUSED_PAD src0_sel:DWORD src1_sel:WORD_1
	v_add_f32_e32 v16, v24, v16
	v_fma_f32 v36, -v42, v43, 1.0
	v_fmac_f32_e32 v43, v36, v43
	v_div_scale_f32 v36, vcc, 1.0, v34, 1.0
	v_mul_f32_e32 v37, v36, v43
	v_fma_f32 v40, -v42, v37, v36
	v_fmac_f32_e32 v37, v40, v43
	v_div_scale_f32 v40, s[76:77], v35, v35, 1.0
	v_rcp_f32_e32 v41, v40
	v_fma_f32 v36, -v42, v37, v36
	v_div_fmas_f32 v36, v36, v43, v37
	v_div_fixup_f32 v34, v36, v34, 1.0
	v_fma_f32 v36, -v40, v41, 1.0
	v_fmac_f32_e32 v41, v36, v41
	v_div_scale_f32 v36, vcc, 1.0, v35, 1.0
	v_mul_f32_e32 v42, v36, v41
	v_fma_f32 v37, -v40, v42, v36
	v_fmac_f32_e32 v42, v37, v41
	v_fma_f32 v40, -v40, v42, v36
	v_pk_add_f32 v[36:37], v[38:39], 1.0 op_sel_hi:[1,0]
	v_div_fmas_f32 v40, v40, v41, v42
	v_div_scale_f32 v38, s[76:77], v36, v36, 1.0
	v_rcp_f32_e32 v39, v38
	v_div_fixup_f32 v35, v40, v35, 1.0
	v_rcp_f32_e32 v24, v18
	v_add_f32_e32 v19, v27, v19
	v_fma_f32 v40, -v38, v39, 1.0
	v_fmac_f32_e32 v39, v40, v39
	v_div_scale_f32 v40, vcc, 1.0, v36, 1.0
	v_mul_f32_e32 v41, v40, v39
	v_fma_f32 v42, -v38, v41, v40
	v_fmac_f32_e32 v41, v42, v39
	v_fma_f32 v38, -v38, v41, v40
	v_div_scale_f32 v40, s[76:77], v37, v37, 1.0
	v_rcp_f32_e32 v42, v40
	v_div_fmas_f32 v38, v38, v39, v41
	v_div_fixup_f32 v36, v38, v36, 1.0
	v_mul_f32_e32 v19, 0xbfb8aa3b, v19
	v_fma_f32 v38, -v40, v42, 1.0
	v_fmac_f32_e32 v42, v38, v42
	v_div_scale_f32 v38, vcc, 1.0, v37, 1.0
	v_mul_f32_e32 v39, v38, v42
	v_fma_f32 v41, -v40, v39, v38
	v_fmac_f32_e32 v39, v41, v42
	v_fma_f32 v38, -v40, v39, v38
	v_exp_f32_e32 v23, v19
	v_fma_f32 v19, -v18, v24, 1.0
	v_div_fmas_f32 v38, v38, v42, v39
	v_fmac_f32_e32 v24, v19, v24
	v_div_scale_f32 v19, vcc, 1.0, v20, 1.0
	v_mul_f32_e32 v25, v19, v24
	v_fma_f32 v26, -v18, v25, v19
	v_fmac_f32_e32 v25, v26, v24
	v_fma_f32 v18, -v18, v25, v19
	v_div_scale_f32 v19, s[76:77], v21, v21, 1.0
	v_rcp_f32_e32 v26, v19
	v_div_fmas_f32 v18, v18, v24, v25
	v_div_fixup_f32 v20, v18, v20, 1.0
	v_mul_f32_e32 v16, 0xbfb8aa3b, v16
	v_fma_f32 v18, -v19, v26, 1.0
	v_fmac_f32_e32 v26, v18, v26
	v_div_scale_f32 v18, vcc, 1.0, v21, 1.0
	v_mul_f32_e32 v24, v18, v26
	v_fma_f32 v25, -v19, v24, v18
	v_fmac_f32_e32 v24, v25, v26
	v_fma_f32 v25, -v19, v24, v18
	v_pk_add_f32 v[18:19], v[28:29], 1.0 op_sel_hi:[1,0]
	v_div_fmas_f32 v24, v25, v26, v24
	v_div_scale_f32 v27, s[76:77], v18, v18, 1.0
	v_rcp_f32_e32 v28, v27
	v_div_fixup_f32 v21, v24, v21, 1.0
	v_mul_f32_e32 v17, 0xbfb8aa3b, v17
	v_exp_f32_e32 v16, v16
	v_fma_f32 v24, -v27, v28, 1.0
	v_fmac_f32_e32 v28, v24, v28
	v_div_scale_f32 v24, vcc, 1.0, v18, 1.0
	v_mul_f32_e32 v25, v24, v28
	v_fma_f32 v26, -v27, v25, v24
	v_fmac_f32_e32 v25, v26, v28
	v_div_scale_f32 v26, s[76:77], v19, v19, 1.0
	v_fma_f32 v24, -v27, v25, v24
	v_rcp_f32_e32 v27, v26
	v_div_fmas_f32 v24, v24, v28, v25
	v_div_fixup_f32 v18, v24, v18, 1.0
	v_exp_f32_e32 v17, v17
	v_fma_f32 v24, -v26, v27, 1.0
	v_fmac_f32_e32 v27, v24, v27
	v_div_scale_f32 v24, vcc, 1.0, v19, 1.0
	v_mul_f32_e32 v25, v24, v27
	v_fma_f32 v28, -v26, v25, v24
	v_fmac_f32_e32 v25, v28, v27
	v_fma_f32 v24, -v26, v25, v24
	v_div_fmas_f32 v24, v24, v27, v25
	v_div_fixup_f32 v19, v24, v19, 1.0
	v_and_b32_sdwa v24, v21, v142 dst_sel:DWORD dst_unused:UNUSED_PAD src0_sel:WORD_1 src1_sel:DWORD
	v_and_b32_sdwa v25, v20, v142 dst_sel:DWORD dst_unused:UNUSED_PAD src0_sel:WORD_1 src1_sel:DWORD
	v_add3_u32 v21, v21, v24, s3
	v_and_b32_sdwa v24, v19, v142 dst_sel:DWORD dst_unused:UNUSED_PAD src0_sel:WORD_1 src1_sel:DWORD
	v_add3_u32 v20, v20, v25, s3
	v_and_b32_sdwa v25, v18, v142 dst_sel:DWORD dst_unused:UNUSED_PAD src0_sel:WORD_1 src1_sel:DWORD
	v_add3_u32 v19, v19, v24, s3
	v_add3_u32 v24, v18, v25, s3
	v_and_b32_e32 v25, 0xffff0000, v19
	v_pk_add_f32 v[18:19], v[16:17], 1.0 op_sel_hi:[1,0]
	v_and_b32_e32 v16, 0xffff0000, v24
	v_div_scale_f32 v26, s[76:77], v18, v18, 1.0
	v_rcp_f32_e32 v27, v26
	v_or_b32_sdwa v16, v16, v20 dst_sel:DWORD dst_unused:UNUSED_PAD src0_sel:DWORD src1_sel:WORD_1
	v_or_b32_sdwa v17, v25, v21 dst_sel:DWORD dst_unused:UNUSED_PAD src0_sel:DWORD src1_sel:WORD_1
	v_mfma_f32_16x16x32_bf16 v[12:15], v[230:233], v[218:221], v[150:153]
	v_fma_f32 v20, -v26, v27, 1.0
	v_fmac_f32_e32 v27, v20, v27
	v_div_scale_f32 v20, vcc, 1.0, v18, 1.0
	v_mul_f32_e32 v21, v20, v27
	v_fma_f32 v24, -v26, v21, v20
	v_fmac_f32_e32 v21, v24, v27
	v_div_scale_f32 v24, s[76:77], v19, v19, 1.0
	v_rcp_f32_e32 v25, v24
	v_fma_f32 v20, -v26, v21, v20
	v_div_fmas_f32 v20, v20, v27, v21
	v_div_fixup_f32 v18, v20, v18, 1.0
	v_fma_f32 v20, -v24, v25, 1.0
	v_fmac_f32_e32 v25, v20, v25
	v_div_scale_f32 v20, vcc, 1.0, v19, 1.0
	v_mul_f32_e32 v26, v20, v25
	v_fma_f32 v21, -v24, v26, v20
	v_fmac_f32_e32 v26, v21, v25
	v_fma_f32 v24, -v24, v26, v20
	v_pk_add_f32 v[20:21], v[22:23], 1.0 op_sel_hi:[1,0]
	v_div_fmas_f32 v24, v24, v25, v26
	v_div_scale_f32 v22, s[76:77], v20, v20, 1.0
	v_rcp_f32_e32 v23, v22
	v_mfma_f32_16x16x32_bf16 v[8:11], v[202:205], v[186:189], v[8:11]
	v_div_fixup_f32 v19, v24, v19, 1.0
	v_add_f32_e32 v5, v13, v5
	v_fma_f32 v24, -v22, v23, 1.0
	v_fmac_f32_e32 v23, v24, v23
	v_div_scale_f32 v24, vcc, 1.0, v20, 1.0
	v_mul_f32_e32 v25, v24, v23
	v_mul_f32_e32 v5, 0xbfb8aa3b, v5
	v_fma_f32 v26, -v22, v25, v24
	v_add_f32_e32 v4, v12, v4
	v_exp_f32_e32 v12, v5
	v_add_f32_e32 v5, v14, v6
	v_mfma_f32_16x16x32_bf16 v[8:11], v[234:237], v[218:221], v[8:11]
	v_fmac_f32_e32 v25, v26, v23
	v_mul_f32_e32 v4, 0xbfb8aa3b, v4
	v_mul_f32_e32 v5, 0xbfb8aa3b, v5
	v_fma_f32 v22, -v22, v25, v24
	v_div_scale_f32 v24, s[76:77], v21, v21, 1.0
	v_exp_f32_e32 v4, v4
	v_exp_f32_e32 v5, v5
	v_rcp_f32_e32 v26, v24
	v_add_f32_e32 v6, v15, v7
	v_add_f32_e32 v1, v9, v1
	v_div_fmas_f32 v22, v22, v23, v25
	v_mul_f32_e32 v6, 0xbfb8aa3b, v6
	v_mul_f32_e32 v1, 0xbfb8aa3b, v1
	v_pk_add_f32 v[4:5], v[4:5], 1.0 op_sel_hi:[1,0]
	v_div_fixup_f32 v20, v22, v20, 1.0
	v_fma_f32 v22, -v24, v26, 1.0
	v_exp_f32_e32 v13, v6
	v_exp_f32_e32 v6, v1
	v_add_f32_e32 v1, v10, v2
	v_div_scale_f32 v2, s[76:77], v4, v4, 1.0
	v_fmac_f32_e32 v26, v22, v26
	v_div_scale_f32 v22, vcc, 1.0, v21, 1.0
	v_add_f32_e32 v0, v8, v0
	v_rcp_f32_e32 v8, v2
	v_mul_f32_e32 v23, v22, v26
	v_fma_f32 v25, -v24, v23, v22
	v_add_f32_e32 v3, v11, v3
	v_fmac_f32_e32 v23, v25, v26
	v_mul_f32_e32 v3, 0xbfb8aa3b, v3
	v_fma_f32 v22, -v24, v23, v22
	v_exp_f32_e32 v7, v3
	v_fma_f32 v3, -v2, v8, 1.0
	v_div_fmas_f32 v22, v22, v26, v23
	v_fmac_f32_e32 v8, v3, v8
	v_div_scale_f32 v3, vcc, 1.0, v4, 1.0
	v_mul_f32_e32 v9, v3, v8
	v_fma_f32 v10, -v2, v9, v3
	v_fmac_f32_e32 v9, v10, v8
	v_fma_f32 v2, -v2, v9, v3
	v_div_scale_f32 v3, s[76:77], v5, v5, 1.0
	v_rcp_f32_e32 v10, v3
	v_div_fmas_f32 v2, v2, v8, v9
	v_div_fixup_f32 v4, v2, v4, 1.0
	v_mul_f32_e32 v0, 0xbfb8aa3b, v0
	v_fma_f32 v2, -v3, v10, 1.0
	v_fmac_f32_e32 v10, v2, v10
	v_div_scale_f32 v2, vcc, 1.0, v5, 1.0
	v_mul_f32_e32 v8, v2, v10
	v_fma_f32 v9, -v3, v8, v2
	v_fmac_f32_e32 v8, v9, v10
	v_fma_f32 v9, -v3, v8, v2
	v_pk_add_f32 v[2:3], v[12:13], 1.0 op_sel_hi:[1,0]
	v_div_fmas_f32 v8, v9, v10, v8
	v_div_scale_f32 v11, s[76:77], v2, v2, 1.0
	v_rcp_f32_e32 v12, v11
	v_div_fixup_f32 v5, v8, v5, 1.0
	v_mul_f32_e32 v1, 0xbfb8aa3b, v1
	v_exp_f32_e32 v0, v0
	v_fma_f32 v8, -v11, v12, 1.0
	v_fmac_f32_e32 v12, v8, v12
	v_div_scale_f32 v8, vcc, 1.0, v2, 1.0
	v_mul_f32_e32 v9, v8, v12
	v_fma_f32 v10, -v11, v9, v8
	v_fmac_f32_e32 v9, v10, v12
	v_div_scale_f32 v10, s[76:77], v3, v3, 1.0
	v_fma_f32 v8, -v11, v9, v8
	v_rcp_f32_e32 v11, v10
	v_div_fmas_f32 v8, v8, v12, v9
	v_div_fixup_f32 v2, v8, v2, 1.0
	v_exp_f32_e32 v1, v1
	v_fma_f32 v8, -v10, v11, 1.0
	v_fmac_f32_e32 v11, v8, v11
	v_div_scale_f32 v8, vcc, 1.0, v3, 1.0
	v_mul_f32_e32 v9, v8, v11
	v_fma_f32 v12, -v10, v9, v8
	v_fmac_f32_e32 v9, v12, v11
	v_fma_f32 v8, -v10, v9, v8
	v_div_fmas_f32 v8, v8, v11, v9
	v_div_fixup_f32 v3, v8, v3, 1.0
	v_and_b32_sdwa v8, v5, v142 dst_sel:DWORD dst_unused:UNUSED_PAD src0_sel:WORD_1 src1_sel:DWORD
	v_and_b32_sdwa v9, v4, v142 dst_sel:DWORD dst_unused:UNUSED_PAD src0_sel:WORD_1 src1_sel:DWORD
	v_add3_u32 v5, v5, v8, s3
	v_and_b32_sdwa v8, v3, v142 dst_sel:DWORD dst_unused:UNUSED_PAD src0_sel:WORD_1 src1_sel:DWORD
	v_add3_u32 v4, v4, v9, s3
	v_and_b32_sdwa v9, v2, v142 dst_sel:DWORD dst_unused:UNUSED_PAD src0_sel:WORD_1 src1_sel:DWORD
	v_add3_u32 v3, v3, v8, s3
	v_add3_u32 v8, v2, v9, s3
	v_and_b32_e32 v9, 0xffff0000, v3
	v_pk_add_f32 v[2:3], v[0:1], 1.0 op_sel_hi:[1,0]
	v_and_b32_e32 v0, 0xffff0000, v8
	v_div_scale_f32 v10, s[76:77], v2, v2, 1.0
	v_rcp_f32_e32 v11, v10
	v_or_b32_sdwa v0, v0, v4 dst_sel:DWORD dst_unused:UNUSED_PAD src0_sel:DWORD src1_sel:WORD_1
	v_or_b32_sdwa v1, v9, v5 dst_sel:DWORD dst_unused:UNUSED_PAD src0_sel:DWORD src1_sel:WORD_1
	v_div_fixup_f32 v37, v38, v37, 1.0
	v_fma_f32 v4, -v10, v11, 1.0
	v_fmac_f32_e32 v11, v4, v11
	v_div_scale_f32 v4, vcc, 1.0, v2, 1.0
	v_mul_f32_e32 v5, v4, v11
	v_fma_f32 v8, -v10, v5, v4
	v_fmac_f32_e32 v5, v8, v11
	v_div_scale_f32 v8, s[76:77], v3, v3, 1.0
	v_rcp_f32_e32 v9, v8
	v_fma_f32 v4, -v10, v5, v4
	v_div_fmas_f32 v4, v4, v11, v5
	v_div_fixup_f32 v2, v4, v2, 1.0
	v_fma_f32 v4, -v8, v9, 1.0
	v_fmac_f32_e32 v9, v4, v9
	v_div_scale_f32 v4, vcc, 1.0, v3, 1.0
	v_mul_f32_e32 v10, v4, v9
	v_fma_f32 v5, -v8, v10, v4
	v_fmac_f32_e32 v10, v5, v9
	v_fma_f32 v8, -v8, v10, v4
	v_pk_add_f32 v[4:5], v[6:7], 1.0 op_sel_hi:[1,0]
	v_div_fmas_f32 v8, v8, v9, v10
	v_div_scale_f32 v6, s[76:77], v4, v4, 1.0
	v_rcp_f32_e32 v7, v6
	v_div_fixup_f32 v3, v8, v3, 1.0
	v_and_b32_sdwa v38, v35, v142 dst_sel:DWORD dst_unused:UNUSED_PAD src0_sel:WORD_1 src1_sel:DWORD
	v_and_b32_sdwa v39, v34, v142 dst_sel:DWORD dst_unused:UNUSED_PAD src0_sel:WORD_1 src1_sel:DWORD
	v_fma_f32 v8, -v6, v7, 1.0
	v_fmac_f32_e32 v7, v8, v7
	v_div_scale_f32 v8, vcc, 1.0, v4, 1.0
	v_mul_f32_e32 v9, v8, v7
	v_fma_f32 v10, -v6, v9, v8
	v_fmac_f32_e32 v9, v10, v7
	v_fma_f32 v6, -v6, v9, v8
	v_div_scale_f32 v8, s[76:77], v5, v5, 1.0
	v_rcp_f32_e32 v10, v8
	v_div_fmas_f32 v6, v6, v7, v9
	v_div_fixup_f32 v4, v6, v4, 1.0
	v_div_fixup_f32 v21, v22, v21, 1.0
	v_fma_f32 v6, -v8, v10, 1.0
	v_fmac_f32_e32 v10, v6, v10
	v_div_scale_f32 v6, vcc, 1.0, v5, 1.0
	v_mul_f32_e32 v7, v6, v10
	v_fma_f32 v9, -v8, v7, v6
	v_fmac_f32_e32 v7, v9, v10
	v_fma_f32 v6, -v8, v7, v6
	v_div_fmas_f32 v6, v6, v10, v7
	v_and_b32_sdwa v22, v19, v142 dst_sel:DWORD dst_unused:UNUSED_PAD src0_sel:WORD_1 src1_sel:DWORD
	v_and_b32_sdwa v23, v18, v142 dst_sel:DWORD dst_unused:UNUSED_PAD src0_sel:WORD_1 src1_sel:DWORD
	v_div_fixup_f32 v5, v6, v5, 1.0
	v_and_b32_sdwa v6, v3, v142 dst_sel:DWORD dst_unused:UNUSED_PAD src0_sel:WORD_1 src1_sel:DWORD
	v_and_b32_sdwa v7, v2, v142 dst_sel:DWORD dst_unused:UNUSED_PAD src0_sel:WORD_1 src1_sel:DWORD
	v_add3_u32 v34, v34, v39, s3
	v_add3_u32 v35, v35, v38, s3
	v_and_b32_sdwa v38, v37, v142 dst_sel:DWORD dst_unused:UNUSED_PAD src0_sel:WORD_1 src1_sel:DWORD
	v_and_b32_sdwa v39, v36, v142 dst_sel:DWORD dst_unused:UNUSED_PAD src0_sel:WORD_1 src1_sel:DWORD
	v_add3_u32 v18, v18, v23, s3
	v_add3_u32 v19, v19, v22, s3
	v_and_b32_sdwa v22, v21, v142 dst_sel:DWORD dst_unused:UNUSED_PAD src0_sel:WORD_1 src1_sel:DWORD
	v_and_b32_sdwa v23, v20, v142 dst_sel:DWORD dst_unused:UNUSED_PAD src0_sel:WORD_1 src1_sel:DWORD
	v_add3_u32 v2, v2, v7, s3
	v_add3_u32 v3, v3, v6, s3
	v_and_b32_sdwa v6, v5, v142 dst_sel:DWORD dst_unused:UNUSED_PAD src0_sel:WORD_1 src1_sel:DWORD
	v_and_b32_sdwa v7, v4, v142 dst_sel:DWORD dst_unused:UNUSED_PAD src0_sel:WORD_1 src1_sel:DWORD
	v_add3_u32 v37, v37, v38, s3
	v_add3_u32 v36, v36, v39, s3
	v_add3_u32 v21, v21, v22, s3
	v_add3_u32 v20, v20, v23, s3
	v_add3_u32 v5, v5, v6, s3
	v_add3_u32 v4, v4, v7, s3
	v_and_b32_e32 v37, 0xffff0000, v37
	v_and_b32_e32 v36, 0xffff0000, v36
	v_and_b32_e32 v21, 0xffff0000, v21
	v_and_b32_e32 v20, 0xffff0000, v20
	v_and_b32_e32 v5, 0xffff0000, v5
	v_and_b32_e32 v4, 0xffff0000, v4
	v_or_b32_sdwa v35, v37, v35 dst_sel:DWORD dst_unused:UNUSED_PAD src0_sel:DWORD src1_sel:WORD_1
	v_or_b32_sdwa v34, v36, v34 dst_sel:DWORD dst_unused:UNUSED_PAD src0_sel:DWORD src1_sel:WORD_1
	v_or_b32_sdwa v19, v21, v19 dst_sel:DWORD dst_unused:UNUSED_PAD src0_sel:DWORD src1_sel:WORD_1
	v_or_b32_sdwa v18, v20, v18 dst_sel:DWORD dst_unused:UNUSED_PAD src0_sel:DWORD src1_sel:WORD_1
	v_or_b32_sdwa v3, v5, v3 dst_sel:DWORD dst_unused:UNUSED_PAD src0_sel:DWORD src1_sel:WORD_1
	v_or_b32_sdwa v2, v4, v2 dst_sel:DWORD dst_unused:UNUSED_PAD src0_sel:DWORD src1_sel:WORD_1
	v_lshl_add_u64 v[86:87], v[104:105], 0, s[72:73]
	global_store_dwordx4 v[98:99], v[32:35], off offset:640
	global_store_dwordx4 v[98:99], v[16:19], off offset:768
	global_store_dwordx4 v[98:99], v[0:3], off offset:896
	s_barrier
	global_load_lds_dwordx4 v[86:87], off
	v_lshl_add_u64 v[0:1], v[86:87], 0, s[10:11]
	s_mov_b32 m0, s71
	v_readfirstlane_b32 s71, v136
	global_load_lds_dwordx4 v[0:1], off
	v_lshl_add_u64 v[0:1], v[86:87], 0, s[12:13]
	s_mov_b32 m0, s71
	v_readfirstlane_b32 s71, v137
	global_load_lds_dwordx4 v[0:1], off
	v_lshl_add_u64 v[0:1], v[86:87], 0, s[14:15]
	s_mov_b32 m0, s71
	v_readfirstlane_b32 s71, v138
	v_lshl_add_u64 v[84:85], v[112:113], 0, s[74:75]
	global_load_lds_dwordx4 v[0:1], off
	s_mov_b32 m0, s71
	v_readfirstlane_b32 s71, v139
	global_load_lds_dwordx4 v[84:85], off
	v_lshl_add_u64 v[0:1], v[84:85], 0, s[10:11]
	s_mov_b32 m0, s71
	v_readfirstlane_b32 s71, v140
	global_load_lds_dwordx4 v[0:1], off
	v_lshl_add_u64 v[0:1], v[84:85], 0, s[12:13]
	s_mov_b32 m0, s71
	v_readfirstlane_b32 s71, v141
	global_load_lds_dwordx4 v[0:1], off
	v_lshl_add_u64 v[0:1], v[84:85], 0, s[14:15]
	s_mov_b32 m0, s71
	s_and_b64 vcc, exec, s[6:7]
	global_load_lds_dwordx4 v[0:1], off
	s_cbranch_vccnz .LBB0_464
	s_sleep 8

.LBB0_465:
	v_lshl_add_u64 v[126:127], v[90:91], 0, v[96:97]
	v_readfirstlane_b32 s76, v92
	s_waitcnt vmcnt(0) lgkmcnt(0)
	s_barrier
	v_readfirstlane_b32 s77, v93
	v_lshl_add_u64 v[154:155], v[126:127], 0, s[50:51]
	s_mov_b32 m0, s76
	v_readfirstlane_b32 s84, v94
	v_lshl_add_u64 v[158:159], v[126:127], 0, s[56:57]
	ds_read_b128 v[146:149], v131 offset:16384
	ds_read_b128 v[150:153], v131 offset:18432
	global_load_lds_dwordx4 v[154:155], off
	s_mov_b32 m0, s77
	v_readfirstlane_b32 s85, v95
	v_lshl_add_u64 v[160:161], v[126:127], 0, s[58:59]
	global_load_lds_dwordx4 v[158:159], off
	s_mov_b32 m0, s84
	v_lshl_add_u64 v[166:167], v[88:89], 0, v[96:97]
	v_readfirstlane_b32 s86, v122
	v_lshl_add_u64 v[162:163], v[126:127], 0, s[60:61]
	global_load_lds_dwordx4 v[160:161], off
	s_mov_b32 m0, s85
	v_readfirstlane_b32 s87, v123
	v_lshl_add_u64 v[156:157], v[166:167], 0, s[18:19]
	global_load_lds_dwordx4 v[162:163], off
	s_mov_b32 m0, s86
	v_readfirstlane_b32 s88, v124
	v_lshl_add_u64 v[164:165], v[166:167], 0, s[24:25]
	global_load_lds_dwordx4 v[156:157], off
	s_mov_b32 m0, s87
	v_lshl_add_u64 v[170:171], v[166:167], 0, s[26:27]
	global_load_lds_dwordx4 v[164:165], off
	s_mov_b32 m0, s88
	v_readfirstlane_b32 s76, v125
	global_load_lds_dwordx4 v[170:171], off
	ds_read_b128 v[154:157], v130
	ds_read_b128 v[158:161], v130 offset:2048
	ds_read_b128 v[162:165], v131 offset:20480
	ds_read_b128 v[170:173], v131 offset:22528
	s_waitcnt lgkmcnt(0)
	v_mfma_f32_16x16x32_bf16 v[60:63], v[146:149], v[154:157], v[60:63]
	s_mov_b32 m0, s76
	v_readfirstlane_b32 s76, v129
	v_readfirstlane_b32 s77, v135
	v_mfma_f32_16x16x32_bf16 v[56:59], v[150:153], v[154:157], v[56:59]
	v_lshl_add_u64 v[178:179], v[126:127], 0, s[62:63]
	v_readfirstlane_b32 s84, v136
	v_lshl_add_u64 v[184:185], v[126:127], 0, s[64:65]
	v_mfma_f32_16x16x32_bf16 v[52:55], v[162:165], v[154:157], v[52:55]
	v_readfirstlane_b32 s85, v137
	v_lshl_add_u64 v[186:187], v[126:127], 0, s[66:67]
	v_readfirstlane_b32 s86, v138
	v_mfma_f32_16x16x32_bf16 v[48:51], v[170:173], v[154:157], v[48:51]
	v_lshl_add_u64 v[154:155], v[166:167], 0, s[28:29]
	global_load_lds_dwordx4 v[154:155], off
	v_mfma_f32_16x16x32_bf16 v[44:47], v[146:149], v[158:161], v[44:47]
	s_mov_b32 m0, s76
	v_lshl_add_u64 v[126:127], v[126:127], 0, s[68:69]
	v_readfirstlane_b32 s87, v139
	v_mfma_f32_16x16x32_bf16 v[40:43], v[150:153], v[158:161], v[40:43]
	v_lshl_add_u64 v[182:183], v[166:167], 0, s[30:31]
	v_readfirstlane_b32 s88, v140
	v_lshl_add_u64 v[188:189], v[166:167], 0, s[34:35]
	v_mfma_f32_16x16x32_bf16 v[36:39], v[162:165], v[158:161], v[36:39]
	v_readfirstlane_b32 s89, v141
	v_lshl_add_u64 v[190:191], v[166:167], 0, s[36:37]
	v_lshl_add_u64 v[166:167], v[166:167], 0, s[38:39]
	v_mfma_f32_16x16x32_bf16 v[32:35], v[170:173], v[158:161], v[32:35]
	ds_read_b128 v[154:157], v130 offset:4096
	ds_read_b128 v[158:161], v130 offset:6144
	s_add_i32 s71, s71, 2
	v_lshl_add_u64 v[88:89], v[88:89], 0, s[30:31]
	s_waitcnt lgkmcnt(0)
	v_mfma_f32_16x16x32_bf16 v[28:31], v[146:149], v[154:157], v[28:31]
	s_cmp_lt_u32 s71, 12
	v_lshl_add_u64 v[90:91], v[90:91], 0, s[30:31]
	v_mfma_f32_16x16x32_bf16 v[24:27], v[150:153], v[154:157], v[24:27]
	v_mfma_f32_16x16x32_bf16 v[20:23], v[162:165], v[154:157], v[20:23]
	v_mfma_f32_16x16x32_bf16 v[16:19], v[170:173], v[154:157], v[16:19]
	v_mfma_f32_16x16x32_bf16 v[12:15], v[146:149], v[158:161], v[12:15]
	v_mfma_f32_16x16x32_bf16 v[4:7], v[150:153], v[158:161], v[4:7]
	ds_read_b128 v[146:149], v133 offset:16384
	ds_read_b128 v[150:153], v133 offset:18432
	v_mfma_f32_16x16x32_bf16 v[0:3], v[162:165], v[158:161], v[0:3]
	v_mfma_f32_16x16x32_bf16 v[8:11], v[170:173], v[158:161], v[8:11]
	ds_read_b128 v[154:157], v132
	ds_read_b128 v[158:161], v132 offset:2048
	ds_read_b128 v[162:165], v133 offset:20480
	ds_read_b128 v[170:173], v133 offset:22528
	s_waitcnt lgkmcnt(0)
	v_mfma_f32_16x16x32_bf16 v[60:63], v[146:149], v[154:157], v[60:63]
	v_mfma_f32_16x16x32_bf16 v[56:59], v[150:153], v[154:157], v[56:59]
	v_mfma_f32_16x16x32_bf16 v[52:55], v[162:165], v[154:157], v[52:55]
	v_mfma_f32_16x16x32_bf16 v[48:51], v[170:173], v[154:157], v[48:51]
	ds_read_b128 v[154:157], v132 offset:4096
	ds_read_b128 v[174:177], v132 offset:6144
	s_waitcnt vmcnt(0) lgkmcnt(0)
	s_barrier
	global_load_lds_dwordx4 v[178:179], off
	s_mov_b32 m0, s77
	v_mfma_f32_16x16x32_bf16 v[44:47], v[146:149], v[158:161], v[44:47]
	v_mfma_f32_16x16x32_bf16 v[40:43], v[150:153], v[158:161], v[40:43]
	v_mfma_f32_16x16x32_bf16 v[36:39], v[162:165], v[158:161], v[36:39]
	v_mfma_f32_16x16x32_bf16 v[32:35], v[170:173], v[158:161], v[32:35]
	ds_read_b128 v[158:161], v131 offset:49152
	ds_read_b128 v[178:181], v131 offset:51200
	global_load_lds_dwordx4 v[184:185], off
	s_mov_b32 m0, s84
	s_waitcnt lgkmcnt(0)
	v_mfma_f32_16x16x32_bf16 v[28:31], v[146:149], v[154:157], v[28:31]
	global_load_lds_dwordx4 v[186:187], off
	s_mov_b32 m0, s85
	v_mfma_f32_16x16x32_bf16 v[24:27], v[150:153], v[154:157], v[24:27]
	global_load_lds_dwordx4 v[126:127], off
	s_mov_b32 m0, s86
	v_mfma_f32_16x16x32_bf16 v[20:23], v[162:165], v[154:157], v[20:23]
	global_load_lds_dwordx4 v[182:183], off
	s_mov_b32 m0, s87
	v_mfma_f32_16x16x32_bf16 v[16:19], v[170:173], v[154:157], v[16:19]
	global_load_lds_dwordx4 v[188:189], off
	s_mov_b32 m0, s88
	v_mfma_f32_16x16x32_bf16 v[12:15], v[146:149], v[174:177], v[12:15]
	global_load_lds_dwordx4 v[190:191], off
	s_mov_b32 m0, s89
	v_mfma_f32_16x16x32_bf16 v[4:7], v[150:153], v[174:177], v[4:7]
	global_load_lds_dwordx4 v[166:167], off
	ds_read_b128 v[146:149], v130 offset:32768
	ds_read_b128 v[150:153], v130 offset:34816
	v_mfma_f32_16x16x32_bf16 v[0:3], v[162:165], v[174:177], v[0:3]
	ds_read_b128 v[154:157], v131 offset:53248
	ds_read_b128 v[162:165], v131 offset:55296
	s_waitcnt lgkmcnt(0)
	v_mfma_f32_16x16x32_bf16 v[60:63], v[158:161], v[146:149], v[60:63]
	v_mfma_f32_16x16x32_bf16 v[56:59], v[178:181], v[146:149], v[56:59]
	v_mfma_f32_16x16x32_bf16 v[52:55], v[154:157], v[146:149], v[52:55]
	v_mfma_f32_16x16x32_bf16 v[48:51], v[162:165], v[146:149], v[48:51]
	v_mfma_f32_16x16x32_bf16 v[44:47], v[158:161], v[150:153], v[44:47]
	v_mfma_f32_16x16x32_bf16 v[40:43], v[178:181], v[150:153], v[40:43]
	v_mfma_f32_16x16x32_bf16 v[36:39], v[154:157], v[150:153], v[36:39]
	v_mfma_f32_16x16x32_bf16 v[32:35], v[162:165], v[150:153], v[32:35]
	ds_read_b128 v[146:149], v130 offset:36864
	ds_read_b128 v[150:153], v130 offset:38912
	v_mfma_f32_16x16x32_bf16 v[8:11], v[170:173], v[174:177], v[8:11]
	s_waitcnt lgkmcnt(0)
	v_mfma_f32_16x16x32_bf16 v[28:31], v[158:161], v[146:149], v[28:31]
	v_mfma_f32_16x16x32_bf16 v[24:27], v[178:181], v[146:149], v[24:27]
	v_mfma_f32_16x16x32_bf16 v[20:23], v[154:157], v[146:149], v[20:23]
	v_mfma_f32_16x16x32_bf16 v[16:19], v[162:165], v[146:149], v[16:19]
	v_mfma_f32_16x16x32_bf16 v[12:15], v[158:161], v[150:153], v[12:15]
	v_mfma_f32_16x16x32_bf16 v[4:7], v[178:181], v[150:153], v[4:7]
	v_mfma_f32_16x16x32_bf16 v[0:3], v[154:157], v[150:153], v[0:3]
	ds_read_b128 v[146:149], v133 offset:49152
	ds_read_b128 v[154:157], v133 offset:51200
	v_mfma_f32_16x16x32_bf16 v[8:11], v[162:165], v[150:153], v[8:11]
	ds_read_b128 v[150:153], v132 offset:32768
	ds_read_b128 v[158:161], v132 offset:34816
	ds_read_b128 v[162:165], v133 offset:53248
	ds_read_b128 v[170:173], v133 offset:55296
	s_waitcnt lgkmcnt(0)
	v_mfma_f32_16x16x32_bf16 v[60:63], v[146:149], v[150:153], v[60:63]
	v_mfma_f32_16x16x32_bf16 v[56:59], v[154:157], v[150:153], v[56:59]
	v_mfma_f32_16x16x32_bf16 v[52:55], v[162:165], v[150:153], v[52:55]
	v_mfma_f32_16x16x32_bf16 v[48:51], v[170:173], v[150:153], v[48:51]
	v_mfma_f32_16x16x32_bf16 v[44:47], v[146:149], v[158:161], v[44:47]
	v_mfma_f32_16x16x32_bf16 v[40:43], v[154:157], v[158:161], v[40:43]
	v_mfma_f32_16x16x32_bf16 v[36:39], v[162:165], v[158:161], v[36:39]
	v_mfma_f32_16x16x32_bf16 v[32:35], v[170:173], v[158:161], v[32:35]
	ds_read_b128 v[150:153], v132 offset:36864
	ds_read_b128 v[158:161], v132 offset:38912
	s_waitcnt lgkmcnt(0)
	v_mfma_f32_16x16x32_bf16 v[28:31], v[146:149], v[150:153], v[28:31]
	v_mfma_f32_16x16x32_bf16 v[24:27], v[154:157], v[150:153], v[24:27]
	v_mfma_f32_16x16x32_bf16 v[20:23], v[162:165], v[150:153], v[20:23]
	v_mfma_f32_16x16x32_bf16 v[16:19], v[170:173], v[150:153], v[16:19]
	v_mfma_f32_16x16x32_bf16 v[12:15], v[146:149], v[158:161], v[12:15]
	v_mfma_f32_16x16x32_bf16 v[4:7], v[154:157], v[158:161], v[4:7]
	v_mfma_f32_16x16x32_bf16 v[0:3], v[162:165], v[158:161], v[0:3]
	v_mfma_f32_16x16x32_bf16 v[8:11], v[170:173], v[158:161], v[8:11]
	s_cbranch_scc1 .LBB0_465
	v_readfirstlane_b32 s71, v92
	s_waitcnt vmcnt(0) lgkmcnt(0)
	s_barrier
	v_lshl_add_u64 v[88:89], v[86:87], 0, s[40:41]
	s_mov_b32 m0, s71
	v_readfirstlane_b32 s71, v93
	global_load_lds_dwordx4 v[88:89], off
	v_lshl_add_u64 v[88:89], v[86:87], 0, s[42:43]
	s_mov_b32 m0, s71
	v_readfirstlane_b32 s71, v94
	global_load_lds_dwordx4 v[88:89], off
	v_lshl_add_u64 v[88:89], v[86:87], 0, s[44:45]
	s_mov_b32 m0, s71
	v_readfirstlane_b32 s71, v95
	global_load_lds_dwordx4 v[88:89], off
	v_lshl_add_u64 v[86:87], v[86:87], 0, s[48:49]
	s_mov_b32 m0, s71
	v_readfirstlane_b32 s71, v122
	v_lshl_add_u64 v[90:91], v[84:85], 0, s[40:41]
	global_load_lds_dwordx4 v[86:87], off
	s_mov_b32 m0, s71
	v_readfirstlane_b32 s71, v123
	global_load_lds_dwordx4 v[90:91], off
	v_lshl_add_u64 v[86:87], v[84:85], 0, s[42:43]
	s_mov_b32 m0, s71
	v_readfirstlane_b32 s71, v124
	global_load_lds_dwordx4 v[86:87], off
	v_lshl_add_u64 v[90:91], v[84:85], 0, s[44:45]
	s_mov_b32 m0, s71
	ds_read_b128 v[86:89], v131 offset:16384
	global_load_lds_dwordx4 v[90:91], off
	ds_read_b128 v[146:149], v131 offset:18432
	ds_read_b128 v[150:153], v130
	ds_read_b128 v[154:157], v130 offset:2048
	ds_read_b128 v[158:161], v131 offset:20480
	ds_read_b128 v[162:165], v131 offset:22528
	v_readfirstlane_b32 s71, v125
	v_lshl_add_u64 v[84:85], v[84:85], 0, s[48:49]
	s_mov_b32 m0, s71
	s_waitcnt lgkmcnt(0)
	v_mfma_f32_16x16x32_bf16 v[60:63], v[86:89], v[150:153], v[60:63]
	global_load_lds_dwordx4 v[84:85], off
	v_readfirstlane_b32 s71, v129
	v_mfma_f32_16x16x32_bf16 v[56:59], v[146:149], v[150:153], v[56:59]
	s_mov_b32 m0, s71
	v_readfirstlane_b32 s71, v135
	s_and_b64 vcc, exec, s[6:7]
	v_mfma_f32_16x16x32_bf16 v[52:55], v[158:161], v[150:153], v[52:55]
	v_mfma_f32_16x16x32_bf16 v[48:51], v[162:165], v[150:153], v[48:51]
	v_mfma_f32_16x16x32_bf16 v[44:47], v[86:89], v[154:157], v[44:47]
	v_mfma_f32_16x16x32_bf16 v[40:43], v[146:149], v[154:157], v[40:43]
	v_mfma_f32_16x16x32_bf16 v[36:39], v[158:161], v[154:157], v[36:39]
	v_mfma_f32_16x16x32_bf16 v[32:35], v[162:165], v[154:157], v[32:35]
	ds_read_b128 v[150:153], v130 offset:4096
	ds_read_b128 v[154:157], v130 offset:6144
	s_waitcnt lgkmcnt(0)
	v_mfma_f32_16x16x32_bf16 v[28:31], v[86:89], v[150:153], v[28:31]
	v_mfma_f32_16x16x32_bf16 v[24:27], v[146:149], v[150:153], v[24:27]
	v_mfma_f32_16x16x32_bf16 v[170:173], v[158:161], v[150:153], v[20:23]
	v_mfma_f32_16x16x32_bf16 v[150:153], v[162:165], v[150:153], v[16:19]
	v_mfma_f32_16x16x32_bf16 v[84:87], v[86:89], v[154:157], v[12:15]
	v_mfma_f32_16x16x32_bf16 v[4:7], v[146:149], v[154:157], v[4:7]
	ds_read_b128 v[146:149], v133 offset:16384
	v_mfma_f32_16x16x32_bf16 v[88:91], v[158:161], v[154:157], v[0:3]
	v_mfma_f32_16x16x32_bf16 v[154:157], v[162:165], v[154:157], v[8:11]
	ds_read_b128 v[158:161], v133 offset:18432
	s_nop 0
	ds_read_b128 v[0:3], v132
	ds_read_b128 v[8:11], v132 offset:2048
	ds_read_b128 v[162:165], v133 offset:20480
	ds_read_b128 v[174:177], v133 offset:22528
	ds_read_b128 v[178:181], v132 offset:4096
	ds_read_b128 v[182:185], v132 offset:6144
	s_waitcnt vmcnt(0) lgkmcnt(0)
	s_barrier
	s_waitcnt lgkmcnt(0)
	v_mfma_f32_16x16x32_bf16 v[44:47], v[146:149], v[8:11], v[44:47]
	ds_read_b128 v[186:189], v130 offset:32768
	ds_read_b128 v[190:193], v130 offset:34816
	ds_read_b128 v[194:197], v130 offset:36864
	ds_read_b128 v[198:201], v130 offset:38912
	ds_read_b128 v[202:205], v131 offset:49152
	ds_read_b128 v[206:209], v131 offset:51200
	ds_read_b128 v[210:213], v131 offset:53248
	ds_read_b128 v[214:217], v131 offset:55296
	ds_read_b128 v[218:221], v132 offset:32768
	ds_read_b128 v[222:225], v132 offset:34816
	v_mfma_f32_16x16x32_bf16 v[40:43], v[158:161], v[8:11], v[40:43]
	v_mfma_f32_16x16x32_bf16 v[36:39], v[162:165], v[8:11], v[36:39]
	v_mfma_f32_16x16x32_bf16 v[32:35], v[174:177], v[8:11], v[32:35]
	ds_read_b128 v[226:229], v132 offset:36864
	ds_read_b128 v[8:11], v132 offset:38912
	ds_read_b128 v[230:233], v133 offset:49152
	ds_read_b128 v[20:23], v133 offset:51200
	ds_read_b128 v[16:19], v133 offset:53248
	ds_read_b128 v[12:15], v133 offset:55296
	s_waitcnt lgkmcnt(0)
	global_load_dwordx4 v[238:241], v[98:99], off
	global_load_dwordx4 v[242:245], v[98:99], off offset:128
	v_mfma_f32_16x16x32_bf16 v[60:63], v[146:149], v[0:3], v[60:63]
	s_waitcnt vmcnt(0)
	v_lshlrev_b32_e32 v127, 16, v239
	v_mfma_f32_16x16x32_bf16 v[56:59], v[158:161], v[0:3], v[56:59]
	v_lshlrev_b32_e32 v126, 16, v238
	v_mfma_f32_16x16x32_bf16 v[52:55], v[162:165], v[0:3], v[52:55]
	v_mfma_f32_16x16x32_bf16 v[48:51], v[174:177], v[0:3], v[48:51]
	v_mfma_f32_16x16x32_bf16 v[234:237], v[158:161], v[178:181], v[24:27]
	global_load_dwordx4 v[0:3], v[98:99], off offset:384
	s_nop 1
	global_load_dwordx4 v[24:27], v[98:99], off offset:256
	s_waitcnt lgkmcnt(11)
	v_mfma_f32_16x16x32_bf16 v[60:63], v[202:205], v[186:189], v[60:63]
	s_waitcnt lgkmcnt(3)
	v_mfma_f32_16x16x32_bf16 v[60:63], v[230:233], v[218:221], v[60:63]
	v_mfma_f32_16x16x32_bf16 v[56:59], v[206:209], v[186:189], v[56:59]
	v_mfma_f32_16x16x32_bf16 v[28:31], v[146:149], v[178:181], v[28:31]
	s_nop 5
	v_mov_b32_e32 v166, v60
	v_mov_b32_e32 v167, v62
	v_pk_mul_f32 v[126:127], v[166:167], v[126:127]
	v_and_b32_e32 v167, 0xffff0000, v239
	v_and_b32_e32 v166, 0xffff0000, v238
	v_mov_b32_e32 v62, v61
	v_mfma_f32_16x16x32_bf16 v[84:87], v[146:149], v[182:185], v[84:87]
	v_mul_f32_e64 v146, v62, v166
	v_mul_f32_e64 v147, v63, v167
	v_and_b32_sdwa v60, v127, v142 dst_sel:DWORD dst_unused:UNUSED_PAD src0_sel:WORD_1 src1_sel:DWORD
	v_and_b32_sdwa v61, v126, v142 dst_sel:DWORD dst_unused:UNUSED_PAD src0_sel:WORD_1 src1_sel:DWORD
	s_waitcnt lgkmcnt(2)
	v_mfma_f32_16x16x32_bf16 v[56:59], v[20:23], v[218:221], v[56:59]
	v_add3_u32 v126, v126, v61, s3
	v_add3_u32 v127, v127, v60, s3
	v_and_b32_sdwa v143, v147, v142 dst_sel:DWORD dst_unused:UNUSED_PAD src0_sel:WORD_1 src1_sel:DWORD
	v_mfma_f32_16x16x32_bf16 v[60:63], v[162:165], v[182:185], v[88:91]
	v_add3_u32 v143, v147, v143, s3
	v_and_b32_e32 v143, 0xffff0000, v143
	v_or_b32_sdwa v147, v143, v127 dst_sel:DWORD dst_unused:UNUSED_PAD src0_sel:DWORD src1_sel:WORD_1
	v_and_b32_sdwa v88, v146, v142 dst_sel:DWORD dst_unused:UNUSED_PAD src0_sel:WORD_1 src1_sel:DWORD
	v_add3_u32 v145, v146, v88, s3
	v_mfma_f32_16x16x32_bf16 v[52:55], v[210:213], v[186:189], v[52:55]
	v_and_b32_e32 v145, 0xffff0000, v145
	v_or_b32_sdwa v146, v145, v126 dst_sel:DWORD dst_unused:UNUSED_PAD src0_sel:DWORD src1_sel:WORD_1
	v_lshlrev_b32_e32 v127, 16, v241
	v_lshlrev_b32_e32 v126, 16, v240
	v_mov_b32_e32 v148, v56
	v_mov_b32_e32 v149, v58
	v_pk_mul_f32 v[126:127], v[148:149], v[126:127]
	v_and_b32_e32 v149, 0xffff0000, v241
	v_and_b32_e32 v148, 0xffff0000, v240
	v_mov_b32_e32 v58, v57
	v_pk_mul_f32 v[56:57], v[58:59], v[148:149]
	v_and_b32_sdwa v58, v127, v142 dst_sel:DWORD dst_unused:UNUSED_PAD src0_sel:WORD_1 src1_sel:DWORD
	v_and_b32_sdwa v59, v126, v142 dst_sel:DWORD dst_unused:UNUSED_PAD src0_sel:WORD_1 src1_sel:DWORD
	s_waitcnt lgkmcnt(1)
	v_mfma_f32_16x16x32_bf16 v[52:55], v[16:19], v[218:221], v[52:55]
	v_add3_u32 v59, v126, v59, s3
	v_add3_u32 v58, v127, v58, s3
	v_and_b32_sdwa v126, v57, v142 dst_sel:DWORD dst_unused:UNUSED_PAD src0_sel:WORD_1 src1_sel:DWORD
	v_and_b32_sdwa v127, v56, v142 dst_sel:DWORD dst_unused:UNUSED_PAD src0_sel:WORD_1 src1_sel:DWORD
	v_mfma_f32_16x16x32_bf16 v[48:51], v[214:217], v[186:189], v[48:51]
	v_add3_u32 v57, v57, v126, s3
	v_add3_u32 v56, v56, v127, s3
	v_and_b32_e32 v57, 0xffff0000, v57
	v_and_b32_e32 v56, 0xffff0000, v56
	v_or_b32_sdwa v149, v57, v58 dst_sel:DWORD dst_unused:UNUSED_PAD src0_sel:DWORD src1_sel:WORD_1
	v_or_b32_sdwa v148, v56, v59 dst_sel:DWORD dst_unused:UNUSED_PAD src0_sel:DWORD src1_sel:WORD_1
	v_lshlrev_b32_e32 v57, 16, v243
	v_lshlrev_b32_e32 v56, 16, v242
	v_mov_b32_e32 v58, v52
	v_mov_b32_e32 v59, v54
	global_store_dwordx4 v[98:99], v[146:149], off
	v_pk_mul_f32 v[126:127], v[58:59], v[56:57]
	v_mov_b32_e32 v54, v53
	v_and_b32_e32 v147, 0xffff0000, v243
	v_and_b32_e32 v146, 0xffff0000, v242
	v_mfma_f32_16x16x32_bf16 v[150:153], v[174:177], v[178:181], v[150:153]
	v_and_b32_sdwa v143, v127, v142 dst_sel:DWORD dst_unused:UNUSED_PAD src0_sel:WORD_1 src1_sel:DWORD
	v_and_b32_sdwa v145, v126, v142 dst_sel:DWORD dst_unused:UNUSED_PAD src0_sel:WORD_1 src1_sel:DWORD
	v_add3_u32 v126, v126, v145, s3
	v_mfma_f32_16x16x32_bf16 v[4:7], v[158:161], v[182:185], v[4:7]
	v_add3_u32 v127, v127, v143, s3
	v_mfma_f32_16x16x32_bf16 v[88:91], v[174:177], v[182:185], v[154:157]
	s_nop 2
	v_mul_f32_e64 v154, v54, v146
	v_mul_f32_e64 v155, v55, v147
	s_waitcnt lgkmcnt(0)
	v_mfma_f32_16x16x32_bf16 v[48:51], v[12:15], v[218:221], v[48:51]
	v_and_b32_sdwa v143, v155, v142 dst_sel:DWORD dst_unused:UNUSED_PAD src0_sel:WORD_1 src1_sel:DWORD
	v_and_b32_sdwa v145, v154, v142 dst_sel:DWORD dst_unused:UNUSED_PAD src0_sel:WORD_1 src1_sel:DWORD
	v_add3_u32 v143, v155, v143, s3
	v_add3_u32 v145, v154, v145, s3
	v_mfma_f32_16x16x32_bf16 v[44:47], v[202:205], v[190:193], v[44:47]
	v_and_b32_e32 v143, 0xffff0000, v143
	v_and_b32_e32 v145, 0xffff0000, v145
	v_mfma_f32_16x16x32_bf16 v[146:149], v[214:217], v[194:197], v[150:153]
	v_mfma_f32_16x16x32_bf16 v[150:153], v[206:209], v[198:201], v[4:7]
	s_nop 2
	v_or_b32_sdwa v5, v143, v127 dst_sel:DWORD dst_unused:UNUSED_PAD src0_sel:DWORD src1_sel:WORD_1
	v_or_b32_sdwa v4, v145, v126 dst_sel:DWORD dst_unused:UNUSED_PAD src0_sel:DWORD src1_sel:WORD_1
	v_lshlrev_b32_e32 v7, 16, v245
	v_lshlrev_b32_e32 v6, 16, v244
	v_mov_b32_e32 v126, v48
	v_mov_b32_e32 v127, v50
	v_mfma_f32_16x16x32_bf16 v[170:173], v[162:165], v[178:181], v[170:173]
	v_mul_f32_e64 v6, v126, v6
	v_mul_f32_e64 v7, v127, v7
	v_and_b32_e32 v127, 0xffff0000, v245
	v_and_b32_e32 v126, 0xffff0000, v244
	v_mov_b32_e32 v50, v49
	v_pk_mul_f32 v[48:49], v[50:51], v[126:127]
	v_and_b32_sdwa v50, v7, v142 dst_sel:DWORD dst_unused:UNUSED_PAD src0_sel:WORD_1 src1_sel:DWORD
	v_and_b32_sdwa v51, v6, v142 dst_sel:DWORD dst_unused:UNUSED_PAD src0_sel:WORD_1 src1_sel:DWORD
	v_mfma_f32_16x16x32_bf16 v[44:47], v[230:233], v[222:225], v[44:47]
	v_add3_u32 v6, v6, v51, s3
	v_add3_u32 v7, v7, v50, s3
	v_and_b32_sdwa v50, v49, v142 dst_sel:DWORD dst_unused:UNUSED_PAD src0_sel:WORD_1 src1_sel:DWORD
	v_and_b32_sdwa v51, v48, v142 dst_sel:DWORD dst_unused:UNUSED_PAD src0_sel:WORD_1 src1_sel:DWORD
	v_add3_u32 v49, v49, v50, s3
	v_add3_u32 v48, v48, v51, s3
	v_mfma_f32_16x16x32_bf16 v[32:35], v[214:217], v[190:193], v[32:35]
	v_and_b32_e32 v126, 0xffff0000, v49
	v_and_b32_e32 v127, 0xffff0000, v48
	v_or_b32_sdwa v7, v126, v7 dst_sel:DWORD dst_unused:UNUSED_PAD src0_sel:DWORD src1_sel:WORD_1
	v_mfma_f32_16x16x32_bf16 v[52:55], v[210:213], v[194:197], v[170:173]
	v_or_b32_sdwa v6, v127, v6 dst_sel:DWORD dst_unused:UNUSED_PAD src0_sel:DWORD src1_sel:WORD_1
	global_store_dwordx4 v[98:99], v[4:7], off offset:128
	v_mfma_f32_16x16x32_bf16 v[40:43], v[206:209], v[190:193], v[40:43]
	s_waitcnt vmcnt(2)
	v_lshlrev_b32_e32 v5, 16, v25
	v_lshlrev_b32_e32 v4, 16, v24
	v_mov_b32_e32 v6, v44
	v_mov_b32_e32 v7, v46
	v_pk_mul_f32 v[126:127], v[6:7], v[4:5]
	v_and_b32_e32 v5, 0xffff0000, v25
	v_and_b32_e32 v4, 0xffff0000, v24
	v_mov_b32_e32 v46, v45
	v_mfma_f32_16x16x32_bf16 v[48:51], v[12:15], v[222:225], v[32:35]
	v_mul_f32_e64 v24, v46, v4
	v_mul_f32_e64 v25, v47, v5
	v_and_b32_sdwa v4, v126, v142 dst_sel:DWORD dst_unused:UNUSED_PAD src0_sel:WORD_1 src1_sel:DWORD
	v_add3_u32 v126, v126, v4, s3
	v_mfma_f32_16x16x32_bf16 v[32:35], v[16:19], v[226:229], v[52:55]
	global_load_dwordx4 v[44:47], v[98:99], off offset:640
	s_nop 1
	global_load_dwordx4 v[52:55], v[98:99], off offset:512
	v_and_b32_sdwa v143, v127, v142 dst_sel:DWORD dst_unused:UNUSED_PAD src0_sel:WORD_1 src1_sel:DWORD
	v_mfma_f32_16x16x32_bf16 v[36:39], v[210:213], v[190:193], v[36:39]
	v_mfma_f32_16x16x32_bf16 v[28:31], v[202:205], v[194:197], v[28:31]
	v_mfma_f32_16x16x32_bf16 v[56:59], v[206:209], v[194:197], v[234:237]
	v_mfma_f32_16x16x32_bf16 v[84:87], v[202:205], v[198:201], v[84:87]
	v_mfma_f32_16x16x32_bf16 v[60:63], v[210:213], v[198:201], v[60:63]
	v_mfma_f32_16x16x32_bf16 v[88:91], v[214:217], v[198:201], v[88:91]
	v_mfma_f32_16x16x32_bf16 v[40:43], v[20:23], v[222:225], v[40:43]
	v_mfma_f32_16x16x32_bf16 v[36:39], v[16:19], v[222:225], v[36:39]
	v_mfma_f32_16x16x32_bf16 v[154:157], v[230:233], v[226:229], v[28:31]
	v_mfma_f32_16x16x32_bf16 v[56:59], v[20:23], v[226:229], v[56:59]
	v_mfma_f32_16x16x32_bf16 v[28:31], v[12:15], v[226:229], v[146:149]
	v_mfma_f32_16x16x32_bf16 v[4:7], v[230:233], v[8:11], v[84:87]
	v_mfma_f32_16x16x32_bf16 v[20:23], v[20:23], v[8:11], v[150:153]
	s_nop 1
	v_and_b32_sdwa v85, v25, v142 dst_sel:DWORD dst_unused:UNUSED_PAD src0_sel:WORD_1 src1_sel:DWORD
	v_and_b32_sdwa v86, v24, v142 dst_sel:DWORD dst_unused:UNUSED_PAD src0_sel:WORD_1 src1_sel:DWORD
	v_add3_u32 v25, v25, v85, s3
	v_mfma_f32_16x16x32_bf16 v[16:19], v[16:19], v[8:11], v[60:63]
	v_add3_u32 v24, v24, v86, s3
	v_add3_u32 v84, v127, v143, s3
	v_and_b32_e32 v25, 0xffff0000, v25
	v_mfma_f32_16x16x32_bf16 v[8:11], v[12:15], v[8:11], v[88:91]
	v_lshlrev_b32_e32 v13, 16, v27
	v_lshlrev_b32_e32 v12, 16, v26
	v_mov_b32_e32 v14, v40
	v_mov_b32_e32 v15, v42
	v_pk_mul_f32 v[12:13], v[14:15], v[12:13]
	v_and_b32_e32 v15, 0xffff0000, v27
	v_and_b32_e32 v14, 0xffff0000, v26
	v_mov_b32_e32 v42, v41
	v_pk_mul_f32 v[14:15], v[42:43], v[14:15]
	v_and_b32_sdwa v26, v13, v142 dst_sel:DWORD dst_unused:UNUSED_PAD src0_sel:WORD_1 src1_sel:DWORD
	v_and_b32_sdwa v27, v12, v142 dst_sel:DWORD dst_unused:UNUSED_PAD src0_sel:WORD_1 src1_sel:DWORD
	v_add3_u32 v12, v12, v27, s3
	v_add3_u32 v13, v13, v26, s3
	v_and_b32_sdwa v26, v15, v142 dst_sel:DWORD dst_unused:UNUSED_PAD src0_sel:WORD_1 src1_sel:DWORD
	v_and_b32_sdwa v27, v14, v142 dst_sel:DWORD dst_unused:UNUSED_PAD src0_sel:WORD_1 src1_sel:DWORD
	v_add3_u32 v15, v15, v26, s3
	v_add3_u32 v14, v14, v27, s3
	v_and_b32_e32 v15, 0xffff0000, v15
	v_and_b32_e32 v14, 0xffff0000, v14
	v_or_b32_sdwa v27, v15, v13 dst_sel:DWORD dst_unused:UNUSED_PAD src0_sel:DWORD src1_sel:WORD_1
	v_or_b32_sdwa v26, v14, v12 dst_sel:DWORD dst_unused:UNUSED_PAD src0_sel:DWORD src1_sel:WORD_1
	v_lshlrev_b32_e32 v13, 16, v1
	v_lshlrev_b32_e32 v12, 16, v0
	v_mov_b32_e32 v14, v36
	v_mov_b32_e32 v15, v38
	v_pk_mul_f32 v[12:13], v[14:15], v[12:13]
	v_and_b32_e32 v1, 0xffff0000, v1
	v_and_b32_e32 v0, 0xffff0000, v0
	v_mov_b32_e32 v38, v37
	v_pk_mul_f32 v[0:1], v[38:39], v[0:1]
	v_and_b32_sdwa v14, v13, v142 dst_sel:DWORD dst_unused:UNUSED_PAD src0_sel:WORD_1 src1_sel:DWORD
	v_and_b32_sdwa v15, v12, v142 dst_sel:DWORD dst_unused:UNUSED_PAD src0_sel:WORD_1 src1_sel:DWORD
	v_add3_u32 v12, v12, v15, s3
	v_add3_u32 v13, v13, v14, s3
	v_and_b32_sdwa v14, v1, v142 dst_sel:DWORD dst_unused:UNUSED_PAD src0_sel:WORD_1 src1_sel:DWORD
	v_and_b32_sdwa v15, v0, v142 dst_sel:DWORD dst_unused:UNUSED_PAD src0_sel:WORD_1 src1_sel:DWORD
	v_add3_u32 v1, v1, v14, s3
	v_add3_u32 v0, v0, v15, s3
	v_and_b32_e32 v1, 0xffff0000, v1
	v_and_b32_e32 v0, 0xffff0000, v0
	v_or_b32_sdwa v1, v1, v13 dst_sel:DWORD dst_unused:UNUSED_PAD src0_sel:DWORD src1_sel:WORD_1
	v_or_b32_sdwa v0, v0, v12 dst_sel:DWORD dst_unused:UNUSED_PAD src0_sel:DWORD src1_sel:WORD_1
	v_lshlrev_b32_e32 v13, 16, v3
	v_lshlrev_b32_e32 v12, 16, v2
	v_mov_b32_e32 v14, v48
	v_mov_b32_e32 v15, v50
	v_pk_mul_f32 v[12:13], v[14:15], v[12:13]
	v_and_b32_e32 v3, 0xffff0000, v3
	v_and_b32_e32 v2, 0xffff0000, v2
	v_mov_b32_e32 v50, v49
	v_pk_mul_f32 v[2:3], v[50:51], v[2:3]
	v_and_b32_sdwa v14, v13, v142 dst_sel:DWORD dst_unused:UNUSED_PAD src0_sel:WORD_1 src1_sel:DWORD
	v_and_b32_sdwa v15, v12, v142 dst_sel:DWORD dst_unused:UNUSED_PAD src0_sel:WORD_1 src1_sel:DWORD
	v_add3_u32 v12, v12, v15, s3
	v_add3_u32 v13, v13, v14, s3
	v_and_b32_sdwa v14, v3, v142 dst_sel:DWORD dst_unused:UNUSED_PAD src0_sel:WORD_1 src1_sel:DWORD
	v_and_b32_sdwa v15, v2, v142 dst_sel:DWORD dst_unused:UNUSED_PAD src0_sel:WORD_1 src1_sel:DWORD
	v_add3_u32 v3, v3, v14, s3
	v_add3_u32 v2, v2, v15, s3
	v_and_b32_e32 v24, 0xffff0000, v24
	v_and_b32_e32 v3, 0xffff0000, v3
	v_and_b32_e32 v2, 0xffff0000, v2
	v_or_b32_sdwa v25, v25, v84 dst_sel:DWORD dst_unused:UNUSED_PAD src0_sel:DWORD src1_sel:WORD_1
	v_or_b32_sdwa v24, v24, v126 dst_sel:DWORD dst_unused:UNUSED_PAD src0_sel:DWORD src1_sel:WORD_1
	v_or_b32_sdwa v3, v3, v13 dst_sel:DWORD dst_unused:UNUSED_PAD src0_sel:DWORD src1_sel:WORD_1
	v_or_b32_sdwa v2, v2, v12 dst_sel:DWORD dst_unused:UNUSED_PAD src0_sel:DWORD src1_sel:WORD_1
	global_store_dwordx4 v[98:99], v[24:27], off offset:256
	global_store_dwordx4 v[98:99], v[0:3], off offset:384
	global_load_dwordx4 v[0:3], v[98:99], off offset:896
	s_nop 0
	global_load_dwordx4 v[12:15], v[98:99], off offset:768
	s_waitcnt vmcnt(4)
	v_lshlrev_b32_e32 v25, 16, v53
	v_lshlrev_b32_e32 v24, 16, v52
	v_mov_b32_e32 v26, v154
	v_mov_b32_e32 v27, v156
	v_pk_mul_f32 v[24:25], v[26:27], v[24:25]
	v_and_b32_e32 v27, 0xffff0000, v53
	v_and_b32_e32 v26, 0xffff0000, v52
	v_mov_b32_e32 v156, v155
	v_pk_mul_f32 v[26:27], v[156:157], v[26:27]
	v_and_b32_sdwa v36, v25, v142 dst_sel:DWORD dst_unused:UNUSED_PAD src0_sel:WORD_1 src1_sel:DWORD
	v_and_b32_sdwa v37, v24, v142 dst_sel:DWORD dst_unused:UNUSED_PAD src0_sel:WORD_1 src1_sel:DWORD
	v_add3_u32 v24, v24, v37, s3
	v_add3_u32 v25, v25, v36, s3
	v_and_b32_sdwa v36, v27, v142 dst_sel:DWORD dst_unused:UNUSED_PAD src0_sel:WORD_1 src1_sel:DWORD
	v_and_b32_sdwa v37, v26, v142 dst_sel:DWORD dst_unused:UNUSED_PAD src0_sel:WORD_1 src1_sel:DWORD
	v_add3_u32 v27, v27, v36, s3
	v_add3_u32 v26, v26, v37, s3
	v_and_b32_e32 v27, 0xffff0000, v27
	v_and_b32_e32 v26, 0xffff0000, v26
	v_or_b32_sdwa v25, v27, v25 dst_sel:DWORD dst_unused:UNUSED_PAD src0_sel:DWORD src1_sel:WORD_1
	v_or_b32_sdwa v24, v26, v24 dst_sel:DWORD dst_unused:UNUSED_PAD src0_sel:DWORD src1_sel:WORD_1
	v_lshlrev_b32_e32 v27, 16, v55
	v_lshlrev_b32_e32 v26, 16, v54
	v_mov_b32_e32 v36, v56
	v_mov_b32_e32 v37, v58
	v_pk_mul_f32 v[26:27], v[36:37], v[26:27]
	v_and_b32_e32 v37, 0xffff0000, v55
	v_and_b32_e32 v36, 0xffff0000, v54
	v_mov_b32_e32 v58, v57
	v_pk_mul_f32 v[36:37], v[58:59], v[36:37]
	v_and_b32_sdwa v38, v27, v142 dst_sel:DWORD dst_unused:UNUSED_PAD src0_sel:WORD_1 src1_sel:DWORD
	v_and_b32_sdwa v39, v26, v142 dst_sel:DWORD dst_unused:UNUSED_PAD src0_sel:WORD_1 src1_sel:DWORD
	v_add3_u32 v26, v26, v39, s3
	v_add3_u32 v27, v27, v38, s3
	v_and_b32_sdwa v38, v37, v142 dst_sel:DWORD dst_unused:UNUSED_PAD src0_sel:WORD_1 src1_sel:DWORD
	v_and_b32_sdwa v39, v36, v142 dst_sel:DWORD dst_unused:UNUSED_PAD src0_sel:WORD_1 src1_sel:DWORD
	v_add3_u32 v37, v37, v38, s3
	v_add3_u32 v36, v36, v39, s3
	v_and_b32_e32 v37, 0xffff0000, v37
	v_and_b32_e32 v36, 0xffff0000, v36
	v_or_b32_sdwa v27, v37, v27 dst_sel:DWORD dst_unused:UNUSED_PAD src0_sel:DWORD src1_sel:WORD_1
	v_or_b32_sdwa v26, v36, v26 dst_sel:DWORD dst_unused:UNUSED_PAD src0_sel:DWORD src1_sel:WORD_1
	global_store_dwordx4 v[98:99], v[24:27], off offset:512
	v_lshl_add_u64 v[86:87], v[116:117], 0, s[72:73]
	v_lshl_add_u64 v[84:85], v[120:121], 0, s[74:75]
	v_lshlrev_b32_e32 v25, 16, v45
	v_lshlrev_b32_e32 v24, 16, v44
	v_mov_b32_e32 v26, v32
	v_mov_b32_e32 v27, v34
	v_pk_mul_f32 v[24:25], v[26:27], v[24:25]
	v_and_b32_e32 v27, 0xffff0000, v45
	v_and_b32_e32 v26, 0xffff0000, v44
	v_mov_b32_e32 v34, v33
	v_pk_mul_f32 v[26:27], v[34:35], v[26:27]
	v_and_b32_sdwa v32, v25, v142 dst_sel:DWORD dst_unused:UNUSED_PAD src0_sel:WORD_1 src1_sel:DWORD
	v_and_b32_sdwa v33, v24, v142 dst_sel:DWORD dst_unused:UNUSED_PAD src0_sel:WORD_1 src1_sel:DWORD
	v_add3_u32 v24, v24, v33, s3
	v_add3_u32 v25, v25, v32, s3
	v_and_b32_sdwa v32, v27, v142 dst_sel:DWORD dst_unused:UNUSED_PAD src0_sel:WORD_1 src1_sel:DWORD
	v_and_b32_sdwa v33, v26, v142 dst_sel:DWORD dst_unused:UNUSED_PAD src0_sel:WORD_1 src1_sel:DWORD
	v_add3_u32 v27, v27, v32, s3
	v_add3_u32 v26, v26, v33, s3
	v_and_b32_e32 v27, 0xffff0000, v27
	v_and_b32_e32 v26, 0xffff0000, v26
	v_or_b32_sdwa v25, v27, v25 dst_sel:DWORD dst_unused:UNUSED_PAD src0_sel:DWORD src1_sel:WORD_1
	v_or_b32_sdwa v24, v26, v24 dst_sel:DWORD dst_unused:UNUSED_PAD src0_sel:DWORD src1_sel:WORD_1
	v_lshlrev_b32_e32 v27, 16, v47
	v_lshlrev_b32_e32 v26, 16, v46
	v_mov_b32_e32 v32, v28
	v_mov_b32_e32 v33, v30
	v_pk_mul_f32 v[26:27], v[32:33], v[26:27]
	v_and_b32_e32 v33, 0xffff0000, v47
	v_and_b32_e32 v32, 0xffff0000, v46
	v_mov_b32_e32 v30, v29
	v_pk_mul_f32 v[28:29], v[30:31], v[32:33]
	v_and_b32_sdwa v30, v27, v142 dst_sel:DWORD dst_unused:UNUSED_PAD src0_sel:WORD_1 src1_sel:DWORD
	v_and_b32_sdwa v31, v26, v142 dst_sel:DWORD dst_unused:UNUSED_PAD src0_sel:WORD_1 src1_sel:DWORD
	v_add3_u32 v26, v26, v31, s3
	v_add3_u32 v27, v27, v30, s3
	v_and_b32_sdwa v30, v29, v142 dst_sel:DWORD dst_unused:UNUSED_PAD src0_sel:WORD_1 src1_sel:DWORD
	v_and_b32_sdwa v31, v28, v142 dst_sel:DWORD dst_unused:UNUSED_PAD src0_sel:WORD_1 src1_sel:DWORD
	v_add3_u32 v29, v29, v30, s3
	v_add3_u32 v28, v28, v31, s3
	v_and_b32_e32 v29, 0xffff0000, v29
	v_and_b32_e32 v28, 0xffff0000, v28
	v_or_b32_sdwa v27, v29, v27 dst_sel:DWORD dst_unused:UNUSED_PAD src0_sel:DWORD src1_sel:WORD_1
	v_or_b32_sdwa v26, v28, v26 dst_sel:DWORD dst_unused:UNUSED_PAD src0_sel:DWORD src1_sel:WORD_1
	global_store_dwordx4 v[98:99], v[24:27], off offset:640
	s_waitcnt vmcnt(2)
	s_nop 0
	v_lshlrev_b32_e32 v25, 16, v13
	v_lshlrev_b32_e32 v24, 16, v12
	v_mov_b32_e32 v27, v6
	v_and_b32_e32 v13, 0xffff0000, v13
	v_and_b32_e32 v12, 0xffff0000, v12
	v_mov_b32_e32 v6, v5
	v_mov_b32_e32 v26, v4
	v_pk_mul_f32 v[4:5], v[6:7], v[12:13]
	v_pk_mul_f32 v[24:25], v[26:27], v[24:25]
	v_and_b32_sdwa v12, v5, v142 dst_sel:DWORD dst_unused:UNUSED_PAD src0_sel:WORD_1 src1_sel:DWORD
	v_and_b32_sdwa v13, v4, v142 dst_sel:DWORD dst_unused:UNUSED_PAD src0_sel:WORD_1 src1_sel:DWORD
	v_and_b32_sdwa v6, v25, v142 dst_sel:DWORD dst_unused:UNUSED_PAD src0_sel:WORD_1 src1_sel:DWORD
	v_and_b32_sdwa v7, v24, v142 dst_sel:DWORD dst_unused:UNUSED_PAD src0_sel:WORD_1 src1_sel:DWORD
	v_add3_u32 v5, v5, v12, s3
	v_add3_u32 v4, v4, v13, s3
	v_add3_u32 v7, v24, v7, s3
	v_add3_u32 v6, v25, v6, s3
	v_and_b32_e32 v5, 0xffff0000, v5
	v_and_b32_e32 v4, 0xffff0000, v4
	v_or_b32_sdwa v5, v5, v6 dst_sel:DWORD dst_unused:UNUSED_PAD src0_sel:DWORD src1_sel:WORD_1
	v_or_b32_sdwa v4, v4, v7 dst_sel:DWORD dst_unused:UNUSED_PAD src0_sel:DWORD src1_sel:WORD_1
	v_lshlrev_b32_e32 v7, 16, v15
	v_lshlrev_b32_e32 v6, 16, v14
	v_mov_b32_e32 v12, v20
	v_mov_b32_e32 v13, v22
	v_pk_mul_f32 v[6:7], v[12:13], v[6:7]
	v_and_b32_e32 v13, 0xffff0000, v15
	v_and_b32_e32 v12, 0xffff0000, v14
	v_mov_b32_e32 v22, v21
	v_pk_mul_f32 v[12:13], v[22:23], v[12:13]
	v_and_b32_sdwa v14, v7, v142 dst_sel:DWORD dst_unused:UNUSED_PAD src0_sel:WORD_1 src1_sel:DWORD
	v_and_b32_sdwa v15, v6, v142 dst_sel:DWORD dst_unused:UNUSED_PAD src0_sel:WORD_1 src1_sel:DWORD
	v_add3_u32 v6, v6, v15, s3
	v_add3_u32 v7, v7, v14, s3
	v_and_b32_sdwa v14, v13, v142 dst_sel:DWORD dst_unused:UNUSED_PAD src0_sel:WORD_1 src1_sel:DWORD
	v_and_b32_sdwa v15, v12, v142 dst_sel:DWORD dst_unused:UNUSED_PAD src0_sel:WORD_1 src1_sel:DWORD
	v_add3_u32 v13, v13, v14, s3
	v_add3_u32 v12, v12, v15, s3
	v_and_b32_e32 v13, 0xffff0000, v13
	v_and_b32_e32 v12, 0xffff0000, v12
	v_or_b32_sdwa v7, v13, v7 dst_sel:DWORD dst_unused:UNUSED_PAD src0_sel:DWORD src1_sel:WORD_1
	v_or_b32_sdwa v6, v12, v6 dst_sel:DWORD dst_unused:UNUSED_PAD src0_sel:DWORD src1_sel:WORD_1
	global_store_dwordx4 v[98:99], v[4:7], off offset:768
	s_nop 1
	v_lshlrev_b32_e32 v5, 16, v1
	v_lshlrev_b32_e32 v4, 16, v0
	v_mov_b32_e32 v6, v16
	v_mov_b32_e32 v7, v18
	v_pk_mul_f32 v[4:5], v[6:7], v[4:5]
	v_and_b32_e32 v1, 0xffff0000, v1
	v_and_b32_e32 v0, 0xffff0000, v0
	v_mov_b32_e32 v18, v17
	v_pk_mul_f32 v[0:1], v[18:19], v[0:1]
	v_and_b32_sdwa v6, v5, v142 dst_sel:DWORD dst_unused:UNUSED_PAD src0_sel:WORD_1 src1_sel:DWORD
	v_and_b32_sdwa v7, v4, v142 dst_sel:DWORD dst_unused:UNUSED_PAD src0_sel:WORD_1 src1_sel:DWORD
	v_add3_u32 v4, v4, v7, s3
	v_add3_u32 v5, v5, v6, s3
	v_and_b32_sdwa v6, v1, v142 dst_sel:DWORD dst_unused:UNUSED_PAD src0_sel:WORD_1 src1_sel:DWORD
	v_and_b32_sdwa v7, v0, v142 dst_sel:DWORD dst_unused:UNUSED_PAD src0_sel:WORD_1 src1_sel:DWORD
	v_add3_u32 v1, v1, v6, s3
	v_add3_u32 v0, v0, v7, s3
	v_and_b32_e32 v1, 0xffff0000, v1
	v_and_b32_e32 v0, 0xffff0000, v0
	v_or_b32_sdwa v1, v1, v5 dst_sel:DWORD dst_unused:UNUSED_PAD src0_sel:DWORD src1_sel:WORD_1
	v_or_b32_sdwa v0, v0, v4 dst_sel:DWORD dst_unused:UNUSED_PAD src0_sel:DWORD src1_sel:WORD_1
	v_lshlrev_b32_e32 v5, 16, v3
	v_lshlrev_b32_e32 v4, 16, v2
	v_mov_b32_e32 v6, v8
	v_mov_b32_e32 v7, v10
	v_pk_mul_f32 v[4:5], v[6:7], v[4:5]
	v_and_b32_e32 v3, 0xffff0000, v3
	v_and_b32_e32 v2, 0xffff0000, v2
	v_mov_b32_e32 v10, v9
	v_pk_mul_f32 v[2:3], v[10:11], v[2:3]
	v_and_b32_sdwa v6, v5, v142 dst_sel:DWORD dst_unused:UNUSED_PAD src0_sel:WORD_1 src1_sel:DWORD
	v_and_b32_sdwa v7, v4, v142 dst_sel:DWORD dst_unused:UNUSED_PAD src0_sel:WORD_1 src1_sel:DWORD
	v_add3_u32 v4, v4, v7, s3
	v_add3_u32 v5, v5, v6, s3
	v_and_b32_sdwa v6, v3, v142 dst_sel:DWORD dst_unused:UNUSED_PAD src0_sel:WORD_1 src1_sel:DWORD
	v_and_b32_sdwa v7, v2, v142 dst_sel:DWORD dst_unused:UNUSED_PAD src0_sel:WORD_1 src1_sel:DWORD
	v_add3_u32 v3, v3, v6, s3
	v_add3_u32 v2, v2, v7, s3
	v_and_b32_e32 v3, 0xffff0000, v3
	v_and_b32_e32 v2, 0xffff0000, v2
	v_or_b32_sdwa v3, v3, v5 dst_sel:DWORD dst_unused:UNUSED_PAD src0_sel:DWORD src1_sel:WORD_1
	v_or_b32_sdwa v2, v2, v4 dst_sel:DWORD dst_unused:UNUSED_PAD src0_sel:DWORD src1_sel:WORD_1
	global_store_dwordx4 v[98:99], v[0:3], off offset:896
	s_barrier
	global_load_lds_dwordx4 v[86:87], off
	v_lshl_add_u64 v[0:1], v[86:87], 0, s[10:11]
	s_mov_b32 m0, s71
	v_readfirstlane_b32 s71, v136
	global_load_lds_dwordx4 v[0:1], off
	v_lshl_add_u64 v[0:1], v[86:87], 0, s[12:13]
	s_mov_b32 m0, s71
	v_readfirstlane_b32 s71, v137
	global_load_lds_dwordx4 v[0:1], off
	v_lshl_add_u64 v[0:1], v[86:87], 0, s[14:15]
	s_mov_b32 m0, s71
	v_readfirstlane_b32 s71, v138
	global_load_lds_dwordx4 v[0:1], off
	s_mov_b32 m0, s71
	v_readfirstlane_b32 s71, v139
	global_load_lds_dwordx4 v[84:85], off
	v_lshl_add_u64 v[0:1], v[84:85], 0, s[10:11]
	s_mov_b32 m0, s71
	v_readfirstlane_b32 s71, v140
	global_load_lds_dwordx4 v[0:1], off
	v_lshl_add_u64 v[0:1], v[84:85], 0, s[12:13]
	s_mov_b32 m0, s71
	v_readfirstlane_b32 s71, v141
	global_load_lds_dwordx4 v[0:1], off
	v_lshl_add_u64 v[0:1], v[84:85], 0, s[14:15]
	s_mov_b32 m0, s71
	s_nop 0
	global_load_lds_dwordx4 v[0:1], off
	s_cbranch_vccnz .LBB0_468
	s_sleep 8

.LBB0_469:
	v_lshl_add_u64 v[126:127], v[90:91], 0, v[96:97]
	v_readfirstlane_b32 s72, v92
	s_waitcnt vmcnt(0) lgkmcnt(0)
	s_barrier
	v_readfirstlane_b32 s73, v93
	v_lshl_add_u64 v[154:155], v[126:127], 0, s[18:19]
	s_mov_b32 m0, s72
	v_readfirstlane_b32 s74, v94
	v_lshl_add_u64 v[158:159], v[126:127], 0, s[24:25]
	ds_read_b128 v[146:149], v131 offset:16384
	ds_read_b128 v[150:153], v131 offset:18432
	global_load_lds_dwordx4 v[154:155], off
	s_mov_b32 m0, s73
	v_readfirstlane_b32 s75, v95
	v_lshl_add_u64 v[160:161], v[126:127], 0, s[26:27]
	global_load_lds_dwordx4 v[158:159], off
	s_mov_b32 m0, s74
	v_lshl_add_u64 v[166:167], v[88:89], 0, v[96:97]
	v_readfirstlane_b32 s76, v122
	v_lshl_add_u64 v[162:163], v[126:127], 0, s[28:29]
	global_load_lds_dwordx4 v[160:161], off
	s_mov_b32 m0, s75
	v_readfirstlane_b32 s77, v123
	v_lshl_add_u64 v[156:157], v[166:167], 0, s[18:19]
	global_load_lds_dwordx4 v[162:163], off
	s_mov_b32 m0, s76
	v_readfirstlane_b32 s84, v124
	v_lshl_add_u64 v[164:165], v[166:167], 0, s[24:25]
	global_load_lds_dwordx4 v[156:157], off
	s_mov_b32 m0, s77
	v_lshl_add_u64 v[170:171], v[166:167], 0, s[26:27]
	global_load_lds_dwordx4 v[164:165], off
	s_mov_b32 m0, s84
	v_readfirstlane_b32 s72, v125
	global_load_lds_dwordx4 v[170:171], off
	ds_read_b128 v[154:157], v130
	ds_read_b128 v[158:161], v130 offset:2048
	ds_read_b128 v[162:165], v131 offset:20480
	ds_read_b128 v[170:173], v131 offset:22528
	s_waitcnt lgkmcnt(0)
	v_mfma_f32_16x16x32_bf16 v[60:63], v[146:149], v[154:157], v[60:63]
	s_mov_b32 m0, s72
	v_readfirstlane_b32 s72, v129
	v_readfirstlane_b32 s73, v135
	v_mfma_f32_16x16x32_bf16 v[56:59], v[150:153], v[154:157], v[56:59]
	v_lshl_add_u64 v[178:179], v[126:127], 0, s[30:31]
	v_readfirstlane_b32 s74, v136
	v_lshl_add_u64 v[184:185], v[126:127], 0, s[34:35]
	v_mfma_f32_16x16x32_bf16 v[52:55], v[162:165], v[154:157], v[52:55]
	v_readfirstlane_b32 s75, v137
	v_lshl_add_u64 v[186:187], v[126:127], 0, s[36:37]
	v_readfirstlane_b32 s76, v138
	v_mfma_f32_16x16x32_bf16 v[48:51], v[170:173], v[154:157], v[48:51]
	v_lshl_add_u64 v[154:155], v[166:167], 0, s[28:29]
	global_load_lds_dwordx4 v[154:155], off
	v_mfma_f32_16x16x32_bf16 v[44:47], v[146:149], v[158:161], v[44:47]
	s_mov_b32 m0, s72
	v_lshl_add_u64 v[126:127], v[126:127], 0, s[38:39]
	v_readfirstlane_b32 s77, v139
	v_mfma_f32_16x16x32_bf16 v[40:43], v[150:153], v[158:161], v[40:43]
	v_lshl_add_u64 v[182:183], v[166:167], 0, s[30:31]
	v_readfirstlane_b32 s84, v140
	v_lshl_add_u64 v[188:189], v[166:167], 0, s[34:35]
	v_mfma_f32_16x16x32_bf16 v[36:39], v[162:165], v[158:161], v[36:39]
	v_readfirstlane_b32 s85, v141
	v_lshl_add_u64 v[190:191], v[166:167], 0, s[36:37]
	v_lshl_add_u64 v[166:167], v[166:167], 0, s[38:39]
	v_mfma_f32_16x16x32_bf16 v[32:35], v[170:173], v[158:161], v[32:35]
	ds_read_b128 v[154:157], v130 offset:4096
	ds_read_b128 v[158:161], v130 offset:6144
	s_add_i32 s71, s71, 2
	v_lshl_add_u64 v[88:89], v[88:89], 0, s[30:31]
	s_waitcnt lgkmcnt(0)
	v_mfma_f32_16x16x32_bf16 v[28:31], v[146:149], v[154:157], v[28:31]
	s_cmp_lt_u32 s71, 12
	v_lshl_add_u64 v[90:91], v[90:91], 0, s[30:31]
	v_mfma_f32_16x16x32_bf16 v[24:27], v[150:153], v[154:157], v[24:27]
	v_mfma_f32_16x16x32_bf16 v[20:23], v[162:165], v[154:157], v[20:23]
	v_mfma_f32_16x16x32_bf16 v[16:19], v[170:173], v[154:157], v[16:19]
	v_mfma_f32_16x16x32_bf16 v[12:15], v[146:149], v[158:161], v[12:15]
	v_mfma_f32_16x16x32_bf16 v[4:7], v[150:153], v[158:161], v[4:7]
	ds_read_b128 v[146:149], v133 offset:16384
	ds_read_b128 v[150:153], v133 offset:18432
	v_mfma_f32_16x16x32_bf16 v[0:3], v[162:165], v[158:161], v[0:3]
	v_mfma_f32_16x16x32_bf16 v[8:11], v[170:173], v[158:161], v[8:11]
	ds_read_b128 v[154:157], v132
	ds_read_b128 v[158:161], v132 offset:2048
	ds_read_b128 v[162:165], v133 offset:20480
	ds_read_b128 v[170:173], v133 offset:22528
	s_waitcnt lgkmcnt(0)
	v_mfma_f32_16x16x32_bf16 v[60:63], v[146:149], v[154:157], v[60:63]
	v_mfma_f32_16x16x32_bf16 v[56:59], v[150:153], v[154:157], v[56:59]
	v_mfma_f32_16x16x32_bf16 v[52:55], v[162:165], v[154:157], v[52:55]
	v_mfma_f32_16x16x32_bf16 v[48:51], v[170:173], v[154:157], v[48:51]
	ds_read_b128 v[154:157], v132 offset:4096
	ds_read_b128 v[174:177], v132 offset:6144
	s_waitcnt vmcnt(0) lgkmcnt(0)
	s_barrier
	global_load_lds_dwordx4 v[178:179], off
	s_mov_b32 m0, s73
	v_mfma_f32_16x16x32_bf16 v[44:47], v[146:149], v[158:161], v[44:47]
	v_mfma_f32_16x16x32_bf16 v[40:43], v[150:153], v[158:161], v[40:43]
	v_mfma_f32_16x16x32_bf16 v[36:39], v[162:165], v[158:161], v[36:39]
	v_mfma_f32_16x16x32_bf16 v[32:35], v[170:173], v[158:161], v[32:35]
	ds_read_b128 v[158:161], v131 offset:49152
	ds_read_b128 v[178:181], v131 offset:51200
	global_load_lds_dwordx4 v[184:185], off
	s_mov_b32 m0, s74
	s_waitcnt lgkmcnt(0)
	v_mfma_f32_16x16x32_bf16 v[28:31], v[146:149], v[154:157], v[28:31]
	global_load_lds_dwordx4 v[186:187], off
	s_mov_b32 m0, s75
	v_mfma_f32_16x16x32_bf16 v[24:27], v[150:153], v[154:157], v[24:27]
	global_load_lds_dwordx4 v[126:127], off
	s_mov_b32 m0, s76
	v_mfma_f32_16x16x32_bf16 v[20:23], v[162:165], v[154:157], v[20:23]
	global_load_lds_dwordx4 v[182:183], off
	s_mov_b32 m0, s77
	v_mfma_f32_16x16x32_bf16 v[16:19], v[170:173], v[154:157], v[16:19]
	global_load_lds_dwordx4 v[188:189], off
	s_mov_b32 m0, s84
	v_mfma_f32_16x16x32_bf16 v[12:15], v[146:149], v[174:177], v[12:15]
	global_load_lds_dwordx4 v[190:191], off
	s_mov_b32 m0, s85
	v_mfma_f32_16x16x32_bf16 v[4:7], v[150:153], v[174:177], v[4:7]
	global_load_lds_dwordx4 v[166:167], off
	ds_read_b128 v[146:149], v130 offset:32768
	ds_read_b128 v[150:153], v130 offset:34816
	v_mfma_f32_16x16x32_bf16 v[0:3], v[162:165], v[174:177], v[0:3]
	ds_read_b128 v[154:157], v131 offset:53248
	ds_read_b128 v[162:165], v131 offset:55296
	s_waitcnt lgkmcnt(0)
	v_mfma_f32_16x16x32_bf16 v[60:63], v[158:161], v[146:149], v[60:63]
	v_mfma_f32_16x16x32_bf16 v[56:59], v[178:181], v[146:149], v[56:59]
	v_mfma_f32_16x16x32_bf16 v[52:55], v[154:157], v[146:149], v[52:55]
	v_mfma_f32_16x16x32_bf16 v[48:51], v[162:165], v[146:149], v[48:51]
	v_mfma_f32_16x16x32_bf16 v[44:47], v[158:161], v[150:153], v[44:47]
	v_mfma_f32_16x16x32_bf16 v[40:43], v[178:181], v[150:153], v[40:43]
	v_mfma_f32_16x16x32_bf16 v[36:39], v[154:157], v[150:153], v[36:39]
	v_mfma_f32_16x16x32_bf16 v[32:35], v[162:165], v[150:153], v[32:35]
	ds_read_b128 v[146:149], v130 offset:36864
	ds_read_b128 v[150:153], v130 offset:38912
	v_mfma_f32_16x16x32_bf16 v[8:11], v[170:173], v[174:177], v[8:11]
	s_waitcnt lgkmcnt(0)
	v_mfma_f32_16x16x32_bf16 v[28:31], v[158:161], v[146:149], v[28:31]
	v_mfma_f32_16x16x32_bf16 v[24:27], v[178:181], v[146:149], v[24:27]
	v_mfma_f32_16x16x32_bf16 v[20:23], v[154:157], v[146:149], v[20:23]
	v_mfma_f32_16x16x32_bf16 v[16:19], v[162:165], v[146:149], v[16:19]
	v_mfma_f32_16x16x32_bf16 v[12:15], v[158:161], v[150:153], v[12:15]
	v_mfma_f32_16x16x32_bf16 v[4:7], v[178:181], v[150:153], v[4:7]
	v_mfma_f32_16x16x32_bf16 v[0:3], v[154:157], v[150:153], v[0:3]
	ds_read_b128 v[146:149], v133 offset:49152
	ds_read_b128 v[154:157], v133 offset:51200
	v_mfma_f32_16x16x32_bf16 v[8:11], v[162:165], v[150:153], v[8:11]
	ds_read_b128 v[150:153], v132 offset:32768
	ds_read_b128 v[158:161], v132 offset:34816
	ds_read_b128 v[162:165], v133 offset:53248
	ds_read_b128 v[170:173], v133 offset:55296
	s_waitcnt lgkmcnt(0)
	v_mfma_f32_16x16x32_bf16 v[60:63], v[146:149], v[150:153], v[60:63]
	v_mfma_f32_16x16x32_bf16 v[56:59], v[154:157], v[150:153], v[56:59]
	v_mfma_f32_16x16x32_bf16 v[52:55], v[162:165], v[150:153], v[52:55]
	v_mfma_f32_16x16x32_bf16 v[48:51], v[170:173], v[150:153], v[48:51]
	v_mfma_f32_16x16x32_bf16 v[44:47], v[146:149], v[158:161], v[44:47]
	v_mfma_f32_16x16x32_bf16 v[40:43], v[154:157], v[158:161], v[40:43]
	v_mfma_f32_16x16x32_bf16 v[36:39], v[162:165], v[158:161], v[36:39]
	v_mfma_f32_16x16x32_bf16 v[32:35], v[170:173], v[158:161], v[32:35]
	ds_read_b128 v[150:153], v132 offset:36864
	ds_read_b128 v[158:161], v132 offset:38912
	s_waitcnt lgkmcnt(0)
	v_mfma_f32_16x16x32_bf16 v[28:31], v[146:149], v[150:153], v[28:31]
	v_mfma_f32_16x16x32_bf16 v[24:27], v[154:157], v[150:153], v[24:27]
	v_mfma_f32_16x16x32_bf16 v[20:23], v[162:165], v[150:153], v[20:23]
	v_mfma_f32_16x16x32_bf16 v[16:19], v[170:173], v[150:153], v[16:19]
	v_mfma_f32_16x16x32_bf16 v[12:15], v[146:149], v[158:161], v[12:15]
	v_mfma_f32_16x16x32_bf16 v[4:7], v[154:157], v[158:161], v[4:7]
	v_mfma_f32_16x16x32_bf16 v[0:3], v[162:165], v[158:161], v[0:3]
	v_mfma_f32_16x16x32_bf16 v[8:11], v[170:173], v[158:161], v[8:11]
	s_cbranch_scc1 .LBB0_469
	v_readfirstlane_b32 s71, v92
	s_waitcnt vmcnt(0) lgkmcnt(0)
	s_barrier
	v_lshl_add_u64 v[88:89], v[86:87], 0, s[40:41]
	s_mov_b32 m0, s71
	v_readfirstlane_b32 s71, v93
	global_load_lds_dwordx4 v[88:89], off
	v_lshl_add_u64 v[88:89], v[86:87], 0, s[42:43]
	s_mov_b32 m0, s71
	v_readfirstlane_b32 s71, v94
	global_load_lds_dwordx4 v[88:89], off
	v_lshl_add_u64 v[88:89], v[86:87], 0, s[44:45]
	s_mov_b32 m0, s71
	v_readfirstlane_b32 s71, v95
	global_load_lds_dwordx4 v[88:89], off
	v_lshl_add_u64 v[86:87], v[86:87], 0, s[48:49]
	s_mov_b32 m0, s71
	v_readfirstlane_b32 s71, v122
	v_lshl_add_u64 v[90:91], v[84:85], 0, s[40:41]
	global_load_lds_dwordx4 v[86:87], off
	s_mov_b32 m0, s71
	v_readfirstlane_b32 s71, v123
	global_load_lds_dwordx4 v[90:91], off
	v_lshl_add_u64 v[86:87], v[84:85], 0, s[42:43]
	s_mov_b32 m0, s71
	v_readfirstlane_b32 s71, v124
	global_load_lds_dwordx4 v[86:87], off
	v_lshl_add_u64 v[90:91], v[84:85], 0, s[44:45]
	s_mov_b32 m0, s71
	ds_read_b128 v[86:89], v131 offset:16384
	global_load_lds_dwordx4 v[90:91], off
	ds_read_b128 v[146:149], v131 offset:18432
	ds_read_b128 v[150:153], v130
	ds_read_b128 v[154:157], v130 offset:2048
	ds_read_b128 v[158:161], v131 offset:20480
	ds_read_b128 v[162:165], v131 offset:22528
	v_readfirstlane_b32 s71, v125
	v_lshl_add_u64 v[84:85], v[84:85], 0, s[48:49]
	s_mov_b32 m0, s71
	s_waitcnt lgkmcnt(0)
	v_mfma_f32_16x16x32_bf16 v[60:63], v[86:89], v[150:153], v[60:63]
	global_load_lds_dwordx4 v[84:85], off
	v_readfirstlane_b32 s71, v129
	v_mfma_f32_16x16x32_bf16 v[56:59], v[146:149], v[150:153], v[56:59]
	s_mov_b32 m0, s71
	v_readfirstlane_b32 s71, v135
	s_add_i32 s72, s83, 0x1c80
	v_mfma_f32_16x16x32_bf16 v[52:55], v[158:161], v[150:153], v[52:55]
	s_ashr_i32 s73, s72, 31
	s_lshl_b64 s[72:73], s[72:73], 11
	s_and_b64 vcc, exec, s[6:7]
	v_mfma_f32_16x16x32_bf16 v[48:51], v[162:165], v[150:153], v[48:51]
	v_mfma_f32_16x16x32_bf16 v[44:47], v[86:89], v[154:157], v[44:47]
	v_mfma_f32_16x16x32_bf16 v[40:43], v[146:149], v[154:157], v[40:43]
	v_mfma_f32_16x16x32_bf16 v[36:39], v[158:161], v[154:157], v[36:39]
	v_mfma_f32_16x16x32_bf16 v[32:35], v[162:165], v[154:157], v[32:35]
	ds_read_b128 v[150:153], v130 offset:4096
	ds_read_b128 v[154:157], v130 offset:6144
	s_waitcnt lgkmcnt(0)
	v_mfma_f32_16x16x32_bf16 v[28:31], v[86:89], v[150:153], v[28:31]
	v_mfma_f32_16x16x32_bf16 v[24:27], v[146:149], v[150:153], v[24:27]
	v_mfma_f32_16x16x32_bf16 v[20:23], v[158:161], v[150:153], v[20:23]
	v_mfma_f32_16x16x32_bf16 v[16:19], v[162:165], v[150:153], v[16:19]
	v_mfma_f32_16x16x32_bf16 v[12:15], v[86:89], v[154:157], v[12:15]
	ds_read_b128 v[84:87], v133 offset:16384
	v_mfma_f32_16x16x32_bf16 v[4:7], v[146:149], v[154:157], v[4:7]
	ds_read_b128 v[88:91], v133 offset:18432
	ds_read_b128 v[146:149], v132
	ds_read_b128 v[150:153], v132 offset:2048
	v_mfma_f32_16x16x32_bf16 v[0:3], v[158:161], v[154:157], v[0:3]
	ds_read_b128 v[158:161], v133 offset:22528
	v_mfma_f32_16x16x32_bf16 v[8:11], v[162:165], v[154:157], v[8:11]
	ds_read_b128 v[154:157], v133 offset:20480
	s_waitcnt lgkmcnt(0)
	v_mfma_f32_16x16x32_bf16 v[60:63], v[84:87], v[146:149], v[60:63]
	v_mfma_f32_16x16x32_bf16 v[56:59], v[88:91], v[146:149], v[56:59]
	v_mfma_f32_16x16x32_bf16 v[52:55], v[154:157], v[146:149], v[52:55]
	v_mfma_f32_16x16x32_bf16 v[48:51], v[158:161], v[146:149], v[48:51]
	ds_read_b128 v[146:149], v132 offset:4096
	ds_read_b128 v[162:165], v132 offset:6144
	s_waitcnt vmcnt(0) lgkmcnt(0)
	s_barrier
	ds_read_b128 v[170:173], v130 offset:32768
	ds_read_b128 v[174:177], v130 offset:34816
	ds_read_b128 v[178:181], v131 offset:49152
	ds_read_b128 v[182:185], v130 offset:36864
	ds_read_b128 v[186:189], v130 offset:38912
	ds_read_b128 v[190:193], v131 offset:51200
	ds_read_b128 v[194:197], v133 offset:49152
	v_mfma_f32_16x16x32_bf16 v[44:47], v[84:87], v[150:153], v[44:47]
	v_mfma_f32_16x16x32_bf16 v[40:43], v[88:91], v[150:153], v[40:43]
	v_mfma_f32_16x16x32_bf16 v[36:39], v[154:157], v[150:153], v[36:39]
	v_mfma_f32_16x16x32_bf16 v[32:35], v[158:161], v[150:153], v[32:35]
	ds_read_b128 v[150:153], v131 offset:53248
	ds_read_b128 v[198:201], v131 offset:55296
	ds_read_b128 v[202:205], v132 offset:32768
	ds_read_b128 v[206:209], v132 offset:34816
	ds_read_b128 v[210:213], v132 offset:36864
	ds_read_b128 v[214:217], v132 offset:38912
	ds_read_b128 v[218:221], v133 offset:51200
	ds_read_b128 v[222:225], v133 offset:53248
	ds_read_b128 v[226:229], v133 offset:55296
	s_waitcnt lgkmcnt(0)
	v_mfma_f32_16x16x32_bf16 v[60:63], v[178:181], v[170:173], v[60:63]
	s_waitcnt lgkmcnt(0)
	v_mfma_f32_16x16x32_bf16 v[60:63], v[194:197], v[202:205], v[60:63]
	v_mfma_f32_16x16x32_bf16 v[56:59], v[190:193], v[170:173], v[56:59]
	v_mfma_f32_16x16x32_bf16 v[56:59], v[218:221], v[202:205], v[56:59]
	s_nop 5
	v_and_b32_sdwa v126, v62, v142 dst_sel:DWORD dst_unused:UNUSED_PAD src0_sel:WORD_1 src1_sel:DWORD
	v_and_b32_sdwa v127, v60, v142 dst_sel:DWORD dst_unused:UNUSED_PAD src0_sel:WORD_1 src1_sel:DWORD
	v_add3_u32 v62, v62, v126, s3
	v_mfma_f32_16x16x32_bf16 v[52:55], v[150:153], v[170:173], v[52:55]
	v_and_b32_sdwa v126, v63, v142 dst_sel:DWORD dst_unused:UNUSED_PAD src0_sel:WORD_1 src1_sel:DWORD
	v_add3_u32 v60, v60, v127, s3
	v_and_b32_sdwa v127, v61, v142 dst_sel:DWORD dst_unused:UNUSED_PAD src0_sel:WORD_1 src1_sel:DWORD
	v_add3_u32 v63, v63, v126, s3
	v_add3_u32 v61, v61, v127, s3
	v_and_b32_e32 v63, 0xffff0000, v63
	v_and_b32_e32 v126, 0xffff0000, v61
	v_or_b32_sdwa v61, v63, v62 dst_sel:DWORD dst_unused:UNUSED_PAD src0_sel:DWORD src1_sel:WORD_1
	v_and_b32_sdwa v63, v56, v142 dst_sel:DWORD dst_unused:UNUSED_PAD src0_sel:WORD_1 src1_sel:DWORD
	v_mfma_f32_16x16x32_bf16 v[52:55], v[222:225], v[202:205], v[52:55]
	v_add3_u32 v56, v56, v63, s3
	v_and_b32_sdwa v63, v57, v142 dst_sel:DWORD dst_unused:UNUSED_PAD src0_sel:WORD_1 src1_sel:DWORD
	v_and_b32_sdwa v62, v58, v142 dst_sel:DWORD dst_unused:UNUSED_PAD src0_sel:WORD_1 src1_sel:DWORD
	v_mfma_f32_16x16x32_bf16 v[48:51], v[198:201], v[170:173], v[48:51]
	v_add3_u32 v57, v57, v63, s3
	v_add3_u32 v58, v58, v62, s3
	v_and_b32_sdwa v62, v59, v142 dst_sel:DWORD dst_unused:UNUSED_PAD src0_sel:WORD_1 src1_sel:DWORD
	v_and_b32_e32 v57, 0xffff0000, v57
	v_add3_u32 v59, v59, v62, s3
	v_or_b32_sdwa v62, v57, v56 dst_sel:DWORD dst_unused:UNUSED_PAD src0_sel:DWORD src1_sel:WORD_1
	v_and_b32_sdwa v56, v54, v142 dst_sel:DWORD dst_unused:UNUSED_PAD src0_sel:WORD_1 src1_sel:DWORD
	v_mfma_f32_16x16x32_bf16 v[48:51], v[226:229], v[202:205], v[48:51]
	v_and_b32_sdwa v57, v52, v142 dst_sel:DWORD dst_unused:UNUSED_PAD src0_sel:WORD_1 src1_sel:DWORD
	v_add3_u32 v54, v54, v56, s3
	v_and_b32_sdwa v56, v55, v142 dst_sel:DWORD dst_unused:UNUSED_PAD src0_sel:WORD_1 src1_sel:DWORD
	v_mfma_f32_16x16x32_bf16 v[44:47], v[178:181], v[174:177], v[44:47]
	v_add3_u32 v52, v52, v57, s3
	v_and_b32_sdwa v57, v53, v142 dst_sel:DWORD dst_unused:UNUSED_PAD src0_sel:WORD_1 src1_sel:DWORD
	v_add3_u32 v55, v55, v56, s3
	v_add3_u32 v53, v53, v57, s3
	v_and_b32_e32 v55, 0xffff0000, v55
	v_and_b32_e32 v56, 0xffff0000, v53
	v_or_b32_sdwa v53, v55, v54 dst_sel:DWORD dst_unused:UNUSED_PAD src0_sel:DWORD src1_sel:WORD_1
	v_and_b32_sdwa v55, v48, v142 dst_sel:DWORD dst_unused:UNUSED_PAD src0_sel:WORD_1 src1_sel:DWORD
	v_mfma_f32_16x16x32_bf16 v[40:43], v[190:193], v[174:177], v[40:43]
	v_add3_u32 v48, v48, v55, s3
	v_and_b32_sdwa v55, v49, v142 dst_sel:DWORD dst_unused:UNUSED_PAD src0_sel:WORD_1 src1_sel:DWORD
	v_and_b32_sdwa v54, v50, v142 dst_sel:DWORD dst_unused:UNUSED_PAD src0_sel:WORD_1 src1_sel:DWORD
	v_mfma_f32_16x16x32_bf16 v[44:47], v[194:197], v[206:209], v[44:47]
	v_add3_u32 v49, v49, v55, s3
	v_add3_u32 v50, v50, v54, s3
	v_and_b32_sdwa v54, v51, v142 dst_sel:DWORD dst_unused:UNUSED_PAD src0_sel:WORD_1 src1_sel:DWORD
	v_and_b32_e32 v49, 0xffff0000, v49
	v_add3_u32 v51, v51, v54, s3
	v_or_b32_sdwa v54, v49, v48 dst_sel:DWORD dst_unused:UNUSED_PAD src0_sel:DWORD src1_sel:WORD_1
	s_nop 1
	v_and_b32_sdwa v48, v46, v142 dst_sel:DWORD dst_unused:UNUSED_PAD src0_sel:WORD_1 src1_sel:DWORD
	v_mfma_f32_16x16x32_bf16 v[36:39], v[150:153], v[174:177], v[36:39]
	v_and_b32_sdwa v49, v44, v142 dst_sel:DWORD dst_unused:UNUSED_PAD src0_sel:WORD_1 src1_sel:DWORD
	v_add3_u32 v46, v46, v48, s3
	v_and_b32_sdwa v48, v47, v142 dst_sel:DWORD dst_unused:UNUSED_PAD src0_sel:WORD_1 src1_sel:DWORD
	v_mfma_f32_16x16x32_bf16 v[40:43], v[218:221], v[206:209], v[40:43]
	v_add3_u32 v44, v44, v49, s3
	v_and_b32_sdwa v49, v45, v142 dst_sel:DWORD dst_unused:UNUSED_PAD src0_sel:WORD_1 src1_sel:DWORD
	v_add3_u32 v47, v47, v48, s3
	v_add3_u32 v45, v45, v49, s3
	v_and_b32_e32 v47, 0xffff0000, v47
	v_mfma_f32_16x16x32_bf16 v[28:31], v[84:87], v[146:149], v[28:31]
	v_and_b32_e32 v48, 0xffff0000, v45
	v_or_b32_sdwa v45, v47, v46 dst_sel:DWORD dst_unused:UNUSED_PAD src0_sel:DWORD src1_sel:WORD_1
	v_and_b32_sdwa v47, v40, v142 dst_sel:DWORD dst_unused:UNUSED_PAD src0_sel:WORD_1 src1_sel:DWORD
	v_mfma_f32_16x16x32_bf16 v[32:35], v[198:201], v[174:177], v[32:35]
	v_add3_u32 v40, v40, v47, s3
	v_and_b32_sdwa v47, v41, v142 dst_sel:DWORD dst_unused:UNUSED_PAD src0_sel:WORD_1 src1_sel:DWORD
	v_and_b32_sdwa v46, v42, v142 dst_sel:DWORD dst_unused:UNUSED_PAD src0_sel:WORD_1 src1_sel:DWORD
	v_mfma_f32_16x16x32_bf16 v[36:39], v[222:225], v[206:209], v[36:39]
	v_add3_u32 v41, v41, v47, s3
	v_add3_u32 v42, v42, v46, s3
	v_and_b32_sdwa v46, v43, v142 dst_sel:DWORD dst_unused:UNUSED_PAD src0_sel:WORD_1 src1_sel:DWORD
	v_and_b32_e32 v41, 0xffff0000, v41
	v_mfma_f32_16x16x32_bf16 v[24:27], v[88:91], v[146:149], v[24:27]
	v_add3_u32 v43, v43, v46, s3
	v_or_b32_sdwa v46, v41, v40 dst_sel:DWORD dst_unused:UNUSED_PAD src0_sel:DWORD src1_sel:WORD_1
	s_nop 0
	v_and_b32_sdwa v40, v38, v142 dst_sel:DWORD dst_unused:UNUSED_PAD src0_sel:WORD_1 src1_sel:DWORD
	v_mfma_f32_16x16x32_bf16 v[28:31], v[178:181], v[182:185], v[28:31]
	v_and_b32_sdwa v41, v36, v142 dst_sel:DWORD dst_unused:UNUSED_PAD src0_sel:WORD_1 src1_sel:DWORD
	v_add3_u32 v38, v38, v40, s3
	v_and_b32_sdwa v40, v39, v142 dst_sel:DWORD dst_unused:UNUSED_PAD src0_sel:WORD_1 src1_sel:DWORD
	v_mfma_f32_16x16x32_bf16 v[32:35], v[226:229], v[206:209], v[32:35]
	v_add3_u32 v36, v36, v41, s3
	v_and_b32_sdwa v41, v37, v142 dst_sel:DWORD dst_unused:UNUSED_PAD src0_sel:WORD_1 src1_sel:DWORD
	v_add3_u32 v39, v39, v40, s3
	v_add3_u32 v37, v37, v41, s3
	v_and_b32_e32 v39, 0xffff0000, v39
	v_mfma_f32_16x16x32_bf16 v[20:23], v[154:157], v[146:149], v[20:23]
	v_and_b32_e32 v40, 0xffff0000, v37
	v_or_b32_sdwa v37, v39, v38 dst_sel:DWORD dst_unused:UNUSED_PAD src0_sel:DWORD src1_sel:WORD_1
	v_and_b32_sdwa v39, v32, v142 dst_sel:DWORD dst_unused:UNUSED_PAD src0_sel:WORD_1 src1_sel:DWORD
	v_mfma_f32_16x16x32_bf16 v[24:27], v[190:193], v[182:185], v[24:27]
	v_add3_u32 v32, v32, v39, s3
	v_and_b32_sdwa v39, v33, v142 dst_sel:DWORD dst_unused:UNUSED_PAD src0_sel:WORD_1 src1_sel:DWORD
	v_and_b32_sdwa v38, v34, v142 dst_sel:DWORD dst_unused:UNUSED_PAD src0_sel:WORD_1 src1_sel:DWORD
	v_mfma_f32_16x16x32_bf16 v[28:31], v[194:197], v[210:213], v[28:31]
	v_add3_u32 v33, v33, v39, s3
	v_add3_u32 v34, v34, v38, s3
	v_and_b32_sdwa v38, v35, v142 dst_sel:DWORD dst_unused:UNUSED_PAD src0_sel:WORD_1 src1_sel:DWORD
	v_and_b32_e32 v33, 0xffff0000, v33
	v_mfma_f32_16x16x32_bf16 v[16:19], v[158:161], v[146:149], v[16:19]
	v_add3_u32 v35, v35, v38, s3
	v_or_b32_sdwa v38, v33, v32 dst_sel:DWORD dst_unused:UNUSED_PAD src0_sel:DWORD src1_sel:WORD_1
	s_nop 0
	v_and_b32_sdwa v32, v30, v142 dst_sel:DWORD dst_unused:UNUSED_PAD src0_sel:WORD_1 src1_sel:DWORD
	v_mfma_f32_16x16x32_bf16 v[20:23], v[150:153], v[182:185], v[20:23]
	v_and_b32_sdwa v33, v28, v142 dst_sel:DWORD dst_unused:UNUSED_PAD src0_sel:WORD_1 src1_sel:DWORD
	v_add3_u32 v30, v30, v32, s3
	v_and_b32_sdwa v32, v31, v142 dst_sel:DWORD dst_unused:UNUSED_PAD src0_sel:WORD_1 src1_sel:DWORD
	v_mfma_f32_16x16x32_bf16 v[24:27], v[218:221], v[210:213], v[24:27]
	v_add3_u32 v28, v28, v33, s3
	v_and_b32_sdwa v33, v29, v142 dst_sel:DWORD dst_unused:UNUSED_PAD src0_sel:WORD_1 src1_sel:DWORD
	v_add3_u32 v31, v31, v32, s3
	v_add3_u32 v29, v29, v33, s3
	v_and_b32_e32 v31, 0xffff0000, v31
	v_mfma_f32_16x16x32_bf16 v[12:15], v[84:87], v[162:165], v[12:15]
	v_and_b32_e32 v32, 0xffff0000, v29
	v_or_b32_sdwa v29, v31, v30 dst_sel:DWORD dst_unused:UNUSED_PAD src0_sel:DWORD src1_sel:WORD_1
	v_and_b32_sdwa v31, v24, v142 dst_sel:DWORD dst_unused:UNUSED_PAD src0_sel:WORD_1 src1_sel:DWORD
	v_mfma_f32_16x16x32_bf16 v[16:19], v[198:201], v[182:185], v[16:19]
	v_add3_u32 v24, v24, v31, s3
	v_and_b32_sdwa v31, v25, v142 dst_sel:DWORD dst_unused:UNUSED_PAD src0_sel:WORD_1 src1_sel:DWORD
	v_and_b32_sdwa v30, v26, v142 dst_sel:DWORD dst_unused:UNUSED_PAD src0_sel:WORD_1 src1_sel:DWORD
	v_mfma_f32_16x16x32_bf16 v[20:23], v[222:225], v[210:213], v[20:23]
	v_add3_u32 v25, v25, v31, s3
	v_add3_u32 v26, v26, v30, s3
	v_and_b32_sdwa v30, v27, v142 dst_sel:DWORD dst_unused:UNUSED_PAD src0_sel:WORD_1 src1_sel:DWORD
	v_and_b32_e32 v25, 0xffff0000, v25
	v_mfma_f32_16x16x32_bf16 v[4:7], v[88:91], v[162:165], v[4:7]
	v_add3_u32 v27, v27, v30, s3
	v_or_b32_sdwa v30, v25, v24 dst_sel:DWORD dst_unused:UNUSED_PAD src0_sel:DWORD src1_sel:WORD_1
	s_nop 0
	v_and_b32_sdwa v24, v22, v142 dst_sel:DWORD dst_unused:UNUSED_PAD src0_sel:WORD_1 src1_sel:DWORD
	v_mfma_f32_16x16x32_bf16 v[12:15], v[178:181], v[186:189], v[12:15]
	v_and_b32_sdwa v25, v20, v142 dst_sel:DWORD dst_unused:UNUSED_PAD src0_sel:WORD_1 src1_sel:DWORD
	v_add3_u32 v22, v22, v24, s3
	v_and_b32_sdwa v24, v23, v142 dst_sel:DWORD dst_unused:UNUSED_PAD src0_sel:WORD_1 src1_sel:DWORD
	v_mfma_f32_16x16x32_bf16 v[16:19], v[226:229], v[210:213], v[16:19]
	v_add3_u32 v20, v20, v25, s3
	v_and_b32_sdwa v25, v21, v142 dst_sel:DWORD dst_unused:UNUSED_PAD src0_sel:WORD_1 src1_sel:DWORD
	v_add3_u32 v23, v23, v24, s3
	v_add3_u32 v21, v21, v25, s3
	v_and_b32_e32 v23, 0xffff0000, v23
	v_mfma_f32_16x16x32_bf16 v[0:3], v[154:157], v[162:165], v[0:3]
	v_and_b32_e32 v24, 0xffff0000, v21
	v_or_b32_sdwa v21, v23, v22 dst_sel:DWORD dst_unused:UNUSED_PAD src0_sel:DWORD src1_sel:WORD_1
	v_and_b32_sdwa v23, v16, v142 dst_sel:DWORD dst_unused:UNUSED_PAD src0_sel:WORD_1 src1_sel:DWORD
	v_mfma_f32_16x16x32_bf16 v[4:7], v[190:193], v[186:189], v[4:7]
	v_add3_u32 v16, v16, v23, s3
	v_and_b32_sdwa v23, v17, v142 dst_sel:DWORD dst_unused:UNUSED_PAD src0_sel:WORD_1 src1_sel:DWORD
	v_and_b32_sdwa v22, v18, v142 dst_sel:DWORD dst_unused:UNUSED_PAD src0_sel:WORD_1 src1_sel:DWORD
	v_mfma_f32_16x16x32_bf16 v[12:15], v[194:197], v[214:217], v[12:15]
	v_add3_u32 v17, v17, v23, s3
	v_add3_u32 v18, v18, v22, s3
	v_and_b32_sdwa v22, v19, v142 dst_sel:DWORD dst_unused:UNUSED_PAD src0_sel:WORD_1 src1_sel:DWORD
	v_and_b32_e32 v17, 0xffff0000, v17
	v_mfma_f32_16x16x32_bf16 v[8:11], v[158:161], v[162:165], v[8:11]
	v_add3_u32 v19, v19, v22, s3
	v_or_b32_sdwa v22, v17, v16 dst_sel:DWORD dst_unused:UNUSED_PAD src0_sel:DWORD src1_sel:WORD_1
	s_nop 0
	v_and_b32_sdwa v16, v14, v142 dst_sel:DWORD dst_unused:UNUSED_PAD src0_sel:WORD_1 src1_sel:DWORD
	v_mfma_f32_16x16x32_bf16 v[0:3], v[150:153], v[186:189], v[0:3]
	v_and_b32_sdwa v17, v12, v142 dst_sel:DWORD dst_unused:UNUSED_PAD src0_sel:WORD_1 src1_sel:DWORD
	v_add3_u32 v14, v14, v16, s3
	v_and_b32_sdwa v16, v15, v142 dst_sel:DWORD dst_unused:UNUSED_PAD src0_sel:WORD_1 src1_sel:DWORD
	v_mfma_f32_16x16x32_bf16 v[4:7], v[218:221], v[214:217], v[4:7]
	v_add3_u32 v12, v12, v17, s3
	v_and_b32_sdwa v17, v13, v142 dst_sel:DWORD dst_unused:UNUSED_PAD src0_sel:WORD_1 src1_sel:DWORD
	v_add3_u32 v15, v15, v16, s3
	v_add3_u32 v13, v13, v17, s3
	v_and_b32_e32 v15, 0xffff0000, v15
	v_mfma_f32_16x16x32_bf16 v[8:11], v[198:201], v[186:189], v[8:11]
	v_and_b32_e32 v16, 0xffff0000, v13
	v_or_b32_sdwa v13, v15, v14 dst_sel:DWORD dst_unused:UNUSED_PAD src0_sel:DWORD src1_sel:WORD_1
	v_and_b32_sdwa v15, v4, v142 dst_sel:DWORD dst_unused:UNUSED_PAD src0_sel:WORD_1 src1_sel:DWORD
	v_mfma_f32_16x16x32_bf16 v[0:3], v[222:225], v[214:217], v[0:3]
	v_add3_u32 v4, v4, v15, s3
	v_and_b32_sdwa v15, v5, v142 dst_sel:DWORD dst_unused:UNUSED_PAD src0_sel:WORD_1 src1_sel:DWORD
	v_and_b32_sdwa v14, v6, v142 dst_sel:DWORD dst_unused:UNUSED_PAD src0_sel:WORD_1 src1_sel:DWORD
	v_add3_u32 v5, v5, v15, s3
	v_add3_u32 v6, v6, v14, s3
	v_and_b32_sdwa v14, v7, v142 dst_sel:DWORD dst_unused:UNUSED_PAD src0_sel:WORD_1 src1_sel:DWORD
	v_and_b32_e32 v5, 0xffff0000, v5
	v_mfma_f32_16x16x32_bf16 v[8:11], v[226:229], v[214:217], v[8:11]
	v_add3_u32 v7, v7, v14, s3
	v_or_b32_sdwa v14, v5, v4 dst_sel:DWORD dst_unused:UNUSED_PAD src0_sel:DWORD src1_sel:WORD_1
	v_and_b32_sdwa v4, v2, v142 dst_sel:DWORD dst_unused:UNUSED_PAD src0_sel:WORD_1 src1_sel:DWORD
	v_and_b32_sdwa v5, v0, v142 dst_sel:DWORD dst_unused:UNUSED_PAD src0_sel:WORD_1 src1_sel:DWORD
	v_add3_u32 v2, v2, v4, s3
	v_and_b32_sdwa v4, v3, v142 dst_sel:DWORD dst_unused:UNUSED_PAD src0_sel:WORD_1 src1_sel:DWORD
	v_add3_u32 v0, v0, v5, s3
	v_and_b32_sdwa v5, v1, v142 dst_sel:DWORD dst_unused:UNUSED_PAD src0_sel:WORD_1 src1_sel:DWORD
	v_add3_u32 v3, v3, v4, s3
	v_add3_u32 v1, v1, v5, s3
	v_and_b32_e32 v3, 0xffff0000, v3
	v_and_b32_e32 v4, 0xffff0000, v1
	v_or_b32_sdwa v1, v3, v2 dst_sel:DWORD dst_unused:UNUSED_PAD src0_sel:DWORD src1_sel:WORD_1
	v_and_b32_sdwa v3, v8, v142 dst_sel:DWORD dst_unused:UNUSED_PAD src0_sel:WORD_1 src1_sel:DWORD
	v_or_b32_sdwa v0, v4, v0 dst_sel:DWORD dst_unused:UNUSED_PAD src0_sel:DWORD src1_sel:WORD_1
	v_add3_u32 v4, v8, v3, s3
	v_and_b32_sdwa v3, v11, v142 dst_sel:DWORD dst_unused:UNUSED_PAD src0_sel:WORD_1 src1_sel:DWORD
	v_and_b32_sdwa v5, v9, v142 dst_sel:DWORD dst_unused:UNUSED_PAD src0_sel:WORD_1 src1_sel:DWORD
	v_and_b32_sdwa v2, v10, v142 dst_sel:DWORD dst_unused:UNUSED_PAD src0_sel:WORD_1 src1_sel:DWORD
	v_add3_u32 v3, v11, v3, s3
	v_add3_u32 v5, v9, v5, s3
	v_and_b32_e32 v59, 0xffff0000, v59
	v_and_b32_e32 v51, 0xffff0000, v51
	v_and_b32_e32 v43, 0xffff0000, v43
	v_and_b32_e32 v35, 0xffff0000, v35
	v_and_b32_e32 v27, 0xffff0000, v27
	v_and_b32_e32 v19, 0xffff0000, v19
	v_and_b32_e32 v7, 0xffff0000, v7
	v_add3_u32 v2, v10, v2, s3
	v_and_b32_e32 v3, 0xffff0000, v3
	v_and_b32_e32 v5, 0xffff0000, v5
	v_or_b32_sdwa v60, v126, v60 dst_sel:DWORD dst_unused:UNUSED_PAD src0_sel:DWORD src1_sel:WORD_1
	v_or_b32_sdwa v63, v59, v58 dst_sel:DWORD dst_unused:UNUSED_PAD src0_sel:DWORD src1_sel:WORD_1
	v_or_b32_sdwa v52, v56, v52 dst_sel:DWORD dst_unused:UNUSED_PAD src0_sel:DWORD src1_sel:WORD_1
	v_or_b32_sdwa v55, v51, v50 dst_sel:DWORD dst_unused:UNUSED_PAD src0_sel:DWORD src1_sel:WORD_1
	v_or_b32_sdwa v44, v48, v44 dst_sel:DWORD dst_unused:UNUSED_PAD src0_sel:DWORD src1_sel:WORD_1
	v_or_b32_sdwa v47, v43, v42 dst_sel:DWORD dst_unused:UNUSED_PAD src0_sel:DWORD src1_sel:WORD_1
	v_or_b32_sdwa v36, v40, v36 dst_sel:DWORD dst_unused:UNUSED_PAD src0_sel:DWORD src1_sel:WORD_1
	v_or_b32_sdwa v39, v35, v34 dst_sel:DWORD dst_unused:UNUSED_PAD src0_sel:DWORD src1_sel:WORD_1
	v_or_b32_sdwa v28, v32, v28 dst_sel:DWORD dst_unused:UNUSED_PAD src0_sel:DWORD src1_sel:WORD_1
	v_or_b32_sdwa v31, v27, v26 dst_sel:DWORD dst_unused:UNUSED_PAD src0_sel:DWORD src1_sel:WORD_1
	v_or_b32_sdwa v20, v24, v20 dst_sel:DWORD dst_unused:UNUSED_PAD src0_sel:DWORD src1_sel:WORD_1
	v_or_b32_sdwa v23, v19, v18 dst_sel:DWORD dst_unused:UNUSED_PAD src0_sel:DWORD src1_sel:WORD_1
	v_or_b32_sdwa v12, v16, v12 dst_sel:DWORD dst_unused:UNUSED_PAD src0_sel:DWORD src1_sel:WORD_1
	v_or_b32_sdwa v15, v7, v6 dst_sel:DWORD dst_unused:UNUSED_PAD src0_sel:DWORD src1_sel:WORD_1
	v_or_b32_sdwa v3, v3, v2 dst_sel:DWORD dst_unused:UNUSED_PAD src0_sel:DWORD src1_sel:WORD_1
	v_or_b32_sdwa v2, v5, v4 dst_sel:DWORD dst_unused:UNUSED_PAD src0_sel:DWORD src1_sel:WORD_1
	global_store_dwordx4 v[98:99], v[60:63], off offset:1024
	global_store_dwordx4 v[98:99], v[52:55], off offset:1152
	global_store_dwordx4 v[98:99], v[44:47], off offset:1280
	global_store_dwordx4 v[98:99], v[36:39], off offset:1408
	global_store_dwordx4 v[98:99], v[28:31], off offset:1536
	global_store_dwordx4 v[98:99], v[20:23], off offset:1664
	global_store_dwordx4 v[98:99], v[12:15], off offset:1792
	global_store_dwordx4 v[98:99], v[0:3], off offset:1920
	s_waitcnt vmcnt(0)
	s_barrier
	global_load_lds_dwordx4 v[68:69], off
	s_mov_b32 m0, s71
	v_readfirstlane_b32 s71, v136
	global_load_lds_dwordx4 v[70:71], off
	s_mov_b32 m0, s71
	v_readfirstlane_b32 s71, v137
	global_load_lds_dwordx4 v[72:73], off
	s_mov_b32 m0, s71
	v_readfirstlane_b32 s71, v138
	v_lshl_add_u64 v[84:85], v[108:109], 0, s[72:73]
	global_load_lds_dwordx4 v[74:75], off
	s_mov_b32 m0, s71
	v_readfirstlane_b32 s71, v139
	global_load_lds_dwordx4 v[84:85], off
	v_lshl_add_u64 v[0:1], v[84:85], 0, s[10:11]
	s_mov_b32 m0, s71
	v_readfirstlane_b32 s71, v140
	global_load_lds_dwordx4 v[0:1], off
	v_lshl_add_u64 v[0:1], v[84:85], 0, s[12:13]
	s_mov_b32 m0, s71
	v_readfirstlane_b32 s71, v141
	global_load_lds_dwordx4 v[0:1], off
	v_lshl_add_u64 v[0:1], v[84:85], 0, s[14:15]
	s_mov_b32 m0, s71
	s_nop 0
	global_load_lds_dwordx4 v[0:1], off
	s_cbranch_vccnz .LBB0_472
	s_sleep 8

.LBB0_473:
	v_lshl_add_u64 v[74:75], v[64:65], 0, v[96:97]
	v_readfirstlane_b32 s72, v92
	s_waitcnt vmcnt(0) lgkmcnt(0)
	s_barrier
	v_readfirstlane_b32 s73, v93
	v_lshl_add_u64 v[126:127], v[74:75], 0, s[18:19]
	s_mov_b32 m0, s72
	v_readfirstlane_b32 s74, v94
	v_lshl_add_u64 v[148:149], v[74:75], 0, s[24:25]
	ds_read_b128 v[70:73], v131 offset:16384
	ds_read_b128 v[86:89], v131 offset:18432
	global_load_lds_dwordx4 v[126:127], off
	s_mov_b32 m0, s73
	v_readfirstlane_b32 s75, v95
	v_lshl_add_u64 v[150:151], v[74:75], 0, s[26:27]
	global_load_lds_dwordx4 v[148:149], off
	s_mov_b32 m0, s74
	v_lshl_add_u64 v[90:91], v[68:69], 0, v[96:97]
	v_readfirstlane_b32 s76, v122
	v_lshl_add_u64 v[152:153], v[74:75], 0, s[28:29]
	global_load_lds_dwordx4 v[150:151], off
	s_mov_b32 m0, s75
	v_readfirstlane_b32 s77, v123
	v_lshl_add_u64 v[146:147], v[90:91], 0, s[18:19]
	global_load_lds_dwordx4 v[152:153], off
	s_mov_b32 m0, s76
	v_readfirstlane_b32 s83, v124
	v_lshl_add_u64 v[154:155], v[90:91], 0, s[24:25]
	global_load_lds_dwordx4 v[146:147], off
	s_mov_b32 m0, s77
	v_lshl_add_u64 v[156:157], v[90:91], 0, s[26:27]
	global_load_lds_dwordx4 v[154:155], off
	s_mov_b32 m0, s83
	v_readfirstlane_b32 s72, v125
	global_load_lds_dwordx4 v[156:157], off
	ds_read_b128 v[146:149], v130
	ds_read_b128 v[150:153], v130 offset:2048
	ds_read_b128 v[154:157], v131 offset:20480
	ds_read_b128 v[158:161], v131 offset:22528
	v_lshl_add_u64 v[126:127], v[90:91], 0, s[28:29]
	s_mov_b32 m0, s72
	s_waitcnt lgkmcnt(0)
	v_mfma_f32_16x16x32_bf16 v[60:63], v[70:73], v[146:149], v[60:63]
	global_load_lds_dwordx4 v[126:127], off
	v_readfirstlane_b32 s72, v129
	v_mfma_f32_16x16x32_bf16 v[56:59], v[86:89], v[146:149], v[56:59]
	v_readfirstlane_b32 s73, v135
	v_lshl_add_u64 v[126:127], v[74:75], 0, s[30:31]
	s_mov_b32 m0, s72
	v_mfma_f32_16x16x32_bf16 v[52:55], v[154:157], v[146:149], v[52:55]
	v_readfirstlane_b32 s74, v136
	v_lshl_add_u64 v[174:175], v[74:75], 0, s[34:35]
	v_readfirstlane_b32 s75, v137
	v_mfma_f32_16x16x32_bf16 v[48:51], v[158:161], v[146:149], v[48:51]
	v_lshl_add_u64 v[176:177], v[74:75], 0, s[36:37]
	v_readfirstlane_b32 s76, v138
	v_lshl_add_u64 v[74:75], v[74:75], 0, s[38:39]
	v_mfma_f32_16x16x32_bf16 v[44:47], v[70:73], v[150:153], v[44:47]
	v_readfirstlane_b32 s77, v139
	v_lshl_add_u64 v[166:167], v[90:91], 0, s[30:31]
	v_readfirstlane_b32 s83, v140
	v_mfma_f32_16x16x32_bf16 v[40:43], v[86:89], v[150:153], v[40:43]
	v_lshl_add_u64 v[178:179], v[90:91], 0, s[34:35]
	v_readfirstlane_b32 s84, v141
	v_lshl_add_u64 v[180:181], v[90:91], 0, s[36:37]
	v_mfma_f32_16x16x32_bf16 v[36:39], v[154:157], v[150:153], v[36:39]
	v_lshl_add_u64 v[90:91], v[90:91], 0, s[38:39]
	s_add_i32 s71, s71, 2
	v_lshl_add_u64 v[68:69], v[68:69], 0, s[30:31]
	v_mfma_f32_16x16x32_bf16 v[32:35], v[158:161], v[150:153], v[32:35]
	ds_read_b128 v[146:149], v130 offset:4096
	ds_read_b128 v[150:153], v130 offset:6144
	s_cmp_lt_u32 s71, 12
	v_lshl_add_u64 v[64:65], v[64:65], 0, s[30:31]
	s_waitcnt lgkmcnt(0)
	v_mfma_f32_16x16x32_bf16 v[28:31], v[70:73], v[146:149], v[28:31]
	v_mfma_f32_16x16x32_bf16 v[24:27], v[86:89], v[146:149], v[24:27]
	v_mfma_f32_16x16x32_bf16 v[20:23], v[154:157], v[146:149], v[20:23]
	v_mfma_f32_16x16x32_bf16 v[16:19], v[158:161], v[146:149], v[16:19]
	v_mfma_f32_16x16x32_bf16 v[12:15], v[70:73], v[150:153], v[12:15]
	v_mfma_f32_16x16x32_bf16 v[4:7], v[86:89], v[150:153], v[4:7]
	ds_read_b128 v[70:73], v133 offset:16384
	ds_read_b128 v[86:89], v133 offset:18432
	v_mfma_f32_16x16x32_bf16 v[0:3], v[154:157], v[150:153], v[0:3]
	v_mfma_f32_16x16x32_bf16 v[8:11], v[158:161], v[150:153], v[8:11]
	ds_read_b128 v[146:149], v132
	ds_read_b128 v[150:153], v132 offset:2048
	ds_read_b128 v[154:157], v133 offset:20480
	ds_read_b128 v[158:161], v133 offset:22528
	s_waitcnt lgkmcnt(0)
	v_mfma_f32_16x16x32_bf16 v[60:63], v[70:73], v[146:149], v[60:63]
	v_mfma_f32_16x16x32_bf16 v[56:59], v[86:89], v[146:149], v[56:59]
	v_mfma_f32_16x16x32_bf16 v[52:55], v[154:157], v[146:149], v[52:55]
	v_mfma_f32_16x16x32_bf16 v[48:51], v[158:161], v[146:149], v[48:51]
	ds_read_b128 v[146:149], v132 offset:4096
	ds_read_b128 v[162:165], v132 offset:6144
	s_waitcnt vmcnt(0) lgkmcnt(0)
	s_barrier
	global_load_lds_dwordx4 v[126:127], off
	s_mov_b32 m0, s73
	v_mfma_f32_16x16x32_bf16 v[44:47], v[70:73], v[150:153], v[44:47]
	v_mfma_f32_16x16x32_bf16 v[40:43], v[86:89], v[150:153], v[40:43]
	v_mfma_f32_16x16x32_bf16 v[36:39], v[154:157], v[150:153], v[36:39]
	v_mfma_f32_16x16x32_bf16 v[32:35], v[158:161], v[150:153], v[32:35]
	ds_read_b128 v[150:153], v131 offset:49152
	ds_read_b128 v[170:173], v131 offset:51200
	global_load_lds_dwordx4 v[174:175], off
	s_mov_b32 m0, s74
	s_waitcnt lgkmcnt(0)
	v_mfma_f32_16x16x32_bf16 v[28:31], v[70:73], v[146:149], v[28:31]
	global_load_lds_dwordx4 v[176:177], off
	s_mov_b32 m0, s75
	v_mfma_f32_16x16x32_bf16 v[24:27], v[86:89], v[146:149], v[24:27]
	global_load_lds_dwordx4 v[74:75], off
	s_mov_b32 m0, s76
	v_mfma_f32_16x16x32_bf16 v[20:23], v[154:157], v[146:149], v[20:23]
	global_load_lds_dwordx4 v[166:167], off
	s_mov_b32 m0, s77
	v_mfma_f32_16x16x32_bf16 v[16:19], v[158:161], v[146:149], v[16:19]
	global_load_lds_dwordx4 v[178:179], off
	s_mov_b32 m0, s83
	v_mfma_f32_16x16x32_bf16 v[12:15], v[70:73], v[162:165], v[12:15]
	global_load_lds_dwordx4 v[180:181], off
	s_mov_b32 m0, s84
	v_mfma_f32_16x16x32_bf16 v[4:7], v[86:89], v[162:165], v[4:7]
	global_load_lds_dwordx4 v[90:91], off
	ds_read_b128 v[70:73], v130 offset:32768
	ds_read_b128 v[86:89], v130 offset:34816
	v_mfma_f32_16x16x32_bf16 v[0:3], v[154:157], v[162:165], v[0:3]
	ds_read_b128 v[146:149], v131 offset:53248
	ds_read_b128 v[154:157], v131 offset:55296
	s_waitcnt lgkmcnt(0)
	v_mfma_f32_16x16x32_bf16 v[60:63], v[150:153], v[70:73], v[60:63]
	v_mfma_f32_16x16x32_bf16 v[56:59], v[170:173], v[70:73], v[56:59]
	v_mfma_f32_16x16x32_bf16 v[52:55], v[146:149], v[70:73], v[52:55]
	v_mfma_f32_16x16x32_bf16 v[48:51], v[154:157], v[70:73], v[48:51]
	v_mfma_f32_16x16x32_bf16 v[44:47], v[150:153], v[86:89], v[44:47]
	v_mfma_f32_16x16x32_bf16 v[40:43], v[170:173], v[86:89], v[40:43]
	v_mfma_f32_16x16x32_bf16 v[36:39], v[146:149], v[86:89], v[36:39]
	v_mfma_f32_16x16x32_bf16 v[32:35], v[154:157], v[86:89], v[32:35]
	ds_read_b128 v[70:73], v130 offset:36864
	ds_read_b128 v[86:89], v130 offset:38912
	v_mfma_f32_16x16x32_bf16 v[8:11], v[158:161], v[162:165], v[8:11]
	s_waitcnt lgkmcnt(0)
	v_mfma_f32_16x16x32_bf16 v[28:31], v[150:153], v[70:73], v[28:31]
	v_mfma_f32_16x16x32_bf16 v[24:27], v[170:173], v[70:73], v[24:27]
	v_mfma_f32_16x16x32_bf16 v[20:23], v[146:149], v[70:73], v[20:23]
	v_mfma_f32_16x16x32_bf16 v[16:19], v[154:157], v[70:73], v[16:19]
	v_mfma_f32_16x16x32_bf16 v[12:15], v[150:153], v[86:89], v[12:15]
	v_mfma_f32_16x16x32_bf16 v[4:7], v[170:173], v[86:89], v[4:7]
	v_mfma_f32_16x16x32_bf16 v[0:3], v[146:149], v[86:89], v[0:3]
	ds_read_b128 v[70:73], v133 offset:49152
	ds_read_b128 v[146:149], v133 offset:51200
	v_mfma_f32_16x16x32_bf16 v[8:11], v[154:157], v[86:89], v[8:11]
	ds_read_b128 v[86:89], v132 offset:32768
	ds_read_b128 v[150:153], v132 offset:34816
	ds_read_b128 v[154:157], v133 offset:53248
	ds_read_b128 v[158:161], v133 offset:55296
	s_waitcnt lgkmcnt(0)
	v_mfma_f32_16x16x32_bf16 v[60:63], v[70:73], v[86:89], v[60:63]
	v_mfma_f32_16x16x32_bf16 v[56:59], v[146:149], v[86:89], v[56:59]
	v_mfma_f32_16x16x32_bf16 v[52:55], v[154:157], v[86:89], v[52:55]
	v_mfma_f32_16x16x32_bf16 v[48:51], v[158:161], v[86:89], v[48:51]
	v_mfma_f32_16x16x32_bf16 v[44:47], v[70:73], v[150:153], v[44:47]
	v_mfma_f32_16x16x32_bf16 v[40:43], v[146:149], v[150:153], v[40:43]
	v_mfma_f32_16x16x32_bf16 v[36:39], v[154:157], v[150:153], v[36:39]
	v_mfma_f32_16x16x32_bf16 v[32:35], v[158:161], v[150:153], v[32:35]
	ds_read_b128 v[86:89], v132 offset:36864
	ds_read_b128 v[150:153], v132 offset:38912
	s_waitcnt lgkmcnt(0)
	v_mfma_f32_16x16x32_bf16 v[28:31], v[70:73], v[86:89], v[28:31]
	v_mfma_f32_16x16x32_bf16 v[24:27], v[146:149], v[86:89], v[24:27]
	v_mfma_f32_16x16x32_bf16 v[20:23], v[154:157], v[86:89], v[20:23]
	v_mfma_f32_16x16x32_bf16 v[16:19], v[158:161], v[86:89], v[16:19]
	v_mfma_f32_16x16x32_bf16 v[12:15], v[70:73], v[150:153], v[12:15]
	v_mfma_f32_16x16x32_bf16 v[4:7], v[146:149], v[150:153], v[4:7]
	v_mfma_f32_16x16x32_bf16 v[0:3], v[154:157], v[150:153], v[0:3]
	v_mfma_f32_16x16x32_bf16 v[8:11], v[158:161], v[150:153], v[8:11]
	s_cbranch_scc1 .LBB0_473
	v_readfirstlane_b32 s71, v92
	s_waitcnt vmcnt(0) lgkmcnt(0)
	s_barrier
	s_mov_b32 m0, s71
	v_readfirstlane_b32 s71, v93
	global_load_lds_dwordx4 v[76:77], off
	s_mov_b32 m0, s71
	v_readfirstlane_b32 s71, v94
	global_load_lds_dwordx4 v[78:79], off
	s_mov_b32 m0, s71
	v_readfirstlane_b32 s71, v95
	global_load_lds_dwordx4 v[80:81], off
	s_mov_b32 m0, s71
	v_readfirstlane_b32 s71, v122
	v_lshl_add_u64 v[64:65], v[84:85], 0, s[40:41]
	global_load_lds_dwordx4 v[82:83], off
	s_mov_b32 m0, s71
	v_readfirstlane_b32 s71, v123
	global_load_lds_dwordx4 v[64:65], off
	v_lshl_add_u64 v[64:65], v[84:85], 0, s[42:43]
	s_mov_b32 m0, s71
	v_readfirstlane_b32 s71, v124
	global_load_lds_dwordx4 v[64:65], off
	v_lshl_add_u64 v[64:65], v[84:85], 0, s[44:45]
	s_mov_b32 m0, s71
	ds_read_b128 v[68:71], v131 offset:16384
	global_load_lds_dwordx4 v[64:65], off
	ds_read_b128 v[72:75], v131 offset:18432
	ds_read_b128 v[76:79], v130
	ds_read_b128 v[80:83], v130 offset:2048
	ds_read_b128 v[86:89], v131 offset:20480
	ds_read_b128 v[90:93], v131 offset:22528
	v_readfirstlane_b32 s71, v125
	v_lshl_add_u64 v[64:65], v[84:85], 0, s[48:49]
	s_mov_b32 m0, s71
	s_waitcnt lgkmcnt(0)
	v_mfma_f32_16x16x32_bf16 v[60:63], v[68:71], v[76:79], v[60:63]
	global_load_lds_dwordx4 v[64:65], off
	v_lshl_add_u32 v122, s70, 7, v134
	v_mfma_f32_16x16x32_bf16 v[56:59], v[72:75], v[76:79], v[56:59]
	v_ashrrev_i32_e32 v123, 31, v122
	v_lshlrev_b64 v[64:65], 11, v[122:123]
	s_add_i32 s81, s81, s80
	v_mfma_f32_16x16x32_bf16 v[52:55], v[86:89], v[76:79], v[52:55]
	s_cmp_ge_i32 s81, s82
	v_mfma_f32_16x16x32_bf16 v[48:51], v[90:93], v[76:79], v[48:51]
	v_mfma_f32_16x16x32_bf16 v[44:47], v[68:71], v[80:83], v[44:47]
	v_mfma_f32_16x16x32_bf16 v[40:43], v[72:75], v[80:83], v[40:43]
	v_mfma_f32_16x16x32_bf16 v[36:39], v[86:89], v[80:83], v[36:39]
	v_mfma_f32_16x16x32_bf16 v[32:35], v[90:93], v[80:83], v[32:35]
	ds_read_b128 v[76:79], v130 offset:4096
	ds_read_b128 v[80:83], v130 offset:6144
	ds_read_b128 v[146:149], v133 offset:16384
	s_waitcnt lgkmcnt(0)
	v_mfma_f32_16x16x32_bf16 v[28:31], v[68:71], v[76:79], v[28:31]
	v_mfma_f32_16x16x32_bf16 v[24:27], v[72:75], v[76:79], v[24:27]
	v_mfma_f32_16x16x32_bf16 v[20:23], v[86:89], v[76:79], v[20:23]
	v_mfma_f32_16x16x32_bf16 v[76:79], v[90:93], v[76:79], v[16:19]
	v_mfma_f32_16x16x32_bf16 v[68:71], v[68:71], v[80:83], v[12:15]
	v_mfma_f32_16x16x32_bf16 v[124:127], v[72:75], v[80:83], v[4:7]
	v_mfma_f32_16x16x32_bf16 v[84:87], v[86:89], v[80:83], v[0:3]
	v_mfma_f32_16x16x32_bf16 v[80:83], v[90:93], v[80:83], v[8:11]
	ds_read_b128 v[88:91], v133 offset:18432
	s_nop 0
	ds_read_b128 v[0:3], v132
	ds_read_b128 v[8:11], v132 offset:2048
	ds_read_b128 v[150:153], v133 offset:20480
	ds_read_b128 v[154:157], v133 offset:22528
	ds_read_b128 v[162:165], v132 offset:4096
	ds_read_b128 v[170:173], v132 offset:6144
	s_waitcnt vmcnt(0) lgkmcnt(0)
	s_barrier
	s_waitcnt lgkmcnt(0)
	v_mfma_f32_16x16x32_bf16 v[60:63], v[146:149], v[0:3], v[60:63]
	ds_read_b128 v[174:177], v130 offset:32768
	ds_read_b128 v[178:181], v130 offset:34816
	ds_read_b128 v[182:185], v130 offset:36864
	ds_read_b128 v[186:189], v130 offset:38912
	ds_read_b128 v[194:197], v131 offset:49152
	ds_read_b128 v[198:201], v131 offset:51200
	ds_read_b128 v[202:205], v131 offset:53248
	ds_read_b128 v[206:209], v131 offset:55296
	v_mfma_f32_16x16x32_bf16 v[56:59], v[88:91], v[0:3], v[56:59]
	v_mfma_f32_16x16x32_bf16 v[158:161], v[150:153], v[0:3], v[52:55]
	ds_read_b128 v[92:95], v132 offset:32768
	ds_read_b128 v[72:75], v132 offset:34816
	s_nop 0
	ds_read_b128 v[52:55], v132 offset:36864
	ds_read_b128 v[4:7], v132 offset:38912
	v_mfma_f32_16x16x32_bf16 v[48:51], v[154:157], v[0:3], v[48:51]
	v_lshl_add_u64 v[0:1], v[66:67], 2, s[8:9]
	v_mfma_f32_16x16x32_bf16 v[44:47], v[146:149], v[8:11], v[44:47]
	v_mfma_f32_16x16x32_bf16 v[190:193], v[88:91], v[8:11], v[40:43]
	v_mfma_f32_16x16x32_bf16 v[210:213], v[150:153], v[8:11], v[36:39]
	v_mfma_f32_16x16x32_bf16 v[214:217], v[154:157], v[8:11], v[32:35]
	s_nop 1
	ds_read_b128 v[36:39], v133 offset:49152
	ds_read_b128 v[32:35], v133 offset:51200
	ds_read_b128 v[12:15], v133 offset:53248
	ds_read_b128 v[8:11], v133 offset:55296
	s_waitcnt lgkmcnt(0)
	global_load_dwordx4 v[40:43], v[0:1], off
	global_load_dwordx4 v[222:225], v[98:99], off
	global_load_dwordx4 v[226:229], v[98:99], off offset:1024
	v_mfma_f32_16x16x32_bf16 v[218:221], v[146:149], v[162:165], v[28:31]
	s_nop 2
	global_load_dwordx4 v[28:31], v[0:1], off offset:64
	global_load_dwordx4 v[16:19], v[0:1], off offset:128
	s_nop 0
	global_load_dwordx4 v[0:3], v[0:1], off offset:192
	s_waitcnt vmcnt(0)
	v_lshlrev_b32_e32 v235, 16, v227
	s_waitcnt lgkmcnt(11)
	v_mfma_f32_16x16x32_bf16 v[60:63], v[194:197], v[174:177], v[60:63]
	v_lshlrev_b32_e32 v234, 16, v226
	s_waitcnt lgkmcnt(3)
	v_mfma_f32_16x16x32_bf16 v[60:63], v[36:39], v[92:95], v[60:63]
	v_mfma_f32_16x16x32_bf16 v[24:27], v[88:91], v[162:165], v[24:27]
	v_mfma_f32_16x16x32_bf16 v[20:23], v[150:153], v[162:165], v[20:23]
	s_nop 5
	v_add_f32_e32 v61, v61, v41
	v_mul_f32_e32 v61, 0xbfb8aa3b, v61
	v_add_f32_e32 v60, v60, v40
	v_exp_f32_e32 v166, v61
	v_add_f32_e32 v61, v62, v42
	v_mul_f32_e32 v60, 0xbfb8aa3b, v60
	v_mul_f32_e32 v61, 0xbfb8aa3b, v61
	v_exp_f32_e32 v60, v60
	v_exp_f32_e32 v61, v61
	v_mfma_f32_16x16x32_bf16 v[162:165], v[154:157], v[162:165], v[76:79]
	v_add_f32_e32 v62, v63, v43
	v_mul_f32_e32 v62, 0xbfb8aa3b, v62
	v_pk_add_f32 v[60:61], v[60:61], 1.0 op_sel_hi:[1,0]
	v_mfma_f32_16x16x32_bf16 v[146:149], v[146:149], v[170:173], v[68:71]
	v_exp_f32_e32 v167, v62
	v_lshl_add_u64 v[62:63], s[16:17], 0, v[64:65]
	v_mfma_f32_16x16x32_bf16 v[230:233], v[88:91], v[170:173], v[124:127]
	v_mfma_f32_16x16x32_bf16 v[150:153], v[150:153], v[170:173], v[84:87]
	s_nop 1
	v_lshlrev_b64 v[124:125], 1, v[66:67]
	v_lshl_add_u64 v[126:127], v[62:63], 0, v[124:125]
	v_lshlrev_b32_e32 v63, 16, v223
	v_mfma_f32_16x16x32_bf16 v[154:157], v[154:157], v[170:173], v[80:83]
	v_lshlrev_b32_e32 v62, 16, v222
	v_mfma_f32_16x16x32_bf16 v[170:173], v[198:201], v[174:177], v[56:59]
	s_nop 2
	v_div_scale_f32 v56, s[70:71], v61, v61, 1.0
	v_rcp_f32_e32 v57, v56
	v_mfma_f32_16x16x32_bf16 v[158:161], v[202:205], v[174:177], v[158:161]
	v_fma_f32 v58, -v56, v57, 1.0
	v_mfma_f32_16x16x32_bf16 v[174:177], v[206:209], v[174:177], v[48:51]
	v_fmac_f32_e32 v57, v58, v57
	s_nop 1
	v_div_scale_f32 v48, vcc, 1.0, v61, 1.0
	v_mfma_f32_16x16x32_bf16 v[84:87], v[194:197], v[178:181], v[44:47]
	s_nop 2
	v_mul_f32_e32 v44, v48, v57
	v_div_scale_f32 v46, s[70:71], v60, v60, 1.0
	v_fma_f32 v45, -v56, v44, v48
	v_rcp_f32_e32 v47, v46
	v_fmac_f32_e32 v44, v45, v57
	v_fma_f32 v45, -v56, v44, v48
	v_div_fmas_f32 v44, v45, v57, v44
	v_div_fixup_f32 v45, v44, v61, 1.0
	v_fma_f32 v44, -v46, v47, 1.0
	v_fmac_f32_e32 v47, v44, v47
	v_div_scale_f32 v44, vcc, 1.0, v60, 1.0
	v_mul_f32_e32 v48, v44, v47
	v_mfma_f32_16x16x32_bf16 v[68:71], v[198:201], v[182:185], v[24:27]
	s_nop 2
	v_fma_f32 v24, -v46, v48, v44
	v_fmac_f32_e32 v48, v24, v47
	v_fma_f32 v24, -v46, v48, v44
	v_mfma_f32_16x16x32_bf16 v[56:59], v[202:205], v[182:185], v[20:23]
	s_nop 2
	v_div_fmas_f32 v20, v24, v47, v48
	v_div_fixup_f32 v44, v20, v60, 1.0
	v_mfma_f32_16x16x32_bf16 v[88:91], v[198:201], v[178:181], v[190:193]
	v_mfma_f32_16x16x32_bf16 v[76:79], v[202:205], v[178:181], v[210:213]
	v_mfma_f32_16x16x32_bf16 v[80:83], v[206:209], v[178:181], v[214:217]
	v_fma_f32 v178, v44, v234, v62
	v_fma_f32 v179, v45, v235, v63
	v_mfma_f32_16x16x32_bf16 v[60:63], v[206:209], v[182:185], v[162:165]
	s_nop 2
	v_add_f32_e64 v164, v166, 1.0
	v_add_f32_e64 v165, v167, 1.0
	v_mfma_f32_16x16x32_bf16 v[20:23], v[202:205], v[186:189], v[150:153]
	v_div_scale_f32 v123, s[70:71], v165, v165, 1.0
	v_rcp_f32_e32 v143, v123
	v_div_scale_f32 v145, vcc, 1.0, v165, 1.0
	v_mfma_f32_16x16x32_bf16 v[44:47], v[194:197], v[186:189], v[146:149]
	v_fma_f32 v24, -v123, v143, 1.0
	v_fmac_f32_e32 v143, v24, v143
	v_mul_f32_e32 v150, v145, v143
	v_fma_f32 v146, -v123, v150, v145
	v_fmac_f32_e32 v150, v146, v143
	v_fma_f32 v123, -v123, v150, v145
	v_div_scale_f32 v145, s[70:71], v164, v164, 1.0
	v_rcp_f32_e32 v152, v145
	v_div_fmas_f32 v123, v123, v143, v150
	v_div_fixup_f32 v151, v123, v165, 1.0
	v_and_b32_e32 v163, 0xffff0000, v223
	v_fma_f32 v123, -v145, v152, 1.0
	v_fmac_f32_e32 v152, v123, v152
	v_div_scale_f32 v123, vcc, 1.0, v164, 1.0
	v_mul_f32_e32 v143, v123, v152
	v_fma_f32 v150, -v145, v143, v123
	v_fmac_f32_e32 v143, v150, v152
	v_fma_f32 v123, -v145, v143, v123
	v_div_fmas_f32 v123, v123, v152, v143
	v_and_b32_e32 v162, 0xffff0000, v222
	v_and_b32_e32 v167, 0xffff0000, v227
	v_and_b32_e32 v166, 0xffff0000, v226
	v_div_fixup_f32 v150, v123, v164, 1.0
	s_waitcnt lgkmcnt(2)
	v_mfma_f32_16x16x32_bf16 v[146:149], v[32:35], v[92:95], v[170:173]
	v_fma_f32 v150, v150, v166, v162
	v_fma_f32 v151, v151, v167, v163
	v_and_b32_sdwa v123, v179, v142 dst_sel:DWORD dst_unused:UNUSED_PAD src0_sel:WORD_1 src1_sel:DWORD
	v_and_b32_sdwa v145, v151, v142 dst_sel:DWORD dst_unused:UNUSED_PAD src0_sel:WORD_1 src1_sel:DWORD
	v_add3_u32 v145, v151, v145, s3
	v_add3_u32 v123, v179, v123, s3
	v_and_b32_e32 v145, 0xffff0000, v145
	v_or_b32_sdwa v151, v145, v123 dst_sel:DWORD dst_unused:UNUSED_PAD src0_sel:DWORD src1_sel:WORD_1
	v_add_f32_e32 v123, v146, v28
	v_mul_f32_e32 v123, 0xbfb8aa3b, v123
	v_exp_f32_e32 v146, v123
	v_add_f32_e32 v123, v147, v29
	v_and_b32_sdwa v152, v150, v142 dst_sel:DWORD dst_unused:UNUSED_PAD src0_sel:WORD_1 src1_sel:DWORD
	v_mul_f32_e32 v123, 0xbfb8aa3b, v123
	v_add3_u32 v150, v150, v152, s3
	v_exp_f32_e32 v152, v123
	v_add_f32_e32 v123, v148, v30
	v_mul_f32_e32 v123, 0xbfb8aa3b, v123
	v_exp_f32_e32 v147, v123
	v_add_f32_e32 v123, v149, v31
	v_and_b32_sdwa v143, v178, v142 dst_sel:DWORD dst_unused:UNUSED_PAD src0_sel:WORD_1 src1_sel:DWORD
	v_mul_f32_e32 v123, 0xbfb8aa3b, v123
	v_pk_add_f32 v[146:147], v[146:147], 1.0 op_sel_hi:[1,0]
	v_add3_u32 v143, v178, v143, s3
	v_and_b32_e32 v150, 0xffff0000, v150
	v_exp_f32_e32 v153, v123
	v_div_scale_f32 v123, s[70:71], v147, v147, 1.0
	v_or_b32_sdwa v150, v150, v143 dst_sel:DWORD dst_unused:UNUSED_PAD src0_sel:DWORD src1_sel:WORD_1
	v_rcp_f32_e32 v143, v123
	v_mfma_f32_16x16x32_bf16 v[24:27], v[206:209], v[186:189], v[154:157]
	global_store_dwordx2 v[126:127], v[150:151], off
	v_lshlrev_b32_e32 v149, 16, v225
	v_fma_f32 v145, -v123, v143, 1.0
	v_fmac_f32_e32 v143, v145, v143
	v_div_scale_f32 v145, vcc, 1.0, v147, 1.0
	v_mul_f32_e32 v154, v145, v143
	v_fma_f32 v155, -v123, v154, v145
	v_fmac_f32_e32 v154, v155, v143
	v_fma_f32 v123, -v123, v154, v145
	v_div_scale_f32 v145, s[70:71], v146, v146, 1.0
	v_rcp_f32_e32 v155, v145
	v_div_fmas_f32 v123, v123, v143, v154
	v_div_fixup_f32 v147, v123, v147, 1.0
	v_lshlrev_b32_e32 v148, 16, v224
	v_fma_f32 v123, -v145, v155, 1.0
	v_fmac_f32_e32 v155, v123, v155
	v_div_scale_f32 v123, vcc, 1.0, v146, 1.0
	v_mul_f32_e32 v143, v123, v155
	v_fma_f32 v154, -v145, v143, v123
	v_fmac_f32_e32 v143, v154, v155
	v_fma_f32 v123, -v145, v143, v123
	v_div_fmas_f32 v123, v123, v155, v143
	v_lshlrev_b32_e32 v151, 16, v229
	v_lshlrev_b32_e32 v150, 16, v228
	v_div_fixup_f32 v146, v123, v146, 1.0
	v_pk_fma_f32 v[146:147], v[146:147], v[150:151], v[148:149]
	v_pk_add_f32 v[150:151], v[152:153], 1.0 op_sel_hi:[1,0]
	v_and_b32_e32 v149, 0xffff0000, v225
	v_div_scale_f32 v123, s[70:71], v151, v151, 1.0
	v_rcp_f32_e32 v143, v123
	v_and_b32_e32 v148, 0xffff0000, v224
	v_and_b32_e32 v153, 0xffff0000, v229
	v_and_b32_e32 v152, 0xffff0000, v228
	v_fma_f32 v145, -v123, v143, 1.0
	v_fmac_f32_e32 v143, v145, v143
	v_div_scale_f32 v145, vcc, 1.0, v151, 1.0
	v_mul_f32_e32 v154, v145, v143
	v_fma_f32 v155, -v123, v154, v145
	v_fmac_f32_e32 v154, v155, v143
	v_fma_f32 v123, -v123, v154, v145
	v_div_scale_f32 v145, s[70:71], v150, v150, 1.0
	v_rcp_f32_e32 v155, v145
	v_div_fmas_f32 v123, v123, v143, v154
	v_div_fixup_f32 v151, v123, v151, 1.0
	v_mfma_f32_16x16x32_bf16 v[84:87], v[36:39], v[72:75], v[84:87]
	v_fma_f32 v123, -v145, v155, 1.0
	v_fmac_f32_e32 v155, v123, v155
	v_div_scale_f32 v123, vcc, 1.0, v150, 1.0
	v_mul_f32_e32 v143, v123, v155
	v_fma_f32 v154, -v145, v143, v123
	v_fmac_f32_e32 v143, v154, v155
	v_fma_f32 v123, -v145, v143, v123
	v_div_fmas_f32 v123, v123, v155, v143
	v_div_fixup_f32 v150, v123, v150, 1.0
	v_pk_fma_f32 v[148:149], v[150:151], v[152:153], v[148:149]
	v_and_b32_sdwa v143, v146, v142 dst_sel:DWORD dst_unused:UNUSED_PAD src0_sel:WORD_1 src1_sel:DWORD
	v_add3_u32 v143, v146, v143, s3
	v_and_b32_sdwa v145, v149, v142 dst_sel:DWORD dst_unused:UNUSED_PAD src0_sel:WORD_1 src1_sel:DWORD
	v_and_b32_sdwa v146, v148, v142 dst_sel:DWORD dst_unused:UNUSED_PAD src0_sel:WORD_1 src1_sel:DWORD
	v_and_b32_sdwa v123, v147, v142 dst_sel:DWORD dst_unused:UNUSED_PAD src0_sel:WORD_1 src1_sel:DWORD
	v_add3_u32 v145, v149, v145, s3
	v_add3_u32 v146, v148, v146, s3
	v_add3_u32 v123, v147, v123, s3
	v_and_b32_e32 v145, 0xffff0000, v145
	v_and_b32_e32 v146, 0xffff0000, v146
	v_or_b32_sdwa v147, v145, v123 dst_sel:DWORD dst_unused:UNUSED_PAD src0_sel:DWORD src1_sel:WORD_1
	v_or_b32_sdwa v146, v146, v143 dst_sel:DWORD dst_unused:UNUSED_PAD src0_sel:DWORD src1_sel:WORD_1
	global_store_dwordx2 v[126:127], v[146:147], off offset:32
	global_load_dwordx4 v[146:149], v[98:99], off offset:128
	s_waitcnt lgkmcnt(1)
	v_mfma_f32_16x16x32_bf16 v[150:153], v[12:15], v[92:95], v[158:161]
	global_load_dwordx4 v[154:157], v[98:99], off offset:1152
	v_add_f32_e32 v84, v84, v40
	v_mul_f32_e32 v84, 0xbfb8aa3b, v84
	s_waitcnt lgkmcnt(0)
	v_mfma_f32_16x16x32_bf16 v[92:95], v[8:11], v[92:95], v[174:177]
	s_waitcnt vmcnt(0)
	v_lshlrev_b32_e32 v161, 16, v155
	s_nop 0
	v_add_f32_e32 v123, v150, v16
	v_mul_f32_e32 v123, 0xbfb8aa3b, v123
	v_exp_f32_e32 v150, v123
	v_add_f32_e32 v123, v151, v17
	v_mul_f32_e32 v123, 0xbfb8aa3b, v123
	v_exp_f32_e32 v158, v123
	v_add_f32_e32 v123, v152, v18
	v_mul_f32_e32 v123, 0xbfb8aa3b, v123
	v_exp_f32_e32 v151, v123
	v_add_f32_e32 v123, v153, v19
	v_mul_f32_e32 v123, 0xbfb8aa3b, v123
	v_exp_f32_e32 v159, v123
	v_pk_add_f32 v[150:151], v[150:151], 1.0 op_sel_hi:[1,0]
	v_lshlrev_b32_e32 v153, 16, v147
	v_div_scale_f32 v123, s[70:71], v151, v151, 1.0
	v_rcp_f32_e32 v143, v123
	v_lshlrev_b32_e32 v152, 16, v146
	v_lshlrev_b32_e32 v160, 16, v154
	v_and_b32_e32 v147, 0xffff0000, v147
	v_fma_f32 v145, -v123, v143, 1.0
	v_fmac_f32_e32 v143, v145, v143
	v_div_scale_f32 v145, vcc, 1.0, v151, 1.0
	v_mul_f32_e32 v162, v145, v143
	v_fma_f32 v163, -v123, v162, v145
	v_fmac_f32_e32 v162, v163, v143
	v_fma_f32 v123, -v123, v162, v145
	v_div_scale_f32 v145, s[70:71], v150, v150, 1.0
	v_rcp_f32_e32 v163, v145
	v_div_fmas_f32 v123, v123, v143, v162
	v_div_fixup_f32 v151, v123, v151, 1.0
	v_and_b32_e32 v146, 0xffff0000, v146
	v_fma_f32 v123, -v145, v163, 1.0
	v_fmac_f32_e32 v163, v123, v163
	v_div_scale_f32 v123, vcc, 1.0, v150, 1.0
	v_mul_f32_e32 v143, v123, v163
	v_fma_f32 v162, -v145, v143, v123
	v_fmac_f32_e32 v143, v162, v163
	v_fma_f32 v123, -v145, v143, v123
	v_div_fmas_f32 v123, v123, v163, v143
	v_div_fixup_f32 v150, v123, v150, 1.0
	v_pk_fma_f32 v[150:151], v[150:151], v[160:161], v[152:153]
	v_pk_add_f32 v[152:153], v[158:159], 1.0 op_sel_hi:[1,0]
	v_and_b32_e32 v155, 0xffff0000, v155
	v_div_scale_f32 v123, s[70:71], v153, v153, 1.0
	v_rcp_f32_e32 v143, v123
	v_and_b32_e32 v154, 0xffff0000, v154
	v_add_f32_e32 v93, v93, v1
	v_mul_f32_e32 v93, 0xbfb8aa3b, v93
	v_fma_f32 v145, -v123, v143, 1.0
	v_fmac_f32_e32 v143, v145, v143
	v_div_scale_f32 v145, vcc, 1.0, v153, 1.0
	v_mul_f32_e32 v158, v145, v143
	v_fma_f32 v159, -v123, v158, v145
	v_fmac_f32_e32 v158, v159, v143
	v_fma_f32 v123, -v123, v158, v145
	v_div_scale_f32 v145, s[70:71], v152, v152, 1.0
	v_rcp_f32_e32 v159, v145
	v_div_fmas_f32 v123, v123, v143, v158
	v_div_fixup_f32 v153, v123, v153, 1.0
	v_add_f32_e32 v92, v92, v0
	v_fma_f32 v123, -v145, v159, 1.0
	v_fmac_f32_e32 v159, v123, v159
	v_div_scale_f32 v123, vcc, 1.0, v152, 1.0
	v_mul_f32_e32 v143, v123, v159
	v_fma_f32 v158, -v145, v143, v123
	v_fmac_f32_e32 v143, v158, v159
	v_fma_f32 v123, -v145, v143, v123
	v_div_fmas_f32 v123, v123, v159, v143
	v_div_fixup_f32 v152, v123, v152, 1.0
	v_pk_fma_f32 v[146:147], v[152:153], v[154:155], v[146:147]
	v_and_b32_sdwa v143, v150, v142 dst_sel:DWORD dst_unused:UNUSED_PAD src0_sel:WORD_1 src1_sel:DWORD
	v_add3_u32 v143, v150, v143, s3
	v_and_b32_sdwa v150, v146, v142 dst_sel:DWORD dst_unused:UNUSED_PAD src0_sel:WORD_1 src1_sel:DWORD
	v_add3_u32 v146, v146, v150, s3
	v_exp_f32_e32 v150, v93
	v_add_f32_e32 v93, v94, v2
	v_mul_f32_e32 v92, 0xbfb8aa3b, v92
	v_mul_f32_e32 v93, 0xbfb8aa3b, v93
	v_exp_f32_e32 v92, v92
	v_exp_f32_e32 v93, v93
	v_and_b32_sdwa v145, v147, v142 dst_sel:DWORD dst_unused:UNUSED_PAD src0_sel:WORD_1 src1_sel:DWORD
	v_and_b32_sdwa v123, v151, v142 dst_sel:DWORD dst_unused:UNUSED_PAD src0_sel:WORD_1 src1_sel:DWORD
	v_add3_u32 v145, v147, v145, s3
	v_add3_u32 v123, v151, v123, s3
	v_and_b32_e32 v145, 0xffff0000, v145
	v_pk_add_f32 v[92:93], v[92:93], 1.0 op_sel_hi:[1,0]
	v_and_b32_e32 v146, 0xffff0000, v146
	v_or_b32_sdwa v147, v145, v123 dst_sel:DWORD dst_unused:UNUSED_PAD src0_sel:DWORD src1_sel:WORD_1
	v_div_scale_f32 v123, s[70:71], v93, v93, 1.0
	v_or_b32_sdwa v146, v146, v143 dst_sel:DWORD dst_unused:UNUSED_PAD src0_sel:DWORD src1_sel:WORD_1
	v_rcp_f32_e32 v143, v123
	v_add_f32_e32 v94, v95, v3
	v_mul_f32_e32 v94, 0xbfb8aa3b, v94
	v_exp_f32_e32 v151, v94
	v_fma_f32 v145, -v123, v143, 1.0
	v_fmac_f32_e32 v143, v145, v143
	v_div_scale_f32 v145, vcc, 1.0, v93, 1.0
	v_mul_f32_e32 v152, v145, v143
	v_fma_f32 v153, -v123, v152, v145
	v_fmac_f32_e32 v152, v153, v143
	v_fma_f32 v123, -v123, v152, v145
	v_div_scale_f32 v145, s[70:71], v92, v92, 1.0
	v_rcp_f32_e32 v153, v145
	v_div_fmas_f32 v123, v123, v143, v152
	v_div_fixup_f32 v93, v123, v93, 1.0
	global_store_dwordx2 v[126:127], v[146:147], off offset:64
	v_fma_f32 v123, -v145, v153, 1.0
	v_fmac_f32_e32 v153, v123, v153
	v_div_scale_f32 v123, vcc, 1.0, v92, 1.0
	v_mul_f32_e32 v143, v123, v153
	v_fma_f32 v152, -v145, v143, v123
	v_fmac_f32_e32 v143, v152, v153
	v_fma_f32 v123, -v145, v143, v123
	v_div_fmas_f32 v123, v123, v153, v143
	v_lshlrev_b32_e32 v95, 16, v149
	v_lshlrev_b32_e32 v94, 16, v148
	v_lshlrev_b32_e32 v147, 16, v157
	v_lshlrev_b32_e32 v146, 16, v156
	v_div_fixup_f32 v92, v123, v92, 1.0
	v_pk_fma_f32 v[92:93], v[92:93], v[146:147], v[94:95]
	v_pk_add_f32 v[146:147], v[150:151], 1.0 op_sel_hi:[1,0]
	v_and_b32_e32 v95, 0xffff0000, v149
	v_div_scale_f32 v123, s[70:71], v147, v147, 1.0
	v_rcp_f32_e32 v143, v123
	v_and_b32_e32 v94, 0xffff0000, v148
	v_and_b32_e32 v149, 0xffff0000, v157
	v_and_b32_e32 v148, 0xffff0000, v156
	v_fma_f32 v145, -v123, v143, 1.0
	v_fmac_f32_e32 v143, v145, v143
	v_div_scale_f32 v145, vcc, 1.0, v147, 1.0
	v_mul_f32_e32 v150, v145, v143
	v_fma_f32 v151, -v123, v150, v145
	v_fmac_f32_e32 v150, v151, v143
	v_fma_f32 v123, -v123, v150, v145
	v_div_scale_f32 v145, s[70:71], v146, v146, 1.0
	v_rcp_f32_e32 v151, v145
	v_div_fmas_f32 v123, v123, v143, v150
	v_div_fixup_f32 v147, v123, v147, 1.0
	v_mfma_f32_16x16x32_bf16 v[88:91], v[32:35], v[72:75], v[88:91]
	v_fma_f32 v123, -v145, v151, 1.0
	v_fmac_f32_e32 v151, v123, v151
	v_div_scale_f32 v123, vcc, 1.0, v146, 1.0
	v_mul_f32_e32 v143, v123, v151
	v_fma_f32 v150, -v145, v143, v123
	v_fmac_f32_e32 v143, v150, v151
	v_fma_f32 v123, -v145, v143, v123
	v_div_fmas_f32 v123, v123, v151, v143
	v_div_fixup_f32 v146, v123, v146, 1.0
	v_pk_fma_f32 v[94:95], v[146:147], v[148:149], v[94:95]
	v_and_b32_sdwa v123, v93, v142 dst_sel:DWORD dst_unused:UNUSED_PAD src0_sel:WORD_1 src1_sel:DWORD
	v_and_b32_sdwa v143, v92, v142 dst_sel:DWORD dst_unused:UNUSED_PAD src0_sel:WORD_1 src1_sel:DWORD
	v_add3_u32 v92, v92, v143, s3
	v_add3_u32 v93, v93, v123, s3
	v_and_b32_sdwa v123, v95, v142 dst_sel:DWORD dst_unused:UNUSED_PAD src0_sel:WORD_1 src1_sel:DWORD
	v_and_b32_sdwa v143, v94, v142 dst_sel:DWORD dst_unused:UNUSED_PAD src0_sel:WORD_1 src1_sel:DWORD
	v_add3_u32 v95, v95, v123, s3
	v_add3_u32 v94, v94, v143, s3
	v_and_b32_e32 v95, 0xffff0000, v95
	v_and_b32_e32 v94, 0xffff0000, v94
	v_or_b32_sdwa v93, v95, v93 dst_sel:DWORD dst_unused:UNUSED_PAD src0_sel:DWORD src1_sel:WORD_1
	v_or_b32_sdwa v92, v94, v92 dst_sel:DWORD dst_unused:UNUSED_PAD src0_sel:DWORD src1_sel:WORD_1
	global_store_dwordx2 v[126:127], v[92:93], off offset:96
	global_load_dwordx4 v[92:95], v[98:99], off offset:256
	v_exp_f32_e32 v150, v84
	global_load_dwordx4 v[146:149], v[98:99], off offset:1280
	v_add_f32_e32 v84, v85, v41
	v_mul_f32_e32 v84, 0xbfb8aa3b, v84
	v_exp_f32_e32 v152, v84
	v_add_f32_e32 v84, v86, v42
	v_mul_f32_e32 v84, 0xbfb8aa3b, v84
	v_exp_f32_e32 v151, v84
	v_or_b32_e32 v126, 16, v122
	v_ashrrev_i32_e32 v127, 31, v126
	v_add_f32_e32 v84, v87, v43
	v_lshlrev_b64 v[126:127], 11, v[126:127]
	v_mul_f32_e32 v84, 0xbfb8aa3b, v84
	v_exp_f32_e32 v153, v84
	v_lshl_add_u64 v[84:85], s[16:17], 0, v[126:127]
	v_pk_add_f32 v[126:127], v[150:151], 1.0 op_sel_hi:[1,0]
	v_add_f32_e32 v89, v89, v29
	v_div_scale_f32 v123, s[70:71], v127, v127, 1.0
	v_rcp_f32_e32 v143, v123
	v_mul_f32_e32 v89, 0xbfb8aa3b, v89
	v_add_f32_e32 v88, v88, v28
	v_mul_f32_e32 v88, 0xbfb8aa3b, v88
	v_fma_f32 v145, -v123, v143, 1.0
	v_fmac_f32_e32 v143, v145, v143
	v_div_scale_f32 v145, vcc, 1.0, v127, 1.0
	v_mul_f32_e32 v154, v145, v143
	v_fma_f32 v155, -v123, v154, v145
	v_fmac_f32_e32 v154, v155, v143
	v_fma_f32 v123, -v123, v154, v145
	v_div_scale_f32 v145, s[70:71], v126, v126, 1.0
	v_rcp_f32_e32 v155, v145
	v_div_fmas_f32 v123, v123, v143, v154
	v_div_fixup_f32 v127, v123, v127, 1.0
	v_exp_f32_e32 v88, v88
	v_fma_f32 v123, -v145, v155, 1.0
	v_fmac_f32_e32 v155, v123, v155
	v_div_scale_f32 v123, vcc, 1.0, v126, 1.0
	v_mul_f32_e32 v143, v123, v155
	v_fma_f32 v154, -v145, v143, v123
	v_fmac_f32_e32 v143, v154, v155
	v_fma_f32 v123, -v145, v143, v123
	v_div_fmas_f32 v123, v123, v155, v143
	v_div_fixup_f32 v126, v123, v126, 1.0
	v_lshl_add_u64 v[84:85], v[84:85], 0, v[124:125]
	v_mfma_f32_16x16x32_bf16 v[76:79], v[12:15], v[72:75], v[76:79]
	s_waitcnt vmcnt(1)
	v_lshlrev_b32_e32 v87, 16, v93
	v_lshlrev_b32_e32 v86, 16, v92
	s_waitcnt vmcnt(0)
	v_lshlrev_b32_e32 v151, 16, v147
	v_lshlrev_b32_e32 v150, 16, v146
	v_pk_fma_f32 v[86:87], v[126:127], v[150:151], v[86:87]
	v_pk_add_f32 v[126:127], v[152:153], 1.0 op_sel_hi:[1,0]
	v_and_b32_e32 v93, 0xffff0000, v93
	v_div_scale_f32 v123, s[70:71], v127, v127, 1.0
	v_rcp_f32_e32 v143, v123
	v_and_b32_e32 v92, 0xffff0000, v92
	v_and_b32_e32 v147, 0xffff0000, v147
	v_and_b32_e32 v146, 0xffff0000, v146
	v_fma_f32 v145, -v123, v143, 1.0
	v_fmac_f32_e32 v143, v145, v143
	v_div_scale_f32 v145, vcc, 1.0, v127, 1.0
	v_mul_f32_e32 v150, v145, v143
	v_fma_f32 v151, -v123, v150, v145
	v_fmac_f32_e32 v150, v151, v143
	v_fma_f32 v123, -v123, v150, v145
	v_div_scale_f32 v145, s[70:71], v126, v126, 1.0
	v_rcp_f32_e32 v151, v145
	v_div_fmas_f32 v123, v123, v143, v150
	v_div_fixup_f32 v127, v123, v127, 1.0
	v_add_f32_e32 v77, v77, v17
	v_fma_f32 v123, -v145, v151, 1.0
	v_fmac_f32_e32 v151, v123, v151
	v_div_scale_f32 v123, vcc, 1.0, v126, 1.0
	v_mul_f32_e32 v143, v123, v151
	v_fma_f32 v150, -v145, v143, v123
	v_fmac_f32_e32 v143, v150, v151
	v_fma_f32 v123, -v145, v143, v123
	v_div_fmas_f32 v123, v123, v151, v143
	v_div_fixup_f32 v126, v123, v126, 1.0
	v_pk_fma_f32 v[92:93], v[126:127], v[146:147], v[92:93]
	v_and_b32_sdwa v126, v86, v142 dst_sel:DWORD dst_unused:UNUSED_PAD src0_sel:WORD_1 src1_sel:DWORD
	v_add3_u32 v86, v86, v126, s3
	v_and_b32_sdwa v126, v92, v142 dst_sel:DWORD dst_unused:UNUSED_PAD src0_sel:WORD_1 src1_sel:DWORD
	v_add3_u32 v92, v92, v126, s3
	v_and_b32_e32 v92, 0xffff0000, v92
	v_or_b32_sdwa v86, v92, v86 dst_sel:DWORD dst_unused:UNUSED_PAD src0_sel:DWORD src1_sel:WORD_1
	v_exp_f32_e32 v92, v89
	v_add_f32_e32 v89, v90, v30
	v_mul_f32_e32 v89, 0xbfb8aa3b, v89
	v_exp_f32_e32 v89, v89
	v_and_b32_sdwa v123, v87, v142 dst_sel:DWORD dst_unused:UNUSED_PAD src0_sel:WORD_1 src1_sel:DWORD
	v_add3_u32 v87, v87, v123, s3
	v_and_b32_sdwa v123, v93, v142 dst_sel:DWORD dst_unused:UNUSED_PAD src0_sel:WORD_1 src1_sel:DWORD
	v_pk_add_f32 v[88:89], v[88:89], 1.0 op_sel_hi:[1,0]
	v_add3_u32 v93, v93, v123, s3
	v_div_scale_f32 v123, s[70:71], v89, v89, 1.0
	v_rcp_f32_e32 v126, v123
	v_add_f32_e32 v90, v91, v31
	v_and_b32_e32 v93, 0xffff0000, v93
	v_mul_f32_e32 v90, 0xbfb8aa3b, v90
	v_fma_f32 v127, -v123, v126, 1.0
	v_fmac_f32_e32 v126, v127, v126
	v_div_scale_f32 v127, vcc, 1.0, v89, 1.0
	v_mul_f32_e32 v143, v127, v126
	v_fma_f32 v145, -v123, v143, v127
	v_fmac_f32_e32 v143, v145, v126
	v_fma_f32 v123, -v123, v143, v127
	v_div_scale_f32 v127, s[70:71], v88, v88, 1.0
	v_rcp_f32_e32 v145, v127
	v_div_fmas_f32 v123, v123, v126, v143
	v_div_fixup_f32 v89, v123, v89, 1.0
	v_or_b32_sdwa v87, v93, v87 dst_sel:DWORD dst_unused:UNUSED_PAD src0_sel:DWORD src1_sel:WORD_1
	v_fma_f32 v123, -v127, v145, 1.0
	v_fmac_f32_e32 v145, v123, v145
	v_div_scale_f32 v123, vcc, 1.0, v88, 1.0
	v_mul_f32_e32 v126, v123, v145
	v_fma_f32 v143, -v127, v126, v123
	v_exp_f32_e32 v93, v90
	v_fmac_f32_e32 v126, v143, v145
	v_fma_f32 v123, -v127, v126, v123
	v_div_fmas_f32 v123, v123, v145, v126
	global_store_dwordx2 v[84:85], v[86:87], off
	v_lshlrev_b32_e32 v87, 16, v95
	v_lshlrev_b32_e32 v86, 16, v94
	v_lshlrev_b32_e32 v91, 16, v149
	v_lshlrev_b32_e32 v90, 16, v148
	v_div_fixup_f32 v88, v123, v88, 1.0
	v_pk_fma_f32 v[86:87], v[88:89], v[90:91], v[86:87]
	v_pk_add_f32 v[90:91], v[92:93], 1.0 op_sel_hi:[1,0]
	v_and_b32_e32 v89, 0xffff0000, v95
	v_div_scale_f32 v95, s[70:71], v91, v91, 1.0
	v_rcp_f32_e32 v123, v95
	v_and_b32_e32 v88, 0xffff0000, v94
	v_and_b32_e32 v93, 0xffff0000, v149
	v_and_b32_e32 v92, 0xffff0000, v148
	v_fma_f32 v94, -v95, v123, 1.0
	v_fmac_f32_e32 v123, v94, v123
	v_div_scale_f32 v94, vcc, 1.0, v91, 1.0
	v_mul_f32_e32 v126, v94, v123
	v_fma_f32 v127, -v95, v126, v94
	v_fmac_f32_e32 v126, v127, v123
	v_fma_f32 v94, -v95, v126, v94
	v_div_scale_f32 v95, s[70:71], v90, v90, 1.0
	v_rcp_f32_e32 v127, v95
	v_div_fmas_f32 v94, v94, v123, v126
	v_div_fixup_f32 v91, v94, v91, 1.0
	v_mul_f32_e32 v77, 0xbfb8aa3b, v77
	v_fma_f32 v94, -v95, v127, 1.0
	v_fmac_f32_e32 v127, v94, v127
	v_div_scale_f32 v94, vcc, 1.0, v90, 1.0
	v_mul_f32_e32 v123, v94, v127
	v_fma_f32 v126, -v95, v123, v94
	v_fmac_f32_e32 v123, v126, v127
	v_fma_f32 v94, -v95, v123, v94
	v_div_fmas_f32 v94, v94, v127, v123
	v_div_fixup_f32 v90, v94, v90, 1.0
	v_pk_fma_f32 v[88:89], v[90:91], v[92:93], v[88:89]
	v_and_b32_sdwa v90, v87, v142 dst_sel:DWORD dst_unused:UNUSED_PAD src0_sel:WORD_1 src1_sel:DWORD
	v_and_b32_sdwa v91, v86, v142 dst_sel:DWORD dst_unused:UNUSED_PAD src0_sel:WORD_1 src1_sel:DWORD
	v_add3_u32 v86, v86, v91, s3
	v_add3_u32 v87, v87, v90, s3
	v_and_b32_sdwa v90, v89, v142 dst_sel:DWORD dst_unused:UNUSED_PAD src0_sel:WORD_1 src1_sel:DWORD
	v_and_b32_sdwa v91, v88, v142 dst_sel:DWORD dst_unused:UNUSED_PAD src0_sel:WORD_1 src1_sel:DWORD
	v_add3_u32 v89, v89, v90, s3
	v_add3_u32 v88, v88, v91, s3
	v_and_b32_e32 v89, 0xffff0000, v89
	v_and_b32_e32 v88, 0xffff0000, v88
	v_or_b32_sdwa v87, v89, v87 dst_sel:DWORD dst_unused:UNUSED_PAD src0_sel:DWORD src1_sel:WORD_1
	v_or_b32_sdwa v86, v88, v86 dst_sel:DWORD dst_unused:UNUSED_PAD src0_sel:DWORD src1_sel:WORD_1
	global_store_dwordx2 v[84:85], v[86:87], off offset:32
	global_load_dwordx4 v[86:89], v[98:99], off offset:384
	v_mfma_f32_16x16x32_bf16 v[72:75], v[8:11], v[72:75], v[80:83]
	global_load_dwordx4 v[90:93], v[98:99], off offset:1408
	v_add_f32_e32 v76, v76, v16
	v_mul_f32_e32 v76, 0xbfb8aa3b, v76
	v_exp_f32_e32 v80, v77
	v_add_f32_e32 v77, v78, v18
	v_mul_f32_e32 v77, 0xbfb8aa3b, v77
	v_exp_f32_e32 v76, v76
	v_exp_f32_e32 v77, v77
	v_add_f32_e32 v78, v79, v19
	v_mul_f32_e32 v78, 0xbfb8aa3b, v78
	v_exp_f32_e32 v81, v78
	v_pk_add_f32 v[76:77], v[76:77], 1.0 op_sel_hi:[1,0]
	v_add_f32_e32 v73, v73, v1
	v_div_scale_f32 v94, s[70:71], v77, v77, 1.0
	v_rcp_f32_e32 v95, v94
	v_pk_add_f32 v[80:81], v[80:81], 1.0 op_sel_hi:[1,0]
	v_mul_f32_e32 v73, 0xbfb8aa3b, v73
	v_add_f32_e32 v72, v72, v0
	v_fma_f32 v123, -v94, v95, 1.0
	v_fmac_f32_e32 v95, v123, v95
	v_div_scale_f32 v123, vcc, 1.0, v77, 1.0
	v_mul_f32_e32 v126, v123, v95
	v_fma_f32 v127, -v94, v126, v123
	v_fmac_f32_e32 v126, v127, v95
	v_fma_f32 v94, -v94, v126, v123
	v_div_scale_f32 v123, s[70:71], v76, v76, 1.0
	v_rcp_f32_e32 v127, v123
	v_div_fmas_f32 v94, v94, v95, v126
	v_div_fixup_f32 v77, v94, v77, 1.0
	v_mul_f32_e32 v72, 0xbfb8aa3b, v72
	v_fma_f32 v94, -v123, v127, 1.0
	v_fmac_f32_e32 v127, v94, v127
	v_div_scale_f32 v94, vcc, 1.0, v76, 1.0
	v_mul_f32_e32 v95, v94, v127
	v_fma_f32 v126, -v123, v95, v94
	v_fmac_f32_e32 v95, v126, v127
	v_fma_f32 v94, -v123, v95, v94
	v_div_fmas_f32 v94, v94, v127, v95
	v_div_fixup_f32 v76, v94, v76, 1.0
	v_exp_f32_e32 v72, v72
	v_mfma_f32_16x16x32_bf16 v[64:67], v[194:197], v[182:185], v[218:221]
	s_waitcnt vmcnt(1)
	v_lshlrev_b32_e32 v79, 16, v87
	v_lshlrev_b32_e32 v78, 16, v86
	s_waitcnt vmcnt(0)
	v_lshlrev_b32_e32 v83, 16, v91
	v_lshlrev_b32_e32 v82, 16, v90
	v_pk_fma_f32 v[76:77], v[76:77], v[82:83], v[78:79]
	v_and_b32_e32 v79, 0xffff0000, v87
	v_div_scale_f32 v87, s[70:71], v81, v81, 1.0
	v_rcp_f32_e32 v94, v87
	v_and_b32_e32 v78, 0xffff0000, v86
	v_and_b32_e32 v82, 0xffff0000, v90
	v_and_b32_e32 v83, 0xffff0000, v91
	v_fma_f32 v86, -v87, v94, 1.0
	v_fmac_f32_e32 v94, v86, v94
	v_div_scale_f32 v86, vcc, 1.0, v81, 1.0
	v_mul_f32_e32 v90, v86, v94
	v_fma_f32 v91, -v87, v90, v86
	v_fmac_f32_e32 v90, v91, v94
	v_fma_f32 v86, -v87, v90, v86
	v_div_scale_f32 v87, s[70:71], v80, v80, 1.0
	v_rcp_f32_e32 v91, v87
	v_div_fmas_f32 v86, v86, v94, v90
	v_div_fixup_f32 v81, v86, v81, 1.0
	v_mfma_f32_16x16x32_bf16 v[64:67], v[36:39], v[52:55], v[64:67]
	v_fma_f32 v86, -v87, v91, 1.0
	v_fmac_f32_e32 v91, v86, v91
	v_div_scale_f32 v86, vcc, 1.0, v80, 1.0
	v_mul_f32_e32 v90, v86, v91
	v_fma_f32 v94, -v87, v90, v86
	v_fmac_f32_e32 v90, v94, v91
	v_fma_f32 v86, -v87, v90, v86
	v_div_fmas_f32 v86, v86, v91, v90
	v_div_fixup_f32 v80, v86, v80, 1.0
	v_pk_fma_f32 v[78:79], v[80:81], v[82:83], v[78:79]
	v_and_b32_sdwa v81, v76, v142 dst_sel:DWORD dst_unused:UNUSED_PAD src0_sel:WORD_1 src1_sel:DWORD
	v_add3_u32 v76, v76, v81, s3
	v_and_b32_sdwa v81, v78, v142 dst_sel:DWORD dst_unused:UNUSED_PAD src0_sel:WORD_1 src1_sel:DWORD
	v_add3_u32 v78, v78, v81, s3
	v_and_b32_e32 v78, 0xffff0000, v78
	v_or_b32_sdwa v76, v78, v76 dst_sel:DWORD dst_unused:UNUSED_PAD src0_sel:DWORD src1_sel:WORD_1
	v_exp_f32_e32 v78, v73
	v_add_f32_e32 v73, v74, v2
	v_mul_f32_e32 v73, 0xbfb8aa3b, v73
	v_exp_f32_e32 v73, v73
	v_and_b32_sdwa v80, v77, v142 dst_sel:DWORD dst_unused:UNUSED_PAD src0_sel:WORD_1 src1_sel:DWORD
	v_add3_u32 v77, v77, v80, s3
	v_and_b32_sdwa v80, v79, v142 dst_sel:DWORD dst_unused:UNUSED_PAD src0_sel:WORD_1 src1_sel:DWORD
	v_pk_add_f32 v[72:73], v[72:73], 1.0 op_sel_hi:[1,0]
	v_add3_u32 v79, v79, v80, s3
	v_div_scale_f32 v80, s[70:71], v73, v73, 1.0
	v_rcp_f32_e32 v81, v80
	v_add_f32_e32 v74, v75, v3
	v_and_b32_e32 v79, 0xffff0000, v79
	v_mul_f32_e32 v74, 0xbfb8aa3b, v74
	v_fma_f32 v82, -v80, v81, 1.0
	v_fmac_f32_e32 v81, v82, v81
	v_div_scale_f32 v82, vcc, 1.0, v73, 1.0
	v_mul_f32_e32 v83, v82, v81
	v_fma_f32 v86, -v80, v83, v82
	v_fmac_f32_e32 v83, v86, v81
	v_fma_f32 v80, -v80, v83, v82
	v_div_scale_f32 v82, s[70:71], v72, v72, 1.0
	v_rcp_f32_e32 v86, v82
	v_div_fmas_f32 v80, v80, v81, v83
	v_div_fixup_f32 v73, v80, v73, 1.0
	v_or_b32_sdwa v77, v79, v77 dst_sel:DWORD dst_unused:UNUSED_PAD src0_sel:DWORD src1_sel:WORD_1
	v_fma_f32 v80, -v82, v86, 1.0
	v_fmac_f32_e32 v86, v80, v86
	v_div_scale_f32 v80, vcc, 1.0, v72, 1.0
	v_mul_f32_e32 v81, v80, v86
	v_fma_f32 v83, -v82, v81, v80
	v_exp_f32_e32 v79, v74
	v_fmac_f32_e32 v81, v83, v86
	v_fma_f32 v80, -v82, v81, v80
	v_div_fmas_f32 v80, v80, v86, v81
	global_store_dwordx2 v[84:85], v[76:77], off offset:64
	v_lshlrev_b32_e32 v75, 16, v89
	v_lshlrev_b32_e32 v74, 16, v88
	v_lshlrev_b32_e32 v77, 16, v93
	v_lshlrev_b32_e32 v76, 16, v92
	v_div_fixup_f32 v72, v80, v72, 1.0
	v_pk_fma_f32 v[72:73], v[72:73], v[76:77], v[74:75]
	v_pk_add_f32 v[76:77], v[78:79], 1.0 op_sel_hi:[1,0]
	v_and_b32_e32 v75, 0xffff0000, v89
	v_div_scale_f32 v80, s[70:71], v77, v77, 1.0
	v_rcp_f32_e32 v81, v80
	v_and_b32_e32 v74, 0xffff0000, v88
	v_and_b32_e32 v79, 0xffff0000, v93
	v_and_b32_e32 v78, 0xffff0000, v92
	v_fma_f32 v82, -v80, v81, 1.0
	v_fmac_f32_e32 v81, v82, v81
	v_div_scale_f32 v82, vcc, 1.0, v77, 1.0
	v_mul_f32_e32 v83, v82, v81
	v_fma_f32 v86, -v80, v83, v82
	v_fmac_f32_e32 v83, v86, v81
	v_fma_f32 v80, -v80, v83, v82
	v_div_scale_f32 v82, s[70:71], v76, v76, 1.0
	v_rcp_f32_e32 v86, v82
	v_div_fmas_f32 v80, v80, v81, v83
	v_div_fixup_f32 v77, v80, v77, 1.0
	v_add_f32_e32 v64, v64, v40
	v_fma_f32 v80, -v82, v86, 1.0
	v_fmac_f32_e32 v86, v80, v86
	v_div_scale_f32 v80, vcc, 1.0, v76, 1.0
	v_mul_f32_e32 v81, v80, v86
	v_fma_f32 v83, -v82, v81, v80
	v_fmac_f32_e32 v81, v83, v86
	v_fma_f32 v80, -v82, v81, v80
	v_div_fmas_f32 v80, v80, v86, v81
	v_div_fixup_f32 v76, v80, v76, 1.0
	v_pk_fma_f32 v[74:75], v[76:77], v[78:79], v[74:75]
	v_and_b32_sdwa v76, v73, v142 dst_sel:DWORD dst_unused:UNUSED_PAD src0_sel:WORD_1 src1_sel:DWORD
	v_and_b32_sdwa v77, v72, v142 dst_sel:DWORD dst_unused:UNUSED_PAD src0_sel:WORD_1 src1_sel:DWORD
	v_add3_u32 v72, v72, v77, s3
	v_add3_u32 v73, v73, v76, s3
	v_and_b32_sdwa v76, v75, v142 dst_sel:DWORD dst_unused:UNUSED_PAD src0_sel:WORD_1 src1_sel:DWORD
	v_and_b32_sdwa v77, v74, v142 dst_sel:DWORD dst_unused:UNUSED_PAD src0_sel:WORD_1 src1_sel:DWORD
	v_add3_u32 v75, v75, v76, s3
	v_add3_u32 v74, v74, v77, s3
	v_and_b32_e32 v75, 0xffff0000, v75
	v_and_b32_e32 v74, 0xffff0000, v74
	v_or_b32_sdwa v73, v75, v73 dst_sel:DWORD dst_unused:UNUSED_PAD src0_sel:DWORD src1_sel:WORD_1
	v_or_b32_sdwa v72, v74, v72 dst_sel:DWORD dst_unused:UNUSED_PAD src0_sel:DWORD src1_sel:WORD_1
	global_store_dwordx2 v[84:85], v[72:73], off offset:96
	global_load_dwordx4 v[72:75], v[98:99], off offset:512
	v_mul_f32_e32 v64, 0xbfb8aa3b, v64
	global_load_dwordx4 v[76:79], v[98:99], off offset:1536
	v_exp_f32_e32 v82, v64
	v_add_f32_e32 v64, v65, v41
	v_mul_f32_e32 v64, 0xbfb8aa3b, v64
	v_exp_f32_e32 v84, v64
	v_add_f32_e32 v64, v66, v42
	v_mul_f32_e32 v64, 0xbfb8aa3b, v64
	v_exp_f32_e32 v83, v64
	v_or_b32_e32 v80, 32, v122
	v_ashrrev_i32_e32 v81, 31, v80
	v_add_f32_e32 v64, v67, v43
	v_lshlrev_b64 v[80:81], 11, v[80:81]
	v_mul_f32_e32 v64, 0xbfb8aa3b, v64
	v_exp_f32_e32 v85, v64
	v_lshl_add_u64 v[64:65], s[16:17], 0, v[80:81]
	v_pk_add_f32 v[80:81], v[82:83], 1.0 op_sel_hi:[1,0]
	v_mfma_f32_16x16x32_bf16 v[68:71], v[32:35], v[52:55], v[68:71]
	v_div_scale_f32 v86, s[70:71], v81, v81, 1.0
	v_rcp_f32_e32 v87, v86
	v_lshl_add_u64 v[64:65], v[64:65], 0, v[124:125]
	v_mfma_f32_16x16x32_bf16 v[56:59], v[12:15], v[52:55], v[56:59]
	s_nop 3
	v_add_f32_e32 v69, v69, v29
	v_fma_f32 v88, -v86, v87, 1.0
	v_fmac_f32_e32 v87, v88, v87
	v_div_scale_f32 v88, vcc, 1.0, v81, 1.0
	v_mul_f32_e32 v89, v88, v87
	v_fma_f32 v90, -v86, v89, v88
	v_fmac_f32_e32 v89, v90, v87
	v_fma_f32 v86, -v86, v89, v88
	v_div_scale_f32 v88, s[70:71], v80, v80, 1.0
	v_rcp_f32_e32 v90, v88
	v_div_fmas_f32 v86, v86, v87, v89
	v_div_fixup_f32 v81, v86, v81, 1.0
	v_mul_f32_e32 v69, 0xbfb8aa3b, v69
	v_fma_f32 v86, -v88, v90, 1.0
	v_fmac_f32_e32 v90, v86, v90
	v_div_scale_f32 v86, vcc, 1.0, v80, 1.0
	v_mul_f32_e32 v87, v86, v90
	v_fma_f32 v89, -v88, v87, v86
	v_fmac_f32_e32 v87, v89, v90
	v_fma_f32 v86, -v88, v87, v86
	v_div_fmas_f32 v86, v86, v90, v87
	v_div_fixup_f32 v80, v86, v80, 1.0
	v_add_f32_e32 v68, v68, v28
	v_mul_f32_e32 v68, 0xbfb8aa3b, v68
	v_exp_f32_e32 v68, v68
	v_add_f32_e32 v57, v57, v17
	v_mul_f32_e32 v57, 0xbfb8aa3b, v57
	v_mfma_f32_16x16x32_bf16 v[52:55], v[8:11], v[52:55], v[60:63]
	v_add_f32_e32 v56, v56, v16
	v_mul_f32_e32 v56, 0xbfb8aa3b, v56
	v_exp_f32_e32 v56, v56
	v_exp_f32_e32 v60, v57
	v_add_f32_e32 v57, v58, v18
	v_mul_f32_e32 v57, 0xbfb8aa3b, v57
	v_exp_f32_e32 v57, v57
	v_add_f32_e32 v58, v59, v19
	v_mul_f32_e32 v58, 0xbfb8aa3b, v58
	v_exp_f32_e32 v61, v58
	v_pk_add_f32 v[56:57], v[56:57], 1.0 op_sel_hi:[1,0]
	v_add_f32_e32 v53, v53, v1
	v_mul_f32_e32 v53, 0xbfb8aa3b, v53
	v_pk_add_f32 v[60:61], v[60:61], 1.0 op_sel_hi:[1,0]
	v_add_f32_e32 v52, v52, v0
	v_mul_f32_e32 v52, 0xbfb8aa3b, v52
	v_exp_f32_e32 v52, v52
	v_mfma_f32_16x16x32_bf16 v[36:39], v[36:39], v[4:7], v[44:47]
	s_waitcnt vmcnt(1)
	v_lshlrev_b32_e32 v67, 16, v73
	v_lshlrev_b32_e32 v66, 16, v72
	s_waitcnt vmcnt(0)
	v_lshlrev_b32_e32 v83, 16, v77
	v_lshlrev_b32_e32 v82, 16, v76
	v_pk_fma_f32 v[66:67], v[80:81], v[82:83], v[66:67]
	v_pk_add_f32 v[80:81], v[84:85], 1.0 op_sel_hi:[1,0]
	v_and_b32_e32 v73, 0xffff0000, v73
	v_div_scale_f32 v82, s[70:71], v81, v81, 1.0
	v_rcp_f32_e32 v83, v82
	v_and_b32_e32 v72, 0xffff0000, v72
	v_and_b32_e32 v77, 0xffff0000, v77
	v_and_b32_e32 v76, 0xffff0000, v76
	v_fma_f32 v84, -v82, v83, 1.0
	v_fmac_f32_e32 v83, v84, v83
	v_div_scale_f32 v84, vcc, 1.0, v81, 1.0
	v_mul_f32_e32 v85, v84, v83
	v_fma_f32 v86, -v82, v85, v84
	v_fmac_f32_e32 v85, v86, v83
	v_fma_f32 v82, -v82, v85, v84
	v_div_scale_f32 v84, s[70:71], v80, v80, 1.0
	v_rcp_f32_e32 v86, v84
	v_div_fmas_f32 v82, v82, v83, v85
	v_div_fixup_f32 v81, v82, v81, 1.0
	v_mfma_f32_16x16x32_bf16 v[48:51], v[198:201], v[186:189], v[230:233]
	v_fma_f32 v82, -v84, v86, 1.0
	v_fmac_f32_e32 v86, v82, v86
	v_div_scale_f32 v82, vcc, 1.0, v80, 1.0
	v_mul_f32_e32 v83, v82, v86
	v_fma_f32 v85, -v84, v83, v82
	v_fmac_f32_e32 v83, v85, v86
	v_fma_f32 v82, -v84, v83, v82
	v_div_fmas_f32 v82, v82, v86, v83
	v_div_fixup_f32 v80, v82, v80, 1.0
	v_pk_fma_f32 v[72:73], v[80:81], v[76:77], v[72:73]
	v_and_b32_sdwa v77, v66, v142 dst_sel:DWORD dst_unused:UNUSED_PAD src0_sel:WORD_1 src1_sel:DWORD
	v_add3_u32 v66, v66, v77, s3
	v_and_b32_sdwa v77, v72, v142 dst_sel:DWORD dst_unused:UNUSED_PAD src0_sel:WORD_1 src1_sel:DWORD
	v_add3_u32 v72, v72, v77, s3
	v_and_b32_e32 v72, 0xffff0000, v72
	v_or_b32_sdwa v66, v72, v66 dst_sel:DWORD dst_unused:UNUSED_PAD src0_sel:DWORD src1_sel:WORD_1
	v_exp_f32_e32 v72, v69
	v_add_f32_e32 v69, v70, v30
	v_mul_f32_e32 v69, 0xbfb8aa3b, v69
	v_exp_f32_e32 v69, v69
	v_and_b32_sdwa v76, v67, v142 dst_sel:DWORD dst_unused:UNUSED_PAD src0_sel:WORD_1 src1_sel:DWORD
	v_add3_u32 v67, v67, v76, s3
	v_and_b32_sdwa v76, v73, v142 dst_sel:DWORD dst_unused:UNUSED_PAD src0_sel:WORD_1 src1_sel:DWORD
	v_pk_add_f32 v[68:69], v[68:69], 1.0 op_sel_hi:[1,0]
	v_add3_u32 v73, v73, v76, s3
	v_div_scale_f32 v76, s[70:71], v69, v69, 1.0
	v_rcp_f32_e32 v77, v76
	v_add_f32_e32 v70, v71, v31
	v_and_b32_e32 v73, 0xffff0000, v73
	v_mul_f32_e32 v70, 0xbfb8aa3b, v70
	v_fma_f32 v80, -v76, v77, 1.0
	v_fmac_f32_e32 v77, v80, v77
	v_div_scale_f32 v80, vcc, 1.0, v69, 1.0
	v_mul_f32_e32 v81, v80, v77
	v_fma_f32 v82, -v76, v81, v80
	v_fmac_f32_e32 v81, v82, v77
	v_fma_f32 v76, -v76, v81, v80
	v_div_scale_f32 v80, s[70:71], v68, v68, 1.0
	v_rcp_f32_e32 v82, v80
	v_div_fmas_f32 v76, v76, v77, v81
	v_div_fixup_f32 v69, v76, v69, 1.0
	v_or_b32_sdwa v67, v73, v67 dst_sel:DWORD dst_unused:UNUSED_PAD src0_sel:DWORD src1_sel:WORD_1
	v_fma_f32 v76, -v80, v82, 1.0
	v_fmac_f32_e32 v82, v76, v82
	v_div_scale_f32 v76, vcc, 1.0, v68, 1.0
	v_mul_f32_e32 v77, v76, v82
	v_fma_f32 v81, -v80, v77, v76
	v_exp_f32_e32 v73, v70
	v_fmac_f32_e32 v77, v81, v82
	v_fma_f32 v76, -v80, v77, v76
	v_div_fmas_f32 v76, v76, v82, v77
	global_store_dwordx2 v[64:65], v[66:67], off
	v_lshlrev_b32_e32 v67, 16, v75
	v_lshlrev_b32_e32 v66, 16, v74
	v_lshlrev_b32_e32 v71, 16, v79
	v_lshlrev_b32_e32 v70, 16, v78
	v_div_fixup_f32 v68, v76, v68, 1.0
	v_pk_fma_f32 v[66:67], v[68:69], v[70:71], v[66:67]
	v_pk_add_f32 v[70:71], v[72:73], 1.0 op_sel_hi:[1,0]
	v_and_b32_e32 v69, 0xffff0000, v75
	v_div_scale_f32 v75, s[70:71], v71, v71, 1.0
	v_rcp_f32_e32 v76, v75
	v_and_b32_e32 v68, 0xffff0000, v74
	v_and_b32_e32 v72, 0xffff0000, v78
	v_and_b32_e32 v73, 0xffff0000, v79
	v_fma_f32 v74, -v75, v76, 1.0
	v_fmac_f32_e32 v76, v74, v76
	v_div_scale_f32 v74, vcc, 1.0, v71, 1.0
	v_mul_f32_e32 v77, v74, v76
	v_fma_f32 v78, -v75, v77, v74
	v_fmac_f32_e32 v77, v78, v76
	v_fma_f32 v74, -v75, v77, v74
	v_div_scale_f32 v75, s[70:71], v70, v70, 1.0
	v_rcp_f32_e32 v78, v75
	v_div_fmas_f32 v74, v74, v76, v77
	v_div_fixup_f32 v71, v74, v71, 1.0
	v_mfma_f32_16x16x32_bf16 v[48:51], v[32:35], v[4:7], v[48:51]
	v_fma_f32 v74, -v75, v78, 1.0
	v_fmac_f32_e32 v78, v74, v78
	v_div_scale_f32 v74, vcc, 1.0, v70, 1.0
	v_mul_f32_e32 v76, v74, v78
	v_fma_f32 v77, -v75, v76, v74
	v_fmac_f32_e32 v76, v77, v78
	v_fma_f32 v74, -v75, v76, v74
	v_div_fmas_f32 v74, v74, v78, v76
	v_div_fixup_f32 v70, v74, v70, 1.0
	v_pk_fma_f32 v[68:69], v[70:71], v[72:73], v[68:69]
	v_and_b32_sdwa v70, v67, v142 dst_sel:DWORD dst_unused:UNUSED_PAD src0_sel:WORD_1 src1_sel:DWORD
	v_and_b32_sdwa v71, v66, v142 dst_sel:DWORD dst_unused:UNUSED_PAD src0_sel:WORD_1 src1_sel:DWORD
	v_add3_u32 v66, v66, v71, s3
	v_add3_u32 v67, v67, v70, s3
	v_and_b32_sdwa v70, v69, v142 dst_sel:DWORD dst_unused:UNUSED_PAD src0_sel:WORD_1 src1_sel:DWORD
	v_and_b32_sdwa v71, v68, v142 dst_sel:DWORD dst_unused:UNUSED_PAD src0_sel:WORD_1 src1_sel:DWORD
	v_add3_u32 v69, v69, v70, s3
	v_add3_u32 v68, v68, v71, s3
	v_and_b32_e32 v69, 0xffff0000, v69
	v_and_b32_e32 v68, 0xffff0000, v68
	v_or_b32_sdwa v67, v69, v67 dst_sel:DWORD dst_unused:UNUSED_PAD src0_sel:DWORD src1_sel:WORD_1
	v_or_b32_sdwa v66, v68, v66 dst_sel:DWORD dst_unused:UNUSED_PAD src0_sel:DWORD src1_sel:WORD_1
	global_store_dwordx2 v[64:65], v[66:67], off offset:32
	global_load_dwordx4 v[66:69], v[98:99], off offset:640
	v_div_scale_f32 v74, s[70:71], v57, v57, 1.0
	global_load_dwordx4 v[70:73], v[98:99], off offset:1664
	v_rcp_f32_e32 v75, v74
	v_add_f32_e32 v35, v37, v41
	v_mul_f32_e32 v35, 0xbfb8aa3b, v35
	v_add_f32_e32 v34, v36, v40
	v_fma_f32 v76, -v74, v75, 1.0
	v_fmac_f32_e32 v75, v76, v75
	v_div_scale_f32 v76, vcc, 1.0, v57, 1.0
	v_mul_f32_e32 v77, v76, v75
	v_fma_f32 v78, -v74, v77, v76
	v_fmac_f32_e32 v77, v78, v75
	v_fma_f32 v74, -v74, v77, v76
	v_div_scale_f32 v76, s[70:71], v56, v56, 1.0
	v_rcp_f32_e32 v78, v76
	v_div_fmas_f32 v74, v74, v75, v77
	v_div_fixup_f32 v57, v74, v57, 1.0
	v_exp_f32_e32 v36, v35
	v_fma_f32 v74, -v76, v78, 1.0
	v_fmac_f32_e32 v78, v74, v78
	v_div_scale_f32 v74, vcc, 1.0, v56, 1.0
	v_mul_f32_e32 v75, v74, v78
	v_fma_f32 v77, -v76, v75, v74
	v_fmac_f32_e32 v75, v77, v78
	v_fma_f32 v74, -v76, v75, v74
	v_div_fmas_f32 v74, v74, v78, v75
	v_div_fixup_f32 v56, v74, v56, 1.0
	v_add_f32_e32 v35, v38, v42
	v_mul_f32_e32 v34, 0xbfb8aa3b, v34
	v_mul_f32_e32 v35, 0xbfb8aa3b, v35
	v_exp_f32_e32 v34, v34
	v_exp_f32_e32 v35, v35
	v_add_f32_e32 v37, v39, v43
	v_mul_f32_e32 v37, 0xbfb8aa3b, v37
	v_exp_f32_e32 v37, v37
	v_pk_add_f32 v[34:35], v[34:35], 1.0 op_sel_hi:[1,0]
	v_add_f32_e32 v29, v49, v29
	v_div_scale_f32 v42, s[70:71], v35, v35, 1.0
	v_rcp_f32_e32 v43, v42
	v_pk_add_f32 v[36:37], v[36:37], 1.0 op_sel_hi:[1,0]
	v_mul_f32_e32 v29, 0xbfb8aa3b, v29
	v_add_f32_e32 v28, v48, v28
	v_mul_f32_e32 v28, 0xbfb8aa3b, v28
	v_exp_f32_e32 v28, v28
	v_or_b32_e32 v32, 48, v122
	v_ashrrev_i32_e32 v33, 31, v32
	v_lshlrev_b64 v[32:33], 11, v[32:33]
	v_lshl_add_u64 v[32:33], s[16:17], 0, v[32:33]
	v_lshl_add_u64 v[32:33], v[32:33], 0, v[124:125]
	v_mfma_f32_16x16x32_bf16 v[12:15], v[12:15], v[4:7], v[20:23]
	s_waitcnt vmcnt(1)
	v_lshlrev_b32_e32 v59, 16, v67
	v_lshlrev_b32_e32 v58, 16, v66
	v_mfma_f32_16x16x32_bf16 v[4:7], v[8:11], v[4:7], v[24:27]
	s_waitcnt vmcnt(0)
	v_lshlrev_b32_e32 v63, 16, v71
	v_lshlrev_b32_e32 v62, 16, v70
	v_pk_fma_f32 v[56:57], v[56:57], v[62:63], v[58:59]
	v_and_b32_e32 v59, 0xffff0000, v67
	v_div_scale_f32 v67, s[70:71], v61, v61, 1.0
	v_rcp_f32_e32 v74, v67
	v_and_b32_e32 v58, 0xffff0000, v66
	v_and_b32_e32 v62, 0xffff0000, v70
	v_and_b32_e32 v63, 0xffff0000, v71
	v_fma_f32 v66, -v67, v74, 1.0
	v_fmac_f32_e32 v74, v66, v74
	v_div_scale_f32 v66, vcc, 1.0, v61, 1.0
	v_mul_f32_e32 v70, v66, v74
	v_fma_f32 v71, -v67, v70, v66
	v_fmac_f32_e32 v70, v71, v74
	v_fma_f32 v66, -v67, v70, v66
	v_div_scale_f32 v67, s[70:71], v60, v60, 1.0
	v_rcp_f32_e32 v71, v67
	v_div_fmas_f32 v66, v66, v74, v70
	v_div_fixup_f32 v61, v66, v61, 1.0
	v_add_f32_e32 v9, v13, v17
	v_fma_f32 v66, -v67, v71, 1.0
	v_fmac_f32_e32 v71, v66, v71
	v_div_scale_f32 v66, vcc, 1.0, v60, 1.0
	v_mul_f32_e32 v70, v66, v71
	v_fma_f32 v74, -v67, v70, v66
	v_fmac_f32_e32 v70, v74, v71
	v_fma_f32 v66, -v67, v70, v66
	v_div_fmas_f32 v66, v66, v71, v70
	v_div_fixup_f32 v60, v66, v60, 1.0
	v_pk_fma_f32 v[58:59], v[60:61], v[62:63], v[58:59]
	v_and_b32_sdwa v61, v56, v142 dst_sel:DWORD dst_unused:UNUSED_PAD src0_sel:WORD_1 src1_sel:DWORD
	v_add3_u32 v56, v56, v61, s3
	v_and_b32_sdwa v61, v58, v142 dst_sel:DWORD dst_unused:UNUSED_PAD src0_sel:WORD_1 src1_sel:DWORD
	v_add3_u32 v58, v58, v61, s3
	v_and_b32_e32 v58, 0xffff0000, v58
	v_or_b32_sdwa v56, v58, v56 dst_sel:DWORD dst_unused:UNUSED_PAD src0_sel:DWORD src1_sel:WORD_1
	v_exp_f32_e32 v58, v53
	v_add_f32_e32 v53, v54, v2
	v_mul_f32_e32 v53, 0xbfb8aa3b, v53
	v_exp_f32_e32 v53, v53
	v_and_b32_sdwa v60, v57, v142 dst_sel:DWORD dst_unused:UNUSED_PAD src0_sel:WORD_1 src1_sel:DWORD
	v_add3_u32 v57, v57, v60, s3
	v_and_b32_sdwa v60, v59, v142 dst_sel:DWORD dst_unused:UNUSED_PAD src0_sel:WORD_1 src1_sel:DWORD
	v_pk_add_f32 v[52:53], v[52:53], 1.0 op_sel_hi:[1,0]
	v_add3_u32 v59, v59, v60, s3
	v_div_scale_f32 v60, s[70:71], v53, v53, 1.0
	v_rcp_f32_e32 v61, v60
	v_add_f32_e32 v54, v55, v3
	v_and_b32_e32 v59, 0xffff0000, v59
	v_mul_f32_e32 v54, 0xbfb8aa3b, v54
	v_fma_f32 v62, -v60, v61, 1.0
	v_fmac_f32_e32 v61, v62, v61
	v_div_scale_f32 v62, vcc, 1.0, v53, 1.0
	v_mul_f32_e32 v63, v62, v61
	v_fma_f32 v66, -v60, v63, v62
	v_fmac_f32_e32 v63, v66, v61
	v_fma_f32 v60, -v60, v63, v62
	v_div_scale_f32 v62, s[70:71], v52, v52, 1.0
	v_rcp_f32_e32 v66, v62
	v_div_fmas_f32 v60, v60, v61, v63
	v_div_fixup_f32 v53, v60, v53, 1.0
	v_or_b32_sdwa v57, v59, v57 dst_sel:DWORD dst_unused:UNUSED_PAD src0_sel:DWORD src1_sel:WORD_1
	v_fma_f32 v60, -v62, v66, 1.0
	v_fmac_f32_e32 v66, v60, v66
	v_div_scale_f32 v60, vcc, 1.0, v52, 1.0
	v_mul_f32_e32 v61, v60, v66
	v_fma_f32 v63, -v62, v61, v60
	v_exp_f32_e32 v59, v54
	v_fmac_f32_e32 v61, v63, v66
	v_fma_f32 v60, -v62, v61, v60
	v_div_fmas_f32 v60, v60, v66, v61
	global_store_dwordx2 v[64:65], v[56:57], off offset:64
	v_lshlrev_b32_e32 v55, 16, v69
	v_lshlrev_b32_e32 v54, 16, v68
	v_lshlrev_b32_e32 v57, 16, v73
	v_lshlrev_b32_e32 v56, 16, v72
	v_div_fixup_f32 v52, v60, v52, 1.0
	v_pk_fma_f32 v[52:53], v[52:53], v[56:57], v[54:55]
	v_pk_add_f32 v[56:57], v[58:59], 1.0 op_sel_hi:[1,0]
	v_and_b32_e32 v55, 0xffff0000, v69
	v_div_scale_f32 v60, s[70:71], v57, v57, 1.0
	v_rcp_f32_e32 v61, v60
	v_and_b32_e32 v54, 0xffff0000, v68
	v_and_b32_e32 v59, 0xffff0000, v73
	v_and_b32_e32 v58, 0xffff0000, v72
	v_fma_f32 v62, -v60, v61, 1.0
	v_fmac_f32_e32 v61, v62, v61
	v_div_scale_f32 v62, vcc, 1.0, v57, 1.0
	v_mul_f32_e32 v63, v62, v61
	v_fma_f32 v66, -v60, v63, v62
	v_fmac_f32_e32 v63, v66, v61
	v_fma_f32 v60, -v60, v63, v62
	v_div_scale_f32 v62, s[70:71], v56, v56, 1.0
	v_rcp_f32_e32 v66, v62
	v_div_fmas_f32 v60, v60, v61, v63
	v_div_fixup_f32 v57, v60, v57, 1.0
	v_mul_f32_e32 v9, 0xbfb8aa3b, v9
	v_fma_f32 v60, -v62, v66, 1.0
	v_fmac_f32_e32 v66, v60, v66
	v_div_scale_f32 v60, vcc, 1.0, v56, 1.0
	v_mul_f32_e32 v61, v60, v66
	v_fma_f32 v63, -v62, v61, v60
	v_fmac_f32_e32 v61, v63, v66
	v_fma_f32 v60, -v62, v61, v60
	v_div_fmas_f32 v60, v60, v66, v61
	v_div_fixup_f32 v56, v60, v56, 1.0
	v_pk_fma_f32 v[54:55], v[56:57], v[58:59], v[54:55]
	v_and_b32_sdwa v56, v53, v142 dst_sel:DWORD dst_unused:UNUSED_PAD src0_sel:WORD_1 src1_sel:DWORD
	v_and_b32_sdwa v57, v52, v142 dst_sel:DWORD dst_unused:UNUSED_PAD src0_sel:WORD_1 src1_sel:DWORD
	v_add3_u32 v52, v52, v57, s3
	v_add3_u32 v53, v53, v56, s3
	v_and_b32_sdwa v56, v55, v142 dst_sel:DWORD dst_unused:UNUSED_PAD src0_sel:WORD_1 src1_sel:DWORD
	v_and_b32_sdwa v57, v54, v142 dst_sel:DWORD dst_unused:UNUSED_PAD src0_sel:WORD_1 src1_sel:DWORD
	v_add3_u32 v55, v55, v56, s3
	v_add3_u32 v54, v54, v57, s3
	v_and_b32_e32 v55, 0xffff0000, v55
	v_and_b32_e32 v54, 0xffff0000, v54
	v_or_b32_sdwa v53, v55, v53 dst_sel:DWORD dst_unused:UNUSED_PAD src0_sel:DWORD src1_sel:WORD_1
	v_or_b32_sdwa v52, v54, v52 dst_sel:DWORD dst_unused:UNUSED_PAD src0_sel:DWORD src1_sel:WORD_1
	global_store_dwordx2 v[64:65], v[52:53], off offset:96
	global_load_dwordx4 v[52:55], v[98:99], off offset:768
	v_fma_f32 v56, -v42, v43, 1.0
	global_load_dwordx4 v[44:47], v[98:99], off offset:1792
	v_fmac_f32_e32 v43, v56, v43
	v_div_scale_f32 v56, vcc, 1.0, v35, 1.0
	v_mul_f32_e32 v57, v56, v43
	v_fma_f32 v58, -v42, v57, v56
	v_fmac_f32_e32 v57, v58, v43
	v_fma_f32 v42, -v42, v57, v56
	v_div_scale_f32 v56, s[70:71], v34, v34, 1.0
	v_rcp_f32_e32 v58, v56
	v_div_fmas_f32 v42, v42, v43, v57
	v_div_fixup_f32 v35, v42, v35, 1.0
	v_add_f32_e32 v8, v12, v16
	v_fma_f32 v42, -v56, v58, 1.0
	v_fmac_f32_e32 v58, v42, v58
	v_div_scale_f32 v42, vcc, 1.0, v34, 1.0
	v_mul_f32_e32 v43, v42, v58
	v_fma_f32 v57, -v56, v43, v42
	v_fmac_f32_e32 v43, v57, v58
	v_fma_f32 v42, -v56, v43, v42
	v_div_fmas_f32 v42, v42, v58, v43
	v_div_fixup_f32 v34, v42, v34, 1.0
	v_div_scale_f32 v42, s[70:71], v37, v37, 1.0
	v_rcp_f32_e32 v43, v42
	v_exp_f32_e32 v10, v9
	v_add_f32_e32 v9, v14, v18
	v_mul_f32_e32 v8, 0xbfb8aa3b, v8
	v_mul_f32_e32 v9, 0xbfb8aa3b, v9
	v_exp_f32_e32 v8, v8
	v_exp_f32_e32 v9, v9
	v_add_f32_e32 v11, v15, v19
	v_mul_f32_e32 v11, 0xbfb8aa3b, v11
	v_exp_f32_e32 v11, v11
	v_pk_add_f32 v[8:9], v[8:9], 1.0 op_sel_hi:[1,0]
	v_add_f32_e32 v1, v5, v1
	v_div_scale_f32 v16, s[70:71], v9, v9, 1.0
	v_rcp_f32_e32 v17, v16
	v_pk_add_f32 v[10:11], v[10:11], 1.0 op_sel_hi:[1,0]
	v_mul_f32_e32 v1, 0xbfb8aa3b, v1
	v_add_f32_e32 v0, v4, v0
	v_fma_f32 v18, -v16, v17, 1.0
	v_fmac_f32_e32 v17, v18, v17
	v_exp_f32_e32 v4, v1
	v_add_f32_e32 v1, v6, v2
	v_mul_f32_e32 v0, 0xbfb8aa3b, v0
	v_mul_f32_e32 v1, 0xbfb8aa3b, v1
	v_exp_f32_e32 v0, v0
	v_exp_f32_e32 v1, v1
	v_add_f32_e32 v2, v7, v3
	v_mul_f32_e32 v2, 0xbfb8aa3b, v2
	v_exp_f32_e32 v5, v2
	v_pk_add_f32 v[0:1], v[0:1], 1.0 op_sel_hi:[1,0]
	v_pk_add_f32 v[4:5], v[4:5], 1.0 op_sel_hi:[1,0]
	s_waitcnt vmcnt(1)
	v_lshlrev_b32_e32 v39, 16, v53
	v_lshlrev_b32_e32 v38, 16, v52
	s_waitcnt vmcnt(0)
	v_lshlrev_b32_e32 v41, 16, v45
	v_lshlrev_b32_e32 v40, 16, v44
	v_pk_fma_f32 v[34:35], v[34:35], v[40:41], v[38:39]
	v_and_b32_e32 v40, 0xffff0000, v44
	v_fma_f32 v44, -v42, v43, 1.0
	v_fmac_f32_e32 v43, v44, v43
	v_div_scale_f32 v44, vcc, 1.0, v37, 1.0
	v_and_b32_e32 v41, 0xffff0000, v45
	v_mul_f32_e32 v45, v44, v43
	v_and_b32_e32 v38, 0xffff0000, v52
	v_fma_f32 v52, -v42, v45, v44
	v_fmac_f32_e32 v45, v52, v43
	v_fma_f32 v42, -v42, v45, v44
	v_div_scale_f32 v44, s[70:71], v36, v36, 1.0
	v_rcp_f32_e32 v52, v44
	v_div_fmas_f32 v42, v42, v43, v45
	v_div_fixup_f32 v37, v42, v37, 1.0
	v_and_b32_e32 v39, 0xffff0000, v53
	v_fma_f32 v42, -v44, v52, 1.0
	v_fmac_f32_e32 v52, v42, v52
	v_div_scale_f32 v42, vcc, 1.0, v36, 1.0
	v_mul_f32_e32 v43, v42, v52
	v_fma_f32 v45, -v44, v43, v42
	v_fmac_f32_e32 v43, v45, v52
	v_fma_f32 v42, -v44, v43, v42
	v_div_fmas_f32 v42, v42, v52, v43
	v_div_fixup_f32 v36, v42, v36, 1.0
	v_pk_fma_f32 v[36:37], v[36:37], v[40:41], v[38:39]
	v_and_b32_sdwa v39, v34, v142 dst_sel:DWORD dst_unused:UNUSED_PAD src0_sel:WORD_1 src1_sel:DWORD
	v_add3_u32 v34, v34, v39, s3
	v_and_b32_sdwa v39, v36, v142 dst_sel:DWORD dst_unused:UNUSED_PAD src0_sel:WORD_1 src1_sel:DWORD
	v_add3_u32 v36, v36, v39, s3
	v_and_b32_e32 v36, 0xffff0000, v36
	v_or_b32_sdwa v34, v36, v34 dst_sel:DWORD dst_unused:UNUSED_PAD src0_sel:DWORD src1_sel:WORD_1
	v_exp_f32_e32 v36, v29
	v_add_f32_e32 v29, v50, v30
	v_mul_f32_e32 v29, 0xbfb8aa3b, v29
	v_exp_f32_e32 v29, v29
	v_and_b32_sdwa v38, v35, v142 dst_sel:DWORD dst_unused:UNUSED_PAD src0_sel:WORD_1 src1_sel:DWORD
	v_add3_u32 v35, v35, v38, s3
	v_and_b32_sdwa v38, v37, v142 dst_sel:DWORD dst_unused:UNUSED_PAD src0_sel:WORD_1 src1_sel:DWORD
	v_pk_add_f32 v[28:29], v[28:29], 1.0 op_sel_hi:[1,0]
	v_add3_u32 v37, v37, v38, s3
	v_div_scale_f32 v38, s[70:71], v29, v29, 1.0
	v_rcp_f32_e32 v39, v38
	v_add_f32_e32 v30, v51, v31
	v_and_b32_e32 v37, 0xffff0000, v37
	v_mul_f32_e32 v30, 0xbfb8aa3b, v30
	v_fma_f32 v40, -v38, v39, 1.0
	v_fmac_f32_e32 v39, v40, v39
	v_div_scale_f32 v40, vcc, 1.0, v29, 1.0
	v_mul_f32_e32 v41, v40, v39
	v_fma_f32 v42, -v38, v41, v40
	v_fmac_f32_e32 v41, v42, v39
	v_fma_f32 v38, -v38, v41, v40
	v_div_scale_f32 v40, s[70:71], v28, v28, 1.0
	v_rcp_f32_e32 v42, v40
	v_div_fmas_f32 v38, v38, v39, v41
	v_div_fixup_f32 v29, v38, v29, 1.0
	v_or_b32_sdwa v35, v37, v35 dst_sel:DWORD dst_unused:UNUSED_PAD src0_sel:DWORD src1_sel:WORD_1
	v_fma_f32 v38, -v40, v42, 1.0
	v_fmac_f32_e32 v42, v38, v42
	v_div_scale_f32 v38, vcc, 1.0, v28, 1.0
	v_mul_f32_e32 v39, v38, v42
	v_fma_f32 v41, -v40, v39, v38
	v_exp_f32_e32 v37, v30
	v_fmac_f32_e32 v39, v41, v42
	v_fma_f32 v38, -v40, v39, v38
	v_div_fmas_f32 v38, v38, v42, v39
	global_store_dwordx2 v[32:33], v[34:35], off
	v_lshlrev_b32_e32 v31, 16, v55
	v_lshlrev_b32_e32 v30, 16, v54
	v_lshlrev_b32_e32 v35, 16, v47
	v_lshlrev_b32_e32 v34, 16, v46
	v_div_fixup_f32 v28, v38, v28, 1.0
	v_pk_fma_f32 v[28:29], v[28:29], v[34:35], v[30:31]
	v_pk_add_f32 v[34:35], v[36:37], 1.0 op_sel_hi:[1,0]
	v_and_b32_e32 v31, 0xffff0000, v55
	v_div_scale_f32 v38, s[70:71], v35, v35, 1.0
	v_rcp_f32_e32 v39, v38
	v_and_b32_e32 v30, 0xffff0000, v54
	v_and_b32_e32 v37, 0xffff0000, v47
	v_and_b32_e32 v36, 0xffff0000, v46
	v_fma_f32 v40, -v38, v39, 1.0
	v_fmac_f32_e32 v39, v40, v39
	v_div_scale_f32 v40, vcc, 1.0, v35, 1.0
	v_mul_f32_e32 v41, v40, v39
	v_fma_f32 v42, -v38, v41, v40
	v_fmac_f32_e32 v41, v42, v39
	v_fma_f32 v38, -v38, v41, v40
	v_div_scale_f32 v40, s[70:71], v34, v34, 1.0
	v_rcp_f32_e32 v42, v40
	v_div_fmas_f32 v38, v38, v39, v41
	v_div_fixup_f32 v35, v38, v35, 1.0
	v_fma_f32 v38, -v40, v42, 1.0
	v_fmac_f32_e32 v42, v38, v42
	v_div_scale_f32 v38, vcc, 1.0, v34, 1.0
	v_mul_f32_e32 v39, v38, v42
	v_fma_f32 v41, -v40, v39, v38
	v_fmac_f32_e32 v39, v41, v42
	v_fma_f32 v38, -v40, v39, v38
	v_div_fmas_f32 v38, v38, v42, v39
	v_div_fixup_f32 v34, v38, v34, 1.0
	v_pk_fma_f32 v[30:31], v[34:35], v[36:37], v[30:31]
	v_and_b32_sdwa v34, v29, v142 dst_sel:DWORD dst_unused:UNUSED_PAD src0_sel:WORD_1 src1_sel:DWORD
	v_and_b32_sdwa v35, v28, v142 dst_sel:DWORD dst_unused:UNUSED_PAD src0_sel:WORD_1 src1_sel:DWORD
	v_add3_u32 v28, v28, v35, s3
	v_add3_u32 v29, v29, v34, s3
	v_and_b32_sdwa v34, v31, v142 dst_sel:DWORD dst_unused:UNUSED_PAD src0_sel:WORD_1 src1_sel:DWORD
	v_and_b32_sdwa v35, v30, v142 dst_sel:DWORD dst_unused:UNUSED_PAD src0_sel:WORD_1 src1_sel:DWORD
	v_add3_u32 v31, v31, v34, s3
	v_add3_u32 v30, v30, v35, s3
	v_and_b32_e32 v31, 0xffff0000, v31
	v_and_b32_e32 v30, 0xffff0000, v30
	v_or_b32_sdwa v29, v31, v29 dst_sel:DWORD dst_unused:UNUSED_PAD src0_sel:DWORD src1_sel:WORD_1
	v_or_b32_sdwa v28, v30, v28 dst_sel:DWORD dst_unused:UNUSED_PAD src0_sel:DWORD src1_sel:WORD_1
	global_store_dwordx2 v[32:33], v[28:29], off offset:32
	global_load_dwordx4 v[28:31], v[98:99], off offset:896
	v_div_scale_f32 v18, vcc, 1.0, v9, 1.0
	global_load_dwordx4 v[20:23], v[98:99], off offset:1920
	v_mul_f32_e32 v19, v18, v17
	v_fma_f32 v24, -v16, v19, v18
	v_fmac_f32_e32 v19, v24, v17
	v_fma_f32 v16, -v16, v19, v18
	v_div_scale_f32 v18, s[70:71], v8, v8, 1.0
	v_rcp_f32_e32 v24, v18
	v_div_fmas_f32 v16, v16, v17, v19
	v_div_fixup_f32 v9, v16, v9, 1.0
	v_fma_f32 v16, -v18, v24, 1.0
	v_fmac_f32_e32 v24, v16, v24
	v_div_scale_f32 v16, vcc, 1.0, v8, 1.0
	v_mul_f32_e32 v17, v16, v24
	v_fma_f32 v19, -v18, v17, v16
	v_fmac_f32_e32 v17, v19, v24
	v_fma_f32 v16, -v18, v17, v16
	v_div_fmas_f32 v16, v16, v24, v17
	v_div_fixup_f32 v8, v16, v8, 1.0
	v_div_scale_f32 v16, s[70:71], v11, v11, 1.0
	v_rcp_f32_e32 v17, v16
	s_waitcnt vmcnt(1)
	v_lshlrev_b32_e32 v13, 16, v29
	v_fma_f32 v18, -v16, v17, 1.0
	v_fmac_f32_e32 v17, v18, v17
	v_div_scale_f32 v18, vcc, 1.0, v11, 1.0
	v_lshlrev_b32_e32 v12, 16, v28
	s_waitcnt vmcnt(0)
	v_lshlrev_b32_e32 v15, 16, v21
	v_lshlrev_b32_e32 v14, 16, v20
	v_mul_f32_e32 v19, v18, v17
	v_pk_fma_f32 v[8:9], v[8:9], v[14:15], v[12:13]
	v_and_b32_e32 v14, 0xffff0000, v20
	v_fma_f32 v20, -v16, v19, v18
	v_fmac_f32_e32 v19, v20, v17
	v_fma_f32 v16, -v16, v19, v18
	v_div_scale_f32 v18, s[70:71], v10, v10, 1.0
	v_rcp_f32_e32 v20, v18
	v_div_fmas_f32 v16, v16, v17, v19
	v_div_fixup_f32 v11, v16, v11, 1.0
	v_and_b32_e32 v13, 0xffff0000, v29
	v_fma_f32 v16, -v18, v20, 1.0
	v_fmac_f32_e32 v20, v16, v20
	v_div_scale_f32 v16, vcc, 1.0, v10, 1.0
	v_mul_f32_e32 v17, v16, v20
	v_fma_f32 v19, -v18, v17, v16
	v_fmac_f32_e32 v17, v19, v20
	v_fma_f32 v16, -v18, v17, v16
	v_div_fmas_f32 v16, v16, v20, v17
	v_and_b32_e32 v12, 0xffff0000, v28
	v_and_b32_e32 v15, 0xffff0000, v21
	v_div_fixup_f32 v10, v16, v10, 1.0
	v_pk_fma_f32 v[10:11], v[10:11], v[14:15], v[12:13]
	v_and_b32_sdwa v12, v9, v142 dst_sel:DWORD dst_unused:UNUSED_PAD src0_sel:WORD_1 src1_sel:DWORD
	v_and_b32_sdwa v13, v8, v142 dst_sel:DWORD dst_unused:UNUSED_PAD src0_sel:WORD_1 src1_sel:DWORD
	v_add3_u32 v8, v8, v13, s3
	v_add3_u32 v9, v9, v12, s3
	v_and_b32_sdwa v12, v11, v142 dst_sel:DWORD dst_unused:UNUSED_PAD src0_sel:WORD_1 src1_sel:DWORD
	v_and_b32_sdwa v13, v10, v142 dst_sel:DWORD dst_unused:UNUSED_PAD src0_sel:WORD_1 src1_sel:DWORD
	v_add3_u32 v11, v11, v12, s3
	v_add3_u32 v10, v10, v13, s3
	v_and_b32_e32 v11, 0xffff0000, v11
	v_and_b32_e32 v10, 0xffff0000, v10
	v_or_b32_sdwa v9, v11, v9 dst_sel:DWORD dst_unused:UNUSED_PAD src0_sel:DWORD src1_sel:WORD_1
	v_or_b32_sdwa v8, v10, v8 dst_sel:DWORD dst_unused:UNUSED_PAD src0_sel:DWORD src1_sel:WORD_1
	global_store_dwordx2 v[32:33], v[8:9], off offset:64
	v_div_scale_f32 v8, s[70:71], v1, v1, 1.0
	v_rcp_f32_e32 v9, v8
	v_lshlrev_b32_e32 v3, 16, v31
	v_lshlrev_b32_e32 v2, 16, v30
	v_lshlrev_b32_e32 v7, 16, v23
	v_fma_f32 v10, -v8, v9, 1.0
	v_fmac_f32_e32 v9, v10, v9
	v_div_scale_f32 v10, vcc, 1.0, v1, 1.0
	v_mul_f32_e32 v11, v10, v9
	v_fma_f32 v12, -v8, v11, v10
	v_fmac_f32_e32 v11, v12, v9
	v_fma_f32 v8, -v8, v11, v10
	v_div_scale_f32 v10, s[70:71], v0, v0, 1.0
	v_rcp_f32_e32 v12, v10
	v_div_fmas_f32 v8, v8, v9, v11
	v_div_fixup_f32 v1, v8, v1, 1.0
	v_lshlrev_b32_e32 v6, 16, v22
	v_fma_f32 v8, -v10, v12, 1.0
	v_fmac_f32_e32 v12, v8, v12
	v_div_scale_f32 v8, vcc, 1.0, v0, 1.0
	v_mul_f32_e32 v9, v8, v12
	v_fma_f32 v11, -v10, v9, v8
	v_fmac_f32_e32 v9, v11, v12
	v_fma_f32 v8, -v10, v9, v8
	v_div_fmas_f32 v8, v8, v12, v9
	v_div_fixup_f32 v0, v8, v0, 1.0
	v_div_scale_f32 v8, s[70:71], v5, v5, 1.0
	v_rcp_f32_e32 v9, v8
	v_pk_fma_f32 v[0:1], v[0:1], v[6:7], v[2:3]
	v_and_b32_e32 v3, 0xffff0000, v31
	v_and_b32_e32 v2, 0xffff0000, v30
	v_fma_f32 v10, -v8, v9, 1.0
	v_fmac_f32_e32 v9, v10, v9
	v_div_scale_f32 v10, vcc, 1.0, v5, 1.0
	v_mul_f32_e32 v11, v10, v9
	v_fma_f32 v12, -v8, v11, v10
	v_fmac_f32_e32 v11, v12, v9
	v_fma_f32 v8, -v8, v11, v10
	v_div_scale_f32 v10, s[70:71], v4, v4, 1.0
	v_rcp_f32_e32 v12, v10
	v_div_fmas_f32 v8, v8, v9, v11
	v_div_fixup_f32 v5, v8, v5, 1.0
	v_and_b32_e32 v7, 0xffff0000, v23
	v_fma_f32 v8, -v10, v12, 1.0
	v_fmac_f32_e32 v12, v8, v12
	v_div_scale_f32 v8, vcc, 1.0, v4, 1.0
	v_mul_f32_e32 v9, v8, v12
	v_fma_f32 v11, -v10, v9, v8
	v_fmac_f32_e32 v9, v11, v12
	v_fma_f32 v8, -v10, v9, v8
	v_div_fmas_f32 v8, v8, v12, v9
	v_and_b32_e32 v6, 0xffff0000, v22
	v_div_fixup_f32 v4, v8, v4, 1.0
	v_pk_fma_f32 v[2:3], v[4:5], v[6:7], v[2:3]
	v_and_b32_sdwa v4, v1, v142 dst_sel:DWORD dst_unused:UNUSED_PAD src0_sel:WORD_1 src1_sel:DWORD
	v_and_b32_sdwa v5, v0, v142 dst_sel:DWORD dst_unused:UNUSED_PAD src0_sel:WORD_1 src1_sel:DWORD
	v_add3_u32 v0, v0, v5, s3
	v_add3_u32 v1, v1, v4, s3
	v_and_b32_sdwa v4, v3, v142 dst_sel:DWORD dst_unused:UNUSED_PAD src0_sel:WORD_1 src1_sel:DWORD
	v_and_b32_sdwa v5, v2, v142 dst_sel:DWORD dst_unused:UNUSED_PAD src0_sel:WORD_1 src1_sel:DWORD
	v_add3_u32 v3, v3, v4, s3
	v_add3_u32 v2, v2, v5, s3
	v_and_b32_e32 v3, 0xffff0000, v3
	v_and_b32_e32 v2, 0xffff0000, v2
	v_or_b32_sdwa v1, v3, v1 dst_sel:DWORD dst_unused:UNUSED_PAD src0_sel:DWORD src1_sel:WORD_1
	v_or_b32_sdwa v0, v2, v0 dst_sel:DWORD dst_unused:UNUSED_PAD src0_sel:DWORD src1_sel:WORD_1
	global_store_dwordx2 v[32:33], v[0:1], off offset:96
	s_cbranch_scc0 .LBB0_454
